# tail round of the four residual GEMM phases split into quarter units over 16 workgroups (conditional MFMA blocks + quarter epilogue)
# speedup vs baseline: 1.0131x; 1.0131x over previous
.LBB0_1423:
	s_and_b64 vcc, exec, s[4:5]
	s_cbranch_vccnz .LBB0_1459
	v_ashrrev_i32_e32 v1, 31, v8
	v_lshrrev_b32_e32 v1, 26, v1
	v_add_u32_e32 v1, v8, v1
	v_ashrrev_i32_e32 v9, 6, v1
	v_bfe_i32 v1, v8, 27, 1
	v_lshlrev_b32_e32 v0, 4, v8
	v_lshrrev_b32_e32 v1, 22, v1
	v_add_u32_e32 v1, v0, v1
	v_and_b32_e32 v1, 0xfffffc00, v1
	v_sub_u32_e32 v1, v0, v1
	v_lshrrev_b32_e32 v2, 4, v1
	v_bitop3_b32 v2, v2, v1, 32 bitop3:0x6c
	v_ashrrev_i32_e32 v1, 31, v1
	v_lshrrev_b32_e32 v1, 26, v1
	v_add_u32_e32 v1, v2, v1
	v_ashrrev_i32_e32 v10, 6, v1
	v_mul_i32_i24_e32 v4, 64, v10
	v_sub_u32_e32 v2, v2, v4
	v_mov_b32_e32 v4, 1
	v_lshlrev_b32_e32 v3, 3, v9
	v_lshlrev_b32_e32 v1, 5, v9
	v_ashrrev_i16_sdwa v2, v4, sext(v2) dst_sel:DWORD dst_unused:UNUSED_PAD src0_sel:DWORD src1_sel:BYTE_0
	v_and_b32_e32 v3, 0x1ffff0, v3
	v_and_b32_e32 v1, 32, v1
	v_bfe_i32 v11, v2, 0, 16
	v_add_u32_e32 v1, v1, v11
	v_add_lshl_u32 v2, v10, v3, 11
	v_add_u32_e32 v0, 0x2000, v0
	s_waitcnt vmcnt(0)
	v_lshl_add_u32 v144, v1, 1, v2
	v_ashrrev_i32_e32 v1, 31, v0
	v_lshrrev_b32_e32 v1, 22, v1
	v_add_u32_e32 v1, v0, v1
	s_load_dwordx2 s[6:7], s[10:11], 0x120
	s_load_dwordx4 s[12:15], s[10:11], 0x0
	v_ashrrev_i32_e32 v12, 10, v1
	v_mul_i32_i24_e32 v1, 0x400, v12
	v_sub_u32_e32 v0, v0, v1
	v_lshrrev_b32_e32 v1, 4, v0
	s_waitcnt lgkmcnt(0)
	s_add_u32 s42, s6, 0x3b0b200
	v_bitop3_b32 v0, v1, v0, 32 bitop3:0x6c
	s_addc_u32 s43, s7, 0
	v_ashrrev_i32_e32 v2, 31, v0
	s_add_u32 s44, s6, 0x600000
	v_lshrrev_b32_e32 v2, 26, v2
	s_addc_u32 s45, s7, 0
	v_add_u32_e32 v2, v0, v2
	s_ashr_i32 s21, s22, 6
	s_ashr_i32 s35, s34, 31
	s_ashr_i32 s9, s8, 31
	s_ashr_i32 s20, s22, 8
	v_ashrrev_i32_e32 v13, 6, v2
	v_and_b32_e32 v2, 0xc0, v2
	s_lshl_b32 s48, s21, 10
	s_lshl_b64 s[10:11], s[34:35], 19
	s_lshl_b64 s[16:17], s[8:9], 19
	v_sub_u32_e32 v0, v0, v2
	s_add_u32 s38, s44, s16
	v_lshlrev_b32_e32 v1, 3, v12
	v_lshlrev_b32_e32 v3, 5, v12
	v_ashrrev_i16_sdwa v0, v4, sext(v0) dst_sel:DWORD dst_unused:UNUSED_PAD src0_sel:DWORD src1_sel:BYTE_0
	s_addc_u32 s39, s45, s17
	s_add_i32 s35, s48, 0
	v_and_b32_e32 v1, 0x1ffff0, v1
	v_and_b32_e32 v3, 32, v3
	v_bfe_i32 v14, v0, 0, 16
	s_add_i32 m0, s35, 0x10000
	v_add_u32_e32 v0, v3, v14
	v_add_lshl_u32 v1, v13, v1, 11
	global_load_lds_dwordx4 v144, s[38:39]
	s_add_i32 m0, s35, 0x12000
	v_lshl_add_u32 v146, v0, 1, v1
	s_add_u32 s16, s38, 0x40000
	global_load_lds_dwordx4 v146, s[38:39]
	s_addc_u32 s17, s39, 0
	s_add_i32 m0, s35, 0x14000
	v_mov_b32_e32 v145, 0
	global_load_lds_dwordx4 v144, s[16:17]
	s_add_i32 m0, s35, 0x16000
	s_add_u32 s36, s42, s10
	s_addc_u32 s37, s43, s11
	s_add_i32 s49, s35, 0x2000
	global_load_lds_dwordx4 v146, s[16:17]
	s_mov_b32 m0, s35
	s_add_u32 s10, s36, 0x40000
	global_load_lds_dwordx4 v144, s[36:37]
	s_mov_b32 m0, s49
	s_addc_u32 s11, s37, 0
	s_add_i32 s50, s35, 0x4000
	global_load_lds_dwordx4 v146, s[36:37]
	s_mov_b32 m0, s50
	s_add_i32 s51, s35, 0x6000
	global_load_lds_dwordx4 v144, s[10:11]
	s_mov_b32 m0, s51
	v_mov_b32_e32 v147, v145
	global_load_lds_dwordx4 v146, s[10:11]
	s_cmp_eq_u32 s20, 1
	s_mov_b32 s52, 0
	s_mov_b32 s101, 0xf
	s_mov_b32 s100, 0xf
	s_mov_b32 s53, 0x10000
	v_lshl_add_u64 v[6:7], s[38:39], 0, v[144:145]
	v_lshl_add_u64 v[4:5], s[38:39], 0, v[146:147]
	v_lshl_add_u64 v[0:1], s[36:37], 0, v[144:145]
	s_cselect_b64 s[10:11], -1, 0
	s_cmp_lg_u32 s20, 1
	v_lshl_add_u64 v[2:3], s[36:37], 0, v[146:147]
	s_cbranch_scc1 .LBB0_1426
	s_barrier

.LBB0_1428:
	s_mov_b32 s101, s100
	s_andn2_b64 vcc, exec, s[6:7]
	s_mov_b32 s8, s24
	s_mov_b32 s34, s26
	s_mov_b64 s[38:39], s[30:31]
	s_mov_b64 s[36:37], s[28:29]
	s_cbranch_vccz .LBB0_1458
.LBB0_1429:
	s_add_i32 s52, s52, 1
	s_mul_i32 s6, s52, s47
	s_mul_hi_u32 s7, s52, s46
	s_add_i32 s7, s7, s6
	s_mul_i32 s6, s52, s46
	s_add_u32 s28, s6, s94
	s_addc_u32 s29, s7, s95
	s_mov_b32 s100, 0xf
	s_cmp_eq_u32 s46, 0x100
	s_cbranch_scc0 .Lqs_done_6
	s_cmp_eq_u32 s52, 4
	s_cbranch_scc0 .Lqs_done_6
	s_mov_b32 s29, 0
	s_mov_b32 s28, 0x7fffffff
	s_cmp_lt_u32 s94, 16
	s_cbranch_scc0 .Lqs_done_6
	s_lshr_b32 s28, s94, 2
	s_add_i32 s28, s28, 0x400
	s_and_b32 s98, s94, 3
	s_lshl_b32 s100, 1, s98
	s_lshl_b32 s98, s98, 4
	s_or_b32 s100, s100, s98
	s_or_b32 s100, s100, 0x40
.Lqs_done_6:
	v_cmp_gt_i64_e32 vcc, s[28:29], v[154:155]
	v_cmp_lt_i64_e64 s[6:7], s[28:29], v[152:153]
	s_cbranch_vccnz .LBB0_1435
	s_ashr_i32 s9, s28, 31
	s_lshr_b32 s9, s9, 29
	s_add_i32 s9, s28, s9
	s_and_b32 s24, s9, -8
	s_sub_i32 s26, s28, s24
	s_cmp_gt_i32 s26, 3
	s_mov_b64 s[24:25], -1
	s_cbranch_scc0 .LBB0_1432
	s_lshl_b32 s24, s26, 7
	s_or_b32 s27, s24, 4
	s_mov_b64 s[24:25], 0

.LBB0_1436:
	ds_read_b128 v[128:131], v165
	ds_read_b128 v[132:135], v165 offset:1024
	ds_read_b128 v[136:139], v165 offset:2048
	ds_read_b128 v[140:143], v165 offset:3072
	ds_read_b128 v[156:159], v166
	ds_read_b128 v[160:163], v166 offset:1024
	ds_read_b128 v[170:173], v166 offset:2048
	ds_read_b128 v[174:177], v166 offset:3072
	s_add_u32 s38, s36, 0xfffc0080
	s_addc_u32 s39, s37, -1
	s_cmp_eq_u32 s68, 12
	s_cselect_b32 s41, s9, s39
	s_cselect_b32 s40, s27, s38
	s_cselect_b32 s39, s25, s67
	s_cselect_b32 s38, s65, s66
	v_lshl_add_u64 v[178:179], s[36:37], 0, v[148:149]
	s_add_i32 m0, s35, 0xc000
	ds_read_b128 v[182:185], v167
	ds_read_b128 v[186:189], v167 offset:1024
	ds_read_b128 v[190:193], v167 offset:2048
	ds_read_b128 v[194:197], v167 offset:3072
	ds_read_b128 v[198:201], v167 offset:4096
	ds_read_b128 v[202:205], v167 offset:5120
	ds_read_b128 v[206:209], v167 offset:6144
	ds_read_b128 v[210:213], v167 offset:7168
	global_load_lds_dwordx4 v[178:179], off
	v_lshl_add_u64 v[178:179], s[36:37], 0, v[150:151]
	s_add_i32 m0, s35, 0xe000
	s_nop 0
	global_load_lds_dwordx4 v[178:179], off
	s_waitcnt vmcnt(8)
	s_waitcnt lgkmcnt(0)
	s_barrier
	s_setprio 1
	s_waitcnt lgkmcnt(0)
	s_bitcmp1_b32 s101, 0
	s_cbranch_scc0 .Lmm_6_0
	v_mfma_f32_16x16x32_bf16 v[124:127], v[128:131], v[182:185], v[124:127]
	v_mfma_f32_16x16x32_bf16 v[120:123], v[136:139], v[182:185], v[120:123]
	v_mfma_f32_16x16x32_bf16 v[108:111], v[128:131], v[190:193], v[108:111]
	v_mfma_f32_16x16x32_bf16 v[104:107], v[136:139], v[190:193], v[104:107]
	v_mfma_f32_16x16x32_bf16 v[92:95], v[128:131], v[198:201], v[92:95]
	v_mfma_f32_16x16x32_bf16 v[88:91], v[136:139], v[198:201], v[88:91]
	v_mfma_f32_16x16x32_bf16 v[76:79], v[128:131], v[206:209], v[76:79]
	v_mfma_f32_16x16x32_bf16 v[72:75], v[136:139], v[206:209], v[72:75]
	v_mfma_f32_16x16x32_bf16 v[124:127], v[132:135], v[186:189], v[124:127]
	v_mfma_f32_16x16x32_bf16 v[120:123], v[140:143], v[186:189], v[120:123]
	v_mfma_f32_16x16x32_bf16 v[108:111], v[132:135], v[194:197], v[108:111]
	v_mfma_f32_16x16x32_bf16 v[104:107], v[140:143], v[194:197], v[104:107]
	v_mfma_f32_16x16x32_bf16 v[92:95], v[132:135], v[202:205], v[92:95]
	v_mfma_f32_16x16x32_bf16 v[88:91], v[140:143], v[202:205], v[88:91]
	v_mfma_f32_16x16x32_bf16 v[76:79], v[132:135], v[210:213], v[76:79]
	v_mfma_f32_16x16x32_bf16 v[72:75], v[140:143], v[210:213], v[72:75]
.Lmm_6_0:
	s_setprio 0
	s_setprio 1
	s_bitcmp1_b32 s101, 1
	s_cbranch_scc0 .Lmm_6_1
	v_mfma_f32_16x16x32_bf16 v[116:119], v[156:159], v[182:185], v[116:119]
	v_mfma_f32_16x16x32_bf16 v[112:115], v[170:173], v[182:185], v[112:115]
	v_mfma_f32_16x16x32_bf16 v[100:103], v[156:159], v[190:193], v[100:103]
	v_mfma_f32_16x16x32_bf16 v[96:99], v[170:173], v[190:193], v[96:99]
	v_mfma_f32_16x16x32_bf16 v[84:87], v[156:159], v[198:201], v[84:87]
	v_mfma_f32_16x16x32_bf16 v[80:83], v[170:173], v[198:201], v[80:83]
	v_mfma_f32_16x16x32_bf16 v[68:71], v[156:159], v[206:209], v[68:71]
	v_mfma_f32_16x16x32_bf16 v[64:67], v[170:173], v[206:209], v[64:67]
	v_mfma_f32_16x16x32_bf16 v[116:119], v[160:163], v[186:189], v[116:119]
	v_mfma_f32_16x16x32_bf16 v[112:115], v[174:177], v[186:189], v[112:115]
	v_mfma_f32_16x16x32_bf16 v[100:103], v[160:163], v[194:197], v[100:103]
	v_mfma_f32_16x16x32_bf16 v[96:99], v[174:177], v[194:197], v[96:99]
	v_mfma_f32_16x16x32_bf16 v[84:87], v[160:163], v[202:205], v[84:87]
	v_mfma_f32_16x16x32_bf16 v[80:83], v[174:177], v[202:205], v[80:83]
	v_mfma_f32_16x16x32_bf16 v[68:71], v[160:163], v[210:213], v[68:71]
	v_mfma_f32_16x16x32_bf16 v[64:67], v[174:177], v[210:213], v[64:67]
.Lmm_6_1:
	s_setprio 0
	s_barrier
	s_add_i32 s69, s58, s48
	v_lshl_add_u64 v[178:179], s[38:39], 0, v[144:145]
	s_mov_b32 m0, s69
	ds_read_b128 v[182:185], v167 offset:16384
	ds_read_b128 v[186:189], v167 offset:17408
	ds_read_b128 v[190:193], v167 offset:18432
	ds_read_b128 v[194:197], v167 offset:19456
	ds_read_b128 v[198:201], v167 offset:20480
	ds_read_b128 v[202:205], v167 offset:21504
	ds_read_b128 v[206:209], v167 offset:22528
	ds_read_b128 v[210:213], v167 offset:23552
	global_load_lds_dwordx4 v[178:179], off
	s_add_i32 m0, s69, 0x2000
	s_add_u32 s70, s38, 0x40000
	v_lshl_add_u64 v[214:215], s[38:39], 0, v[146:147]
	s_addc_u32 s71, s39, 0
	s_add_i32 s69, s59, s48
	global_load_lds_dwordx4 v[214:215], off
	v_lshl_add_u64 v[216:217], s[70:71], 0, v[144:145]
	s_mov_b32 m0, s69
	v_lshl_add_u64 v[218:219], s[40:41], 0, v[146:147]
	global_load_lds_dwordx4 v[216:217], off
	v_lshl_add_u64 v[216:217], s[70:71], 0, v[146:147]
	s_add_i32 m0, s69, 0x2000
	s_nop 0
	global_load_lds_dwordx4 v[216:217], off
	v_lshl_add_u64 v[216:217], s[40:41], 0, v[144:145]
	s_mov_b32 m0, s35
	s_nop 0
	global_load_lds_dwordx4 v[216:217], off
	s_mov_b32 m0, s49
	s_nop 0
	global_load_lds_dwordx4 v[218:219], off
	s_waitcnt vmcnt(8)
	s_waitcnt lgkmcnt(0)
	s_barrier
	s_setprio 1
	s_waitcnt lgkmcnt(0)
	s_bitcmp1_b32 s101, 2
	s_cbranch_scc0 .Lmm_6_2
	v_mfma_f32_16x16x32_bf16 v[60:63], v[128:131], v[182:185], v[60:63]
	v_mfma_f32_16x16x32_bf16 v[56:59], v[136:139], v[182:185], v[56:59]
	v_mfma_f32_16x16x32_bf16 v[44:47], v[128:131], v[190:193], v[44:47]
	v_mfma_f32_16x16x32_bf16 v[40:43], v[136:139], v[190:193], v[40:43]
	v_mfma_f32_16x16x32_bf16 v[28:31], v[128:131], v[198:201], v[28:31]
	v_mfma_f32_16x16x32_bf16 v[24:27], v[136:139], v[198:201], v[24:27]
	v_mfma_f32_16x16x32_bf16 v[12:15], v[128:131], v[206:209], v[12:15]
	v_mfma_f32_16x16x32_bf16 v[8:11], v[136:139], v[206:209], v[8:11]
	v_mfma_f32_16x16x32_bf16 v[60:63], v[132:135], v[186:189], v[60:63]
	v_mfma_f32_16x16x32_bf16 v[56:59], v[140:143], v[186:189], v[56:59]
	v_mfma_f32_16x16x32_bf16 v[44:47], v[132:135], v[194:197], v[44:47]
	v_mfma_f32_16x16x32_bf16 v[40:43], v[140:143], v[194:197], v[40:43]
	v_mfma_f32_16x16x32_bf16 v[28:31], v[132:135], v[202:205], v[28:31]
	v_mfma_f32_16x16x32_bf16 v[24:27], v[140:143], v[202:205], v[24:27]
	v_mfma_f32_16x16x32_bf16 v[12:15], v[132:135], v[210:213], v[12:15]
	v_mfma_f32_16x16x32_bf16 v[8:11], v[140:143], v[210:213], v[8:11]
.Lmm_6_2:
	s_setprio 0
	s_setprio 1
	s_bitcmp1_b32 s101, 3
	s_cbranch_scc0 .Lmm_6_3
	v_mfma_f32_16x16x32_bf16 v[52:55], v[156:159], v[182:185], v[52:55]
	v_mfma_f32_16x16x32_bf16 v[48:51], v[170:173], v[182:185], v[48:51]
	v_mfma_f32_16x16x32_bf16 v[36:39], v[156:159], v[190:193], v[36:39]
	v_mfma_f32_16x16x32_bf16 v[32:35], v[170:173], v[190:193], v[32:35]
	v_mfma_f32_16x16x32_bf16 v[20:23], v[156:159], v[198:201], v[20:23]
	v_mfma_f32_16x16x32_bf16 v[16:19], v[170:173], v[198:201], v[16:19]
	v_mfma_f32_16x16x32_bf16 v[4:7], v[156:159], v[206:209], v[4:7]
	v_mfma_f32_16x16x32_bf16 v[0:3], v[170:173], v[206:209], v[0:3]
	v_mfma_f32_16x16x32_bf16 v[52:55], v[160:163], v[186:189], v[52:55]
	v_mfma_f32_16x16x32_bf16 v[48:51], v[174:177], v[186:189], v[48:51]
	v_mfma_f32_16x16x32_bf16 v[36:39], v[160:163], v[194:197], v[36:39]
	v_mfma_f32_16x16x32_bf16 v[32:35], v[174:177], v[194:197], v[32:35]
	v_mfma_f32_16x16x32_bf16 v[20:23], v[160:163], v[202:205], v[20:23]
	v_mfma_f32_16x16x32_bf16 v[16:19], v[174:177], v[202:205], v[16:19]
	v_mfma_f32_16x16x32_bf16 v[4:7], v[160:163], v[210:213], v[4:7]
	v_mfma_f32_16x16x32_bf16 v[0:3], v[174:177], v[210:213], v[0:3]
.Lmm_6_3:
	s_setprio 0
	s_barrier
	s_add_i32 s69, 0, 0x18000
	s_add_i32 s70, 0, 0x1c000
	v_add_u32_e32 v140, s69, v164
	v_add_u32_e32 v169, s70, v164
	ds_read_b128 v[128:131], v140
	ds_read_b128 v[132:135], v140 offset:1024
	ds_read_b128 v[136:139], v140 offset:2048
	ds_read_b128 v[140:143], v140 offset:3072
	ds_read_b128 v[156:159], v169
	ds_read_b128 v[160:163], v169 offset:1024
	ds_read_b128 v[170:173], v169 offset:2048
	ds_read_b128 v[174:177], v169 offset:3072
	s_add_u32 s40, s40, 0x40000
	s_addc_u32 s41, s41, 0
	s_mov_b32 m0, s50
	v_lshl_add_u64 v[220:221], s[40:41], 0, v[144:145]
	ds_read_b128 v[182:185], v167 offset:32768
	ds_read_b128 v[186:189], v167 offset:33792
	ds_read_b128 v[190:193], v167 offset:34816
	ds_read_b128 v[194:197], v167 offset:35840
	ds_read_b128 v[198:201], v167 offset:36864
	ds_read_b128 v[202:205], v167 offset:37888
	ds_read_b128 v[206:209], v167 offset:38912
	ds_read_b128 v[210:213], v167 offset:39936
	global_load_lds_dwordx4 v[220:221], off
	v_lshl_add_u64 v[220:221], s[40:41], 0, v[146:147]
	s_mov_b32 m0, s51
	s_nop 0
	global_load_lds_dwordx4 v[220:221], off
	s_waitcnt vmcnt(8)
	s_waitcnt lgkmcnt(0)
	s_barrier
	s_setprio 1
	s_waitcnt lgkmcnt(0)
	s_bitcmp1_b32 s101, 0
	s_cbranch_scc0 .Lmm_6_4
	v_mfma_f32_16x16x32_bf16 v[124:127], v[128:131], v[182:185], v[124:127]
	v_mfma_f32_16x16x32_bf16 v[120:123], v[136:139], v[182:185], v[120:123]
	v_mfma_f32_16x16x32_bf16 v[108:111], v[128:131], v[190:193], v[108:111]
	v_mfma_f32_16x16x32_bf16 v[104:107], v[136:139], v[190:193], v[104:107]
	v_mfma_f32_16x16x32_bf16 v[92:95], v[128:131], v[198:201], v[92:95]
	v_mfma_f32_16x16x32_bf16 v[88:91], v[136:139], v[198:201], v[88:91]
	v_mfma_f32_16x16x32_bf16 v[76:79], v[128:131], v[206:209], v[76:79]
	v_mfma_f32_16x16x32_bf16 v[72:75], v[136:139], v[206:209], v[72:75]
	v_mfma_f32_16x16x32_bf16 v[124:127], v[132:135], v[186:189], v[124:127]
	v_mfma_f32_16x16x32_bf16 v[120:123], v[140:143], v[186:189], v[120:123]
	v_mfma_f32_16x16x32_bf16 v[108:111], v[132:135], v[194:197], v[108:111]
	v_mfma_f32_16x16x32_bf16 v[104:107], v[140:143], v[194:197], v[104:107]
	v_mfma_f32_16x16x32_bf16 v[92:95], v[132:135], v[202:205], v[92:95]
	v_mfma_f32_16x16x32_bf16 v[88:91], v[140:143], v[202:205], v[88:91]
	v_mfma_f32_16x16x32_bf16 v[76:79], v[132:135], v[210:213], v[76:79]
	v_mfma_f32_16x16x32_bf16 v[72:75], v[140:143], v[210:213], v[72:75]

.Lmm_6_5:
	s_setprio 0
	s_barrier
	s_add_i32 s40, s69, s48
	v_lshl_add_u64 v[178:179], v[178:179], 0, s[20:21]
	s_mov_b32 m0, s40
	ds_read_b128 v[182:185], v167 offset:49152
	ds_read_b128 v[186:189], v167 offset:50176
	ds_read_b128 v[190:193], v167 offset:51200
	ds_read_b128 v[194:197], v167 offset:52224
	ds_read_b128 v[198:201], v167 offset:53248
	ds_read_b128 v[202:205], v167 offset:54272
	ds_read_b128 v[206:209], v167 offset:55296
	ds_read_b128 v[210:213], v167 offset:56320
	global_load_lds_dwordx4 v[178:179], off
	s_add_i32 m0, s40, 0x2000
	s_add_u32 s38, s38, 0x40080
	v_lshl_add_u64 v[178:179], v[214:215], 0, s[20:21]
	s_addc_u32 s39, s39, 0
	s_add_i32 s40, s70, s48
	global_load_lds_dwordx4 v[178:179], off
	v_lshl_add_u64 v[178:179], s[38:39], 0, v[144:145]
	s_mov_b32 m0, s40
	s_nop 0
	global_load_lds_dwordx4 v[178:179], off
	v_lshl_add_u64 v[178:179], s[38:39], 0, v[146:147]
	s_add_i32 m0, s40, 0x2000
	s_nop 0
	global_load_lds_dwordx4 v[178:179], off
	v_lshl_add_u64 v[178:179], v[216:217], 0, s[20:21]
	s_mov_b32 m0, s56
	s_nop 0
	global_load_lds_dwordx4 v[178:179], off
	v_lshl_add_u64 v[178:179], v[218:219], 0, s[20:21]
	s_mov_b32 m0, s57
	s_nop 0
	global_load_lds_dwordx4 v[178:179], off
	s_waitcnt vmcnt(8)
	s_waitcnt lgkmcnt(0)
	s_barrier
	s_setprio 1
	s_waitcnt lgkmcnt(0)
	s_bitcmp1_b32 s101, 2
	s_cbranch_scc0 .Lmm_6_6
	v_mfma_f32_16x16x32_bf16 v[60:63], v[128:131], v[182:185], v[60:63]
	v_mfma_f32_16x16x32_bf16 v[56:59], v[136:139], v[182:185], v[56:59]
	v_mfma_f32_16x16x32_bf16 v[44:47], v[128:131], v[190:193], v[44:47]
	v_mfma_f32_16x16x32_bf16 v[40:43], v[136:139], v[190:193], v[40:43]
	v_mfma_f32_16x16x32_bf16 v[28:31], v[128:131], v[198:201], v[28:31]
	v_mfma_f32_16x16x32_bf16 v[24:27], v[136:139], v[198:201], v[24:27]
	v_mfma_f32_16x16x32_bf16 v[12:15], v[128:131], v[206:209], v[12:15]
	v_mfma_f32_16x16x32_bf16 v[8:11], v[136:139], v[206:209], v[8:11]
	v_mfma_f32_16x16x32_bf16 v[60:63], v[132:135], v[186:189], v[60:63]
	v_mfma_f32_16x16x32_bf16 v[56:59], v[140:143], v[186:189], v[56:59]
	v_mfma_f32_16x16x32_bf16 v[44:47], v[132:135], v[194:197], v[44:47]
	v_mfma_f32_16x16x32_bf16 v[40:43], v[140:143], v[194:197], v[40:43]
	v_mfma_f32_16x16x32_bf16 v[28:31], v[132:135], v[202:205], v[28:31]
	v_mfma_f32_16x16x32_bf16 v[24:27], v[140:143], v[202:205], v[24:27]
	v_mfma_f32_16x16x32_bf16 v[12:15], v[132:135], v[210:213], v[12:15]
	v_mfma_f32_16x16x32_bf16 v[8:11], v[140:143], v[210:213], v[8:11]

.Lmm_6_7:
	s_setprio 0
	s_barrier
	s_add_i32 s68, s68, 2
	s_add_u32 s36, s36, 0x100
	s_addc_u32 s37, s37, 0
	s_add_u32 s66, s66, 0x100
	s_addc_u32 s67, s67, 0
	s_cmp_gt_u32 s68, 13
	s_cbranch_scc0 .LBB0_1436
	s_and_b64 vcc, exec, s[22:23]
	s_cbranch_vccz .LBB0_1439
	s_barrier
.LBB0_1439:
	s_bitcmp1_b32 s101, 6
	s_cbranch_scc1 .Lqepi_6
	v_and_b32_e32 v128, 63, v180
	v_and_b32_e32 v129, 15, v180
	v_bfe_u32 v130, v180, 4, 2
	v_lshrrev_b32_e32 v131, 6, v180
	v_lshlrev_b32_e32 v131, 12, v131
	v_add_u32_e32 v131, 0x20000, v131
	v_and_b32_e32 v132, 7, v129
	v_xor_b32_e32 v132, v130, v132
	v_lshlrev_b32_e32 v132, 4, v132
	v_lshl_add_u32 v132, v129, 8, v132
	v_add_u32_e32 v169, v131, v132
	v_xor_b32_e32 v170, 64, v169
	v_lshrrev_b32_e32 v133, 2, v128
	v_and_b32_e32 v134, 3, v128
	v_and_b32_e32 v135, 7, v133
	v_lshlrev_b32_e32 v136, 1, v134
	v_xor_b32_e32 v136, v136, v135
	v_lshlrev_b32_e32 v136, 4, v136
	v_lshl_add_u32 v136, v133, 8, v136
	v_add_u32_e32 v171, v131, v136
	v_xor_b32_e32 v172, 16, v171
	s_lshl_b32 s9, s34, 20
	s_cmp_lt_u32 s34, 0x100
	s_cselect_b32 s98, s12, s14
	s_cselect_b32 s99, s13, s15
	s_cselect_b32 s9, s9, 0
	s_add_u32 s98, s98, s9
	s_addc_u32 s99, s99, 0
	v_add_u32_e32 v137, s54, v133
	v_lshlrev_b32_e32 v137, 12, v137
	s_lshl_b32 s9, s8, 8
	s_add_i32 s9, s9, s55
	v_lshl_add_u32 v138, v134, 3, s9
	v_lshl_add_u32 v175, v138, 2, v137
	s_lshl_b32 s9, s34, 8
	s_add_i32 s9, s9, s54
	v_add_u32_e32 v139, s9, v133
	v_lshlrev_b32_e32 v174, 2, v139
	v_lshlrev_b32_e32 v139, 11, v139
	v_lshl_add_u32 v173, v138, 1, v139
	v_cmp_eq_u32_e32 vcc, 0, v134
	global_load_dwordx4 v[188:191], v175, s[98:99]
	global_load_dwordx4 v[192:195], v175, s[98:99] offset:16
	global_load_dwordx4 v[196:199], v175, s[98:99] offset:512
	global_load_dwordx4 v[200:203], v175, s[98:99] offset:528
	s_add_u32 s98, s98, 0x10000
	s_addc_u32 s99, s99, 0
	global_load_dwordx4 v[204:207], v175, s[98:99]
	global_load_dwordx4 v[208:211], v175, s[98:99] offset:16
	global_load_dwordx4 v[212:215], v175, s[98:99] offset:512
	global_load_dwordx4 v[216:219], v175, s[98:99] offset:528
	s_add_u32 s98, s98, 0x10000
	s_addc_u32 s99, s99, 0
	global_load_dwordx4 v[220:223], v175, s[98:99]
	global_load_dwordx4 v[224:227], v175, s[98:99] offset:16
	global_load_dwordx4 v[228:231], v175, s[98:99] offset:512
	global_load_dwordx4 v[232:235], v175, s[98:99] offset:528
	s_add_u32 s98, s98, 0x10000
	s_addc_u32 s99, s99, 0
	global_load_dwordx4 v[236:239], v175, s[98:99]
	global_load_dwordx4 v[240:243], v175, s[98:99] offset:16
	global_load_dwordx4 v[244:247], v175, s[98:99] offset:512
	global_load_dwordx4 v[248:251], v175, s[98:99] offset:528
	s_add_u32 s98, s98, 0x50000
	s_addc_u32 s99, s99, 0
	s_mov_b64 s[8:9], exec
	ds_write_b128 v169, v[124:127]
	ds_write_b128 v170, v[120:123]
	ds_write_b128 v169, v[116:119] offset:128
	ds_write_b128 v170, v[112:115] offset:128
	s_waitcnt lgkmcnt(0)
	ds_read_b128 v[128:131], v171
	ds_read_b128 v[132:135], v172
	ds_read_b128 v[136:139], v171 offset:128
	ds_read_b128 v[140:143], v172 offset:128
	s_waitcnt lgkmcnt(0)
	ds_write_b128 v169, v[108:111]
	ds_write_b128 v170, v[104:107]
	ds_write_b128 v169, v[100:103] offset:128
	ds_write_b128 v170, v[96:99] offset:128
	s_waitcnt vmcnt(12)
	v_pk_add_f32 v[128:129], v[128:129], v[188:189]
	v_pk_add_f32 v[130:131], v[130:131], v[190:191]
	v_pk_add_f32 v[132:133], v[132:133], v[192:193]
	v_pk_add_f32 v[134:135], v[134:135], v[194:195]
	v_pk_mul_f32 v[176:177], v[128:129], v[128:129]
	v_pk_fma_f32 v[176:177], v[130:131], v[130:131], v[176:177]
	v_pk_fma_f32 v[176:177], v[132:133], v[132:133], v[176:177]
	v_pk_fma_f32 v[176:177], v[134:135], v[134:135], v[176:177]
	v_cvt_pk_bf16_f32 v156, v128, v129
	v_cvt_pk_bf16_f32 v157, v130, v131
	v_cvt_pk_bf16_f32 v158, v132, v133
	v_cvt_pk_bf16_f32 v159, v134, v135
	global_store_dwordx4 v173, v[156:159], s[16:17]
	v_pk_add_f32 v[136:137], v[136:137], v[196:197]
	v_pk_add_f32 v[138:139], v[138:139], v[198:199]
	v_pk_add_f32 v[140:141], v[140:141], v[200:201]
	v_pk_add_f32 v[142:143], v[142:143], v[202:203]
	v_pk_fma_f32 v[176:177], v[136:137], v[136:137], v[176:177]
	v_pk_fma_f32 v[176:177], v[138:139], v[138:139], v[176:177]
	v_pk_fma_f32 v[176:177], v[140:141], v[140:141], v[176:177]
	v_pk_fma_f32 v[176:177], v[142:143], v[142:143], v[176:177]
	v_cvt_pk_bf16_f32 v160, v136, v137
	v_cvt_pk_bf16_f32 v161, v138, v139
	v_cvt_pk_bf16_f32 v162, v140, v141
	v_cvt_pk_bf16_f32 v163, v142, v143
	global_store_dwordx4 v173, v[160:163], s[16:17] offset:256
	v_add_f32_e32 v178, v176, v177
	s_nop 1
	v_add_f32_dpp v179, v178, v178 quad_perm:[1,0,3,2] row_mask:0xf bank_mask:0xf
	s_nop 1
	v_add_f32_dpp v181, v179, v179 quad_perm:[2,3,0,1] row_mask:0xf bank_mask:0xf
	s_mov_b64 exec, vcc
	global_atomic_add_f32 v174, v181, s[18:19] offset:0
	s_mov_b64 exec, s[8:9]
	global_load_dwordx4 v[188:191], v175, s[98:99]
	global_load_dwordx4 v[192:195], v175, s[98:99] offset:16
	global_load_dwordx4 v[196:199], v175, s[98:99] offset:512
	global_load_dwordx4 v[200:203], v175, s[98:99] offset:528
	s_add_u32 s98, s98, 0x10000
	s_addc_u32 s99, s99, 0
	v_add_u32_e32 v173, 0x8000, v173
	s_waitcnt lgkmcnt(0)
	ds_read_b128 v[128:131], v171
	ds_read_b128 v[132:135], v172
	ds_read_b128 v[136:139], v171 offset:128
	ds_read_b128 v[140:143], v172 offset:128
	s_waitcnt lgkmcnt(0)
	ds_write_b128 v169, v[92:95]
	ds_write_b128 v170, v[88:91]
	ds_write_b128 v169, v[84:87] offset:128
	ds_write_b128 v170, v[80:83] offset:128
	s_waitcnt vmcnt(15)
	v_pk_add_f32 v[128:129], v[128:129], v[204:205]
	v_pk_add_f32 v[130:131], v[130:131], v[206:207]
	v_pk_add_f32 v[132:133], v[132:133], v[208:209]
	v_pk_add_f32 v[134:135], v[134:135], v[210:211]
	v_pk_mul_f32 v[176:177], v[128:129], v[128:129]
	v_pk_fma_f32 v[176:177], v[130:131], v[130:131], v[176:177]
	v_pk_fma_f32 v[176:177], v[132:133], v[132:133], v[176:177]
	v_pk_fma_f32 v[176:177], v[134:135], v[134:135], v[176:177]
	v_cvt_pk_bf16_f32 v156, v128, v129
	v_cvt_pk_bf16_f32 v157, v130, v131
	v_cvt_pk_bf16_f32 v158, v132, v133
	v_cvt_pk_bf16_f32 v159, v134, v135
	global_store_dwordx4 v173, v[156:159], s[16:17]
	v_pk_add_f32 v[136:137], v[136:137], v[212:213]
	v_pk_add_f32 v[138:139], v[138:139], v[214:215]
	v_pk_add_f32 v[140:141], v[140:141], v[216:217]
	v_pk_add_f32 v[142:143], v[142:143], v[218:219]
	v_pk_fma_f32 v[176:177], v[136:137], v[136:137], v[176:177]
	v_pk_fma_f32 v[176:177], v[138:139], v[138:139], v[176:177]
	v_pk_fma_f32 v[176:177], v[140:141], v[140:141], v[176:177]
	v_pk_fma_f32 v[176:177], v[142:143], v[142:143], v[176:177]
	v_cvt_pk_bf16_f32 v160, v136, v137
	v_cvt_pk_bf16_f32 v161, v138, v139
	v_cvt_pk_bf16_f32 v162, v140, v141
	v_cvt_pk_bf16_f32 v163, v142, v143
	global_store_dwordx4 v173, v[160:163], s[16:17] offset:256
	v_add_f32_e32 v178, v176, v177
	s_nop 1
	v_add_f32_dpp v179, v178, v178 quad_perm:[1,0,3,2] row_mask:0xf bank_mask:0xf
	s_nop 1
	v_add_f32_dpp v181, v179, v179 quad_perm:[2,3,0,1] row_mask:0xf bank_mask:0xf
	s_mov_b64 exec, vcc
	global_atomic_add_f32 v174, v181, s[18:19] offset:64
	s_mov_b64 exec, s[8:9]
	global_load_dwordx4 v[204:207], v175, s[98:99]
	global_load_dwordx4 v[208:211], v175, s[98:99] offset:16
	global_load_dwordx4 v[212:215], v175, s[98:99] offset:512
	global_load_dwordx4 v[216:219], v175, s[98:99] offset:528
	s_add_u32 s98, s98, 0x10000
	s_addc_u32 s99, s99, 0
	v_add_u32_e32 v173, 0x8000, v173
	s_waitcnt lgkmcnt(0)
	ds_read_b128 v[128:131], v171
	ds_read_b128 v[132:135], v172
	ds_read_b128 v[136:139], v171 offset:128
	ds_read_b128 v[140:143], v172 offset:128
	s_waitcnt lgkmcnt(0)
	ds_write_b128 v169, v[76:79]
	ds_write_b128 v170, v[72:75]
	ds_write_b128 v169, v[68:71] offset:128
	ds_write_b128 v170, v[64:67] offset:128
	s_waitcnt vmcnt(18)
	v_pk_add_f32 v[128:129], v[128:129], v[220:221]
	v_pk_add_f32 v[130:131], v[130:131], v[222:223]
	v_pk_add_f32 v[132:133], v[132:133], v[224:225]
	v_pk_add_f32 v[134:135], v[134:135], v[226:227]
	v_pk_mul_f32 v[176:177], v[128:129], v[128:129]
	v_pk_fma_f32 v[176:177], v[130:131], v[130:131], v[176:177]
	v_pk_fma_f32 v[176:177], v[132:133], v[132:133], v[176:177]
	v_pk_fma_f32 v[176:177], v[134:135], v[134:135], v[176:177]
	v_cvt_pk_bf16_f32 v156, v128, v129
	v_cvt_pk_bf16_f32 v157, v130, v131
	v_cvt_pk_bf16_f32 v158, v132, v133
	v_cvt_pk_bf16_f32 v159, v134, v135
	global_store_dwordx4 v173, v[156:159], s[16:17]
	v_pk_add_f32 v[136:137], v[136:137], v[228:229]
	v_pk_add_f32 v[138:139], v[138:139], v[230:231]
	v_pk_add_f32 v[140:141], v[140:141], v[232:233]
	v_pk_add_f32 v[142:143], v[142:143], v[234:235]
	v_pk_fma_f32 v[176:177], v[136:137], v[136:137], v[176:177]
	v_pk_fma_f32 v[176:177], v[138:139], v[138:139], v[176:177]
	v_pk_fma_f32 v[176:177], v[140:141], v[140:141], v[176:177]
	v_pk_fma_f32 v[176:177], v[142:143], v[142:143], v[176:177]
	v_cvt_pk_bf16_f32 v160, v136, v137
	v_cvt_pk_bf16_f32 v161, v138, v139
	v_cvt_pk_bf16_f32 v162, v140, v141
	v_cvt_pk_bf16_f32 v163, v142, v143
	global_store_dwordx4 v173, v[160:163], s[16:17] offset:256
	v_add_f32_e32 v178, v176, v177
	s_nop 1
	v_add_f32_dpp v179, v178, v178 quad_perm:[1,0,3,2] row_mask:0xf bank_mask:0xf
	s_nop 1
	v_add_f32_dpp v181, v179, v179 quad_perm:[2,3,0,1] row_mask:0xf bank_mask:0xf
	s_mov_b64 exec, vcc
	global_atomic_add_f32 v174, v181, s[18:19] offset:128
	s_mov_b64 exec, s[8:9]
	global_load_dwordx4 v[220:223], v175, s[98:99]
	global_load_dwordx4 v[224:227], v175, s[98:99] offset:16
	global_load_dwordx4 v[228:231], v175, s[98:99] offset:512
	global_load_dwordx4 v[232:235], v175, s[98:99] offset:528
	s_add_u32 s98, s98, 0x10000
	s_addc_u32 s99, s99, 0
	v_add_u32_e32 v173, 0x8000, v173
	s_waitcnt lgkmcnt(0)
	ds_read_b128 v[128:131], v171
	ds_read_b128 v[132:135], v172
	ds_read_b128 v[136:139], v171 offset:128
	ds_read_b128 v[140:143], v172 offset:128
	s_waitcnt lgkmcnt(0)
	ds_write_b128 v169, v[60:63]
	ds_write_b128 v170, v[56:59]
	ds_write_b128 v169, v[52:55] offset:128
	ds_write_b128 v170, v[48:51] offset:128
	s_waitcnt vmcnt(21)
	v_pk_add_f32 v[128:129], v[128:129], v[236:237]
	v_pk_add_f32 v[130:131], v[130:131], v[238:239]
	v_pk_add_f32 v[132:133], v[132:133], v[240:241]
	v_pk_add_f32 v[134:135], v[134:135], v[242:243]
	v_pk_mul_f32 v[176:177], v[128:129], v[128:129]
	v_pk_fma_f32 v[176:177], v[130:131], v[130:131], v[176:177]
	v_pk_fma_f32 v[176:177], v[132:133], v[132:133], v[176:177]
	v_pk_fma_f32 v[176:177], v[134:135], v[134:135], v[176:177]
	v_cvt_pk_bf16_f32 v156, v128, v129
	v_cvt_pk_bf16_f32 v157, v130, v131
	v_cvt_pk_bf16_f32 v158, v132, v133
	v_cvt_pk_bf16_f32 v159, v134, v135
	global_store_dwordx4 v173, v[156:159], s[16:17]
	v_pk_add_f32 v[136:137], v[136:137], v[244:245]
	v_pk_add_f32 v[138:139], v[138:139], v[246:247]
	v_pk_add_f32 v[140:141], v[140:141], v[248:249]
	v_pk_add_f32 v[142:143], v[142:143], v[250:251]
	v_pk_fma_f32 v[176:177], v[136:137], v[136:137], v[176:177]
	v_pk_fma_f32 v[176:177], v[138:139], v[138:139], v[176:177]
	v_pk_fma_f32 v[176:177], v[140:141], v[140:141], v[176:177]
	v_pk_fma_f32 v[176:177], v[142:143], v[142:143], v[176:177]
	v_cvt_pk_bf16_f32 v160, v136, v137
	v_cvt_pk_bf16_f32 v161, v138, v139
	v_cvt_pk_bf16_f32 v162, v140, v141
	v_cvt_pk_bf16_f32 v163, v142, v143
	global_store_dwordx4 v173, v[160:163], s[16:17] offset:256
	v_add_f32_e32 v178, v176, v177
	s_nop 1
	v_add_f32_dpp v179, v178, v178 quad_perm:[1,0,3,2] row_mask:0xf bank_mask:0xf
	s_nop 1
	v_add_f32_dpp v181, v179, v179 quad_perm:[2,3,0,1] row_mask:0xf bank_mask:0xf
	s_mov_b64 exec, vcc
	global_atomic_add_f32 v174, v181, s[18:19] offset:192
	s_mov_b64 exec, s[8:9]
	global_load_dwordx4 v[236:239], v175, s[98:99]
	global_load_dwordx4 v[240:243], v175, s[98:99] offset:16
	global_load_dwordx4 v[244:247], v175, s[98:99] offset:512
	global_load_dwordx4 v[248:251], v175, s[98:99] offset:528
	v_add_u32_e32 v173, 0x28000, v173
	s_waitcnt lgkmcnt(0)
	ds_read_b128 v[128:131], v171
	ds_read_b128 v[132:135], v172
	ds_read_b128 v[136:139], v171 offset:128
	ds_read_b128 v[140:143], v172 offset:128
	s_waitcnt lgkmcnt(0)
	ds_write_b128 v169, v[44:47]
	ds_write_b128 v170, v[40:43]
	ds_write_b128 v169, v[36:39] offset:128
	ds_write_b128 v170, v[32:35] offset:128
	s_waitcnt vmcnt(21)
	v_pk_add_f32 v[128:129], v[128:129], v[188:189]
	v_pk_add_f32 v[130:131], v[130:131], v[190:191]
	v_pk_add_f32 v[132:133], v[132:133], v[192:193]
	v_pk_add_f32 v[134:135], v[134:135], v[194:195]
	v_pk_mul_f32 v[176:177], v[128:129], v[128:129]
	v_pk_fma_f32 v[176:177], v[130:131], v[130:131], v[176:177]
	v_pk_fma_f32 v[176:177], v[132:133], v[132:133], v[176:177]
	v_pk_fma_f32 v[176:177], v[134:135], v[134:135], v[176:177]
	v_cvt_pk_bf16_f32 v156, v128, v129
	v_cvt_pk_bf16_f32 v157, v130, v131
	v_cvt_pk_bf16_f32 v158, v132, v133
	v_cvt_pk_bf16_f32 v159, v134, v135
	global_store_dwordx4 v173, v[156:159], s[16:17]
	v_pk_add_f32 v[136:137], v[136:137], v[196:197]
	v_pk_add_f32 v[138:139], v[138:139], v[198:199]
	v_pk_add_f32 v[140:141], v[140:141], v[200:201]
	v_pk_add_f32 v[142:143], v[142:143], v[202:203]
	v_pk_fma_f32 v[176:177], v[136:137], v[136:137], v[176:177]
	v_pk_fma_f32 v[176:177], v[138:139], v[138:139], v[176:177]
	v_pk_fma_f32 v[176:177], v[140:141], v[140:141], v[176:177]
	v_pk_fma_f32 v[176:177], v[142:143], v[142:143], v[176:177]
	v_cvt_pk_bf16_f32 v160, v136, v137
	v_cvt_pk_bf16_f32 v161, v138, v139
	v_cvt_pk_bf16_f32 v162, v140, v141
	v_cvt_pk_bf16_f32 v163, v142, v143
	global_store_dwordx4 v173, v[160:163], s[16:17] offset:256
	v_add_f32_e32 v178, v176, v177
	s_nop 1
	v_add_f32_dpp v179, v178, v178 quad_perm:[1,0,3,2] row_mask:0xf bank_mask:0xf
	s_nop 1
	v_add_f32_dpp v181, v179, v179 quad_perm:[2,3,0,1] row_mask:0xf bank_mask:0xf
	s_mov_b64 exec, vcc
	global_atomic_add_f32 v174, v181, s[18:19] offset:512
	s_mov_b64 exec, s[8:9]
	v_add_u32_e32 v173, 0x8000, v173
	s_waitcnt lgkmcnt(0)
	ds_read_b128 v[128:131], v171
	ds_read_b128 v[132:135], v172
	ds_read_b128 v[136:139], v171 offset:128
	ds_read_b128 v[140:143], v172 offset:128
	s_waitcnt lgkmcnt(0)
	ds_write_b128 v169, v[28:31]
	ds_write_b128 v170, v[24:27]
	ds_write_b128 v169, v[20:23] offset:128
	ds_write_b128 v170, v[16:19] offset:128
	s_waitcnt vmcnt(17)
	v_pk_add_f32 v[128:129], v[128:129], v[204:205]
	v_pk_add_f32 v[130:131], v[130:131], v[206:207]
	v_pk_add_f32 v[132:133], v[132:133], v[208:209]
	v_pk_add_f32 v[134:135], v[134:135], v[210:211]
	v_pk_mul_f32 v[176:177], v[128:129], v[128:129]
	v_pk_fma_f32 v[176:177], v[130:131], v[130:131], v[176:177]
	v_pk_fma_f32 v[176:177], v[132:133], v[132:133], v[176:177]
	v_pk_fma_f32 v[176:177], v[134:135], v[134:135], v[176:177]
	v_cvt_pk_bf16_f32 v156, v128, v129
	v_cvt_pk_bf16_f32 v157, v130, v131
	v_cvt_pk_bf16_f32 v158, v132, v133
	v_cvt_pk_bf16_f32 v159, v134, v135
	global_store_dwordx4 v173, v[156:159], s[16:17]
	v_pk_add_f32 v[136:137], v[136:137], v[212:213]
	v_pk_add_f32 v[138:139], v[138:139], v[214:215]
	v_pk_add_f32 v[140:141], v[140:141], v[216:217]
	v_pk_add_f32 v[142:143], v[142:143], v[218:219]
	v_pk_fma_f32 v[176:177], v[136:137], v[136:137], v[176:177]
	v_pk_fma_f32 v[176:177], v[138:139], v[138:139], v[176:177]
	v_pk_fma_f32 v[176:177], v[140:141], v[140:141], v[176:177]
	v_pk_fma_f32 v[176:177], v[142:143], v[142:143], v[176:177]
	v_cvt_pk_bf16_f32 v160, v136, v137
	v_cvt_pk_bf16_f32 v161, v138, v139
	v_cvt_pk_bf16_f32 v162, v140, v141
	v_cvt_pk_bf16_f32 v163, v142, v143
	global_store_dwordx4 v173, v[160:163], s[16:17] offset:256
	v_add_f32_e32 v178, v176, v177
	s_nop 1
	v_add_f32_dpp v179, v178, v178 quad_perm:[1,0,3,2] row_mask:0xf bank_mask:0xf
	s_nop 1
	v_add_f32_dpp v181, v179, v179 quad_perm:[2,3,0,1] row_mask:0xf bank_mask:0xf
	s_mov_b64 exec, vcc
	global_atomic_add_f32 v174, v181, s[18:19] offset:576
	s_mov_b64 exec, s[8:9]
	v_add_u32_e32 v173, 0x8000, v173
	s_waitcnt lgkmcnt(0)
	ds_read_b128 v[128:131], v171
	ds_read_b128 v[132:135], v172
	ds_read_b128 v[136:139], v171 offset:128
	ds_read_b128 v[140:143], v172 offset:128
	s_waitcnt lgkmcnt(0)
	ds_write_b128 v169, v[12:15]
	ds_write_b128 v170, v[8:11]
	ds_write_b128 v169, v[4:7] offset:128
	ds_write_b128 v170, v[0:3] offset:128
	s_waitcnt vmcnt(13)
	v_pk_add_f32 v[128:129], v[128:129], v[220:221]
	v_pk_add_f32 v[130:131], v[130:131], v[222:223]
	v_pk_add_f32 v[132:133], v[132:133], v[224:225]
	v_pk_add_f32 v[134:135], v[134:135], v[226:227]
	v_pk_mul_f32 v[176:177], v[128:129], v[128:129]
	v_pk_fma_f32 v[176:177], v[130:131], v[130:131], v[176:177]
	v_pk_fma_f32 v[176:177], v[132:133], v[132:133], v[176:177]
	v_pk_fma_f32 v[176:177], v[134:135], v[134:135], v[176:177]
	v_cvt_pk_bf16_f32 v156, v128, v129
	v_cvt_pk_bf16_f32 v157, v130, v131
	v_cvt_pk_bf16_f32 v158, v132, v133
	v_cvt_pk_bf16_f32 v159, v134, v135
	global_store_dwordx4 v173, v[156:159], s[16:17]
	v_pk_add_f32 v[136:137], v[136:137], v[228:229]
	v_pk_add_f32 v[138:139], v[138:139], v[230:231]
	v_pk_add_f32 v[140:141], v[140:141], v[232:233]
	v_pk_add_f32 v[142:143], v[142:143], v[234:235]
	v_pk_fma_f32 v[176:177], v[136:137], v[136:137], v[176:177]
	v_pk_fma_f32 v[176:177], v[138:139], v[138:139], v[176:177]
	v_pk_fma_f32 v[176:177], v[140:141], v[140:141], v[176:177]
	v_pk_fma_f32 v[176:177], v[142:143], v[142:143], v[176:177]
	v_cvt_pk_bf16_f32 v160, v136, v137
	v_cvt_pk_bf16_f32 v161, v138, v139
	v_cvt_pk_bf16_f32 v162, v140, v141
	v_cvt_pk_bf16_f32 v163, v142, v143
	global_store_dwordx4 v173, v[160:163], s[16:17] offset:256
	v_add_f32_e32 v178, v176, v177
	s_nop 1
	v_add_f32_dpp v179, v178, v178 quad_perm:[1,0,3,2] row_mask:0xf bank_mask:0xf
	s_nop 1
	v_add_f32_dpp v181, v179, v179 quad_perm:[2,3,0,1] row_mask:0xf bank_mask:0xf
	s_mov_b64 exec, vcc
	global_atomic_add_f32 v174, v181, s[18:19] offset:640
	s_mov_b64 exec, s[8:9]
	v_add_u32_e32 v173, 0x8000, v173
	s_waitcnt lgkmcnt(0)
	ds_read_b128 v[128:131], v171
	ds_read_b128 v[132:135], v172
	ds_read_b128 v[136:139], v171 offset:128
	ds_read_b128 v[140:143], v172 offset:128
	s_waitcnt lgkmcnt(0)
	s_waitcnt vmcnt(9)
	v_pk_add_f32 v[128:129], v[128:129], v[236:237]
	v_pk_add_f32 v[130:131], v[130:131], v[238:239]
	v_pk_add_f32 v[132:133], v[132:133], v[240:241]
	v_pk_add_f32 v[134:135], v[134:135], v[242:243]
	v_pk_mul_f32 v[176:177], v[128:129], v[128:129]
	v_pk_fma_f32 v[176:177], v[130:131], v[130:131], v[176:177]
	v_pk_fma_f32 v[176:177], v[132:133], v[132:133], v[176:177]
	v_pk_fma_f32 v[176:177], v[134:135], v[134:135], v[176:177]
	v_cvt_pk_bf16_f32 v156, v128, v129
	v_cvt_pk_bf16_f32 v157, v130, v131
	v_cvt_pk_bf16_f32 v158, v132, v133
	v_cvt_pk_bf16_f32 v159, v134, v135
	global_store_dwordx4 v173, v[156:159], s[16:17]
	v_pk_add_f32 v[136:137], v[136:137], v[244:245]
	v_pk_add_f32 v[138:139], v[138:139], v[246:247]
	v_pk_add_f32 v[140:141], v[140:141], v[248:249]
	v_pk_add_f32 v[142:143], v[142:143], v[250:251]
	v_pk_fma_f32 v[176:177], v[136:137], v[136:137], v[176:177]
	v_pk_fma_f32 v[176:177], v[138:139], v[138:139], v[176:177]
	v_pk_fma_f32 v[176:177], v[140:141], v[140:141], v[176:177]
	v_pk_fma_f32 v[176:177], v[142:143], v[142:143], v[176:177]
	v_cvt_pk_bf16_f32 v160, v136, v137
	v_cvt_pk_bf16_f32 v161, v138, v139
	v_cvt_pk_bf16_f32 v162, v140, v141
	v_cvt_pk_bf16_f32 v163, v142, v143
	global_store_dwordx4 v173, v[160:163], s[16:17] offset:256
	v_add_f32_e32 v178, v176, v177
	s_nop 1
	v_add_f32_dpp v179, v178, v178 quad_perm:[1,0,3,2] row_mask:0xf bank_mask:0xf
	s_nop 1
	v_add_f32_dpp v181, v179, v179 quad_perm:[2,3,0,1] row_mask:0xf bank_mask:0xf
	s_mov_b64 exec, vcc
	global_atomic_add_f32 v174, v181, s[18:19] offset:704
	s_mov_b64 exec, s[8:9]
	s_branch .Lqepi_end_6
.Lqepi_6:
	s_bfe_u32 s98, s101, 0x20004
	s_cmp_eq_u32 s98, 0
	s_cbranch_scc1 .Lqn_done_ph6
	s_cmp_eq_u32 s98, 1
	s_cbranch_scc0 .Lqn_2_ph6
	v_mov_b32_e32 v124, v116
	v_mov_b32_e32 v125, v117
	v_mov_b32_e32 v126, v118
	v_mov_b32_e32 v127, v119
	v_mov_b32_e32 v120, v112
	v_mov_b32_e32 v121, v113
	v_mov_b32_e32 v122, v114
	v_mov_b32_e32 v123, v115
	v_mov_b32_e32 v108, v100
	v_mov_b32_e32 v109, v101
	v_mov_b32_e32 v110, v102
	v_mov_b32_e32 v111, v103
	v_mov_b32_e32 v104, v96
	v_mov_b32_e32 v105, v97
	v_mov_b32_e32 v106, v98
	v_mov_b32_e32 v107, v99
	v_mov_b32_e32 v92, v84
	v_mov_b32_e32 v93, v85
	v_mov_b32_e32 v94, v86
	v_mov_b32_e32 v95, v87
	v_mov_b32_e32 v88, v80
	v_mov_b32_e32 v89, v81
	v_mov_b32_e32 v90, v82
	v_mov_b32_e32 v91, v83
	v_mov_b32_e32 v76, v68
	v_mov_b32_e32 v77, v69
	v_mov_b32_e32 v78, v70
	v_mov_b32_e32 v79, v71
	v_mov_b32_e32 v72, v64
	v_mov_b32_e32 v73, v65
	v_mov_b32_e32 v74, v66
	v_mov_b32_e32 v75, v67
	s_branch .Lqn_done_ph6
.Lqn_2_ph6:
	s_cmp_eq_u32 s98, 2
	s_cbranch_scc0 .Lqn_3_ph6
	v_mov_b32_e32 v124, v60
	v_mov_b32_e32 v125, v61
	v_mov_b32_e32 v126, v62
	v_mov_b32_e32 v127, v63
	v_mov_b32_e32 v120, v56
	v_mov_b32_e32 v121, v57
	v_mov_b32_e32 v122, v58
	v_mov_b32_e32 v123, v59
	v_mov_b32_e32 v108, v44
	v_mov_b32_e32 v109, v45
	v_mov_b32_e32 v110, v46
	v_mov_b32_e32 v111, v47
	v_mov_b32_e32 v104, v40
	v_mov_b32_e32 v105, v41
	v_mov_b32_e32 v106, v42
	v_mov_b32_e32 v107, v43
	v_mov_b32_e32 v92, v28
	v_mov_b32_e32 v93, v29
	v_mov_b32_e32 v94, v30
	v_mov_b32_e32 v95, v31
	v_mov_b32_e32 v88, v24
	v_mov_b32_e32 v89, v25
	v_mov_b32_e32 v90, v26
	v_mov_b32_e32 v91, v27
	v_mov_b32_e32 v76, v12
	v_mov_b32_e32 v77, v13
	v_mov_b32_e32 v78, v14
	v_mov_b32_e32 v79, v15
	v_mov_b32_e32 v72, v8
	v_mov_b32_e32 v73, v9
	v_mov_b32_e32 v74, v10
	v_mov_b32_e32 v75, v11
	s_branch .Lqn_done_ph6
.Lqn_3_ph6:
	v_mov_b32_e32 v124, v52
	v_mov_b32_e32 v125, v53
	v_mov_b32_e32 v126, v54
	v_mov_b32_e32 v127, v55
	v_mov_b32_e32 v120, v48
	v_mov_b32_e32 v121, v49
	v_mov_b32_e32 v122, v50
	v_mov_b32_e32 v123, v51
	v_mov_b32_e32 v108, v36
	v_mov_b32_e32 v109, v37
	v_mov_b32_e32 v110, v38
	v_mov_b32_e32 v111, v39
	v_mov_b32_e32 v104, v32
	v_mov_b32_e32 v105, v33
	v_mov_b32_e32 v106, v34
	v_mov_b32_e32 v107, v35
	v_mov_b32_e32 v92, v20
	v_mov_b32_e32 v93, v21
	v_mov_b32_e32 v94, v22
	v_mov_b32_e32 v95, v23
	v_mov_b32_e32 v88, v16
	v_mov_b32_e32 v89, v17
	v_mov_b32_e32 v90, v18
	v_mov_b32_e32 v91, v19
	v_mov_b32_e32 v76, v4
	v_mov_b32_e32 v77, v5
	v_mov_b32_e32 v78, v6
	v_mov_b32_e32 v79, v7
	v_mov_b32_e32 v72, v0
	v_mov_b32_e32 v73, v1
	v_mov_b32_e32 v74, v2
	v_mov_b32_e32 v75, v3
.Lqn_done_ph6:
	v_and_b32_e32 v128, 63, v180
	v_and_b32_e32 v129, 15, v180
	v_bfe_u32 v130, v180, 4, 2
	v_lshrrev_b32_e32 v131, 6, v180
	v_lshlrev_b32_e32 v131, 12, v131
	v_add_u32_e32 v131, 0x20000, v131
	v_and_b32_e32 v132, 7, v129
	v_xor_b32_e32 v132, v130, v132
	v_lshlrev_b32_e32 v132, 4, v132
	v_lshl_add_u32 v132, v129, 8, v132
	v_add_u32_e32 v169, v131, v132
	v_xor_b32_e32 v170, 64, v169
	v_lshrrev_b32_e32 v133, 2, v128
	v_and_b32_e32 v134, 3, v128
	v_and_b32_e32 v135, 7, v133
	v_lshlrev_b32_e32 v136, 1, v134
	v_xor_b32_e32 v136, v136, v135
	v_lshlrev_b32_e32 v136, 4, v136
	v_lshl_add_u32 v136, v133, 8, v136
	v_add_u32_e32 v171, v131, v136
	v_xor_b32_e32 v172, 16, v171
	s_lshr_b32 s99, s98, 1
	s_lshl_b32 s99, s99, 7
	v_add_u32_e32 v137, s54, v133
	v_add_u32_e32 v137, s99, v137
	s_lshl_b32 s9, s34, 8
	s_add_i32 s9, s9, s54
	s_add_i32 s9, s9, s99
	v_add_u32_e32 v139, s9, v133
	v_lshlrev_b32_e32 v174, 2, v139
	v_lshlrev_b32_e32 v139, 11, v139
	v_lshlrev_b32_e32 v137, 12, v137
	s_and_b32 s99, s98, 1
	s_lshl_b32 s99, s99, 7
	s_lshl_b32 s9, s8, 8
	s_add_i32 s9, s9, s55
	s_add_i32 s9, s9, s99
	v_lshl_add_u32 v138, v134, 3, s9
	v_lshl_add_u32 v175, v138, 2, v137
	v_lshl_add_u32 v173, v138, 1, v139
	v_cmp_eq_u32_e32 vcc, 0, v134
	s_lshl_b32 s9, s34, 20
	s_cmp_lt_u32 s34, 0x100
	s_cselect_b32 s98, s12, s14
	s_cselect_b32 s99, s13, s15
	s_cselect_b32 s9, s9, 0
	s_add_u32 s98, s98, s9
	s_addc_u32 s99, s99, 0
	global_load_dwordx4 v[188:191], v175, s[98:99]
	global_load_dwordx4 v[192:195], v175, s[98:99] offset:16
	s_add_u32 s98, s98, 0x10000
	s_addc_u32 s99, s99, 0
	global_load_dwordx4 v[196:199], v175, s[98:99]
	global_load_dwordx4 v[200:203], v175, s[98:99] offset:16
	s_add_u32 s98, s98, 0x10000
	s_addc_u32 s99, s99, 0
	global_load_dwordx4 v[204:207], v175, s[98:99]
	global_load_dwordx4 v[208:211], v175, s[98:99] offset:16
	s_add_u32 s98, s98, 0x10000
	s_addc_u32 s99, s99, 0
	global_load_dwordx4 v[212:215], v175, s[98:99]
	global_load_dwordx4 v[216:219], v175, s[98:99] offset:16
	s_mov_b64 s[8:9], exec
	ds_write_b128 v169, v[124:127]
	ds_write_b128 v170, v[120:123]
	s_waitcnt lgkmcnt(0)
	ds_read_b128 v[128:131], v171
	ds_read_b128 v[132:135], v172
	s_waitcnt vmcnt(0)
	s_waitcnt lgkmcnt(0)
	v_pk_add_f32 v[128:129], v[128:129], v[188:189]
	v_pk_add_f32 v[130:131], v[130:131], v[190:191]
	v_pk_add_f32 v[132:133], v[132:133], v[192:193]
	v_pk_add_f32 v[134:135], v[134:135], v[194:195]
	v_pk_mul_f32 v[176:177], v[128:129], v[128:129]
	v_pk_fma_f32 v[176:177], v[130:131], v[130:131], v[176:177]
	v_pk_fma_f32 v[176:177], v[132:133], v[132:133], v[176:177]
	v_pk_fma_f32 v[176:177], v[134:135], v[134:135], v[176:177]
	v_cvt_pk_bf16_f32 v156, v128, v129
	v_cvt_pk_bf16_f32 v157, v130, v131
	v_cvt_pk_bf16_f32 v158, v132, v133
	v_cvt_pk_bf16_f32 v159, v134, v135
	global_store_dwordx4 v173, v[156:159], s[16:17]
	v_add_f32_e32 v178, v176, v177
	s_nop 1
	v_add_f32_dpp v179, v178, v178 quad_perm:[1,0,3,2] row_mask:0xf bank_mask:0xf
	s_nop 1
	v_add_f32_dpp v181, v179, v179 quad_perm:[2,3,0,1] row_mask:0xf bank_mask:0xf
	s_mov_b64 exec, vcc
	global_atomic_add_f32 v174, v181, s[18:19] offset:0
	s_mov_b64 exec, s[8:9]
	v_add_u32_e32 v173, 0x8000, v173
	ds_write_b128 v169, v[108:111]
	ds_write_b128 v170, v[104:107]
	s_waitcnt lgkmcnt(0)
	ds_read_b128 v[128:131], v171
	ds_read_b128 v[132:135], v172
	s_waitcnt vmcnt(0)
	s_waitcnt lgkmcnt(0)
	v_pk_add_f32 v[128:129], v[128:129], v[196:197]
	v_pk_add_f32 v[130:131], v[130:131], v[198:199]
	v_pk_add_f32 v[132:133], v[132:133], v[200:201]
	v_pk_add_f32 v[134:135], v[134:135], v[202:203]
	v_pk_mul_f32 v[176:177], v[128:129], v[128:129]
	v_pk_fma_f32 v[176:177], v[130:131], v[130:131], v[176:177]
	v_pk_fma_f32 v[176:177], v[132:133], v[132:133], v[176:177]
	v_pk_fma_f32 v[176:177], v[134:135], v[134:135], v[176:177]
	v_cvt_pk_bf16_f32 v156, v128, v129
	v_cvt_pk_bf16_f32 v157, v130, v131
	v_cvt_pk_bf16_f32 v158, v132, v133
	v_cvt_pk_bf16_f32 v159, v134, v135
	global_store_dwordx4 v173, v[156:159], s[16:17]
	v_add_f32_e32 v178, v176, v177
	s_nop 1
	v_add_f32_dpp v179, v178, v178 quad_perm:[1,0,3,2] row_mask:0xf bank_mask:0xf
	s_nop 1
	v_add_f32_dpp v181, v179, v179 quad_perm:[2,3,0,1] row_mask:0xf bank_mask:0xf
	s_mov_b64 exec, vcc
	global_atomic_add_f32 v174, v181, s[18:19] offset:64
	s_mov_b64 exec, s[8:9]
	v_add_u32_e32 v173, 0x8000, v173
	ds_write_b128 v169, v[92:95]
	ds_write_b128 v170, v[88:91]
	s_waitcnt lgkmcnt(0)
	ds_read_b128 v[128:131], v171
	ds_read_b128 v[132:135], v172
	s_waitcnt vmcnt(0)
	s_waitcnt lgkmcnt(0)
	v_pk_add_f32 v[128:129], v[128:129], v[204:205]
	v_pk_add_f32 v[130:131], v[130:131], v[206:207]
	v_pk_add_f32 v[132:133], v[132:133], v[208:209]
	v_pk_add_f32 v[134:135], v[134:135], v[210:211]
	v_pk_mul_f32 v[176:177], v[128:129], v[128:129]
	v_pk_fma_f32 v[176:177], v[130:131], v[130:131], v[176:177]
	v_pk_fma_f32 v[176:177], v[132:133], v[132:133], v[176:177]
	v_pk_fma_f32 v[176:177], v[134:135], v[134:135], v[176:177]
	v_cvt_pk_bf16_f32 v156, v128, v129
	v_cvt_pk_bf16_f32 v157, v130, v131
	v_cvt_pk_bf16_f32 v158, v132, v133
	v_cvt_pk_bf16_f32 v159, v134, v135
	global_store_dwordx4 v173, v[156:159], s[16:17]
	v_add_f32_e32 v178, v176, v177
	s_nop 1
	v_add_f32_dpp v179, v178, v178 quad_perm:[1,0,3,2] row_mask:0xf bank_mask:0xf
	s_nop 1
	v_add_f32_dpp v181, v179, v179 quad_perm:[2,3,0,1] row_mask:0xf bank_mask:0xf
	s_mov_b64 exec, vcc
	global_atomic_add_f32 v174, v181, s[18:19] offset:128
	s_mov_b64 exec, s[8:9]
	v_add_u32_e32 v173, 0x8000, v173
	ds_write_b128 v169, v[76:79]
	ds_write_b128 v170, v[72:75]
	s_waitcnt lgkmcnt(0)
	ds_read_b128 v[128:131], v171
	ds_read_b128 v[132:135], v172
	s_waitcnt vmcnt(0)
	s_waitcnt lgkmcnt(0)
	v_pk_add_f32 v[128:129], v[128:129], v[212:213]
	v_pk_add_f32 v[130:131], v[130:131], v[214:215]
	v_pk_add_f32 v[132:133], v[132:133], v[216:217]
	v_pk_add_f32 v[134:135], v[134:135], v[218:219]
	v_pk_mul_f32 v[176:177], v[128:129], v[128:129]
	v_pk_fma_f32 v[176:177], v[130:131], v[130:131], v[176:177]
	v_pk_fma_f32 v[176:177], v[132:133], v[132:133], v[176:177]
	v_pk_fma_f32 v[176:177], v[134:135], v[134:135], v[176:177]
	v_cvt_pk_bf16_f32 v156, v128, v129
	v_cvt_pk_bf16_f32 v157, v130, v131
	v_cvt_pk_bf16_f32 v158, v132, v133
	v_cvt_pk_bf16_f32 v159, v134, v135
	global_store_dwordx4 v173, v[156:159], s[16:17]
	v_add_f32_e32 v178, v176, v177
	s_nop 1
	v_add_f32_dpp v179, v178, v178 quad_perm:[1,0,3,2] row_mask:0xf bank_mask:0xf
	s_nop 1
	v_add_f32_dpp v181, v179, v179 quad_perm:[2,3,0,1] row_mask:0xf bank_mask:0xf
	s_mov_b64 exec, vcc
	global_atomic_add_f32 v174, v181, s[18:19] offset:192
	s_mov_b64 exec, s[8:9]
.Lqepi_end_6:
.LBB0_1455:
	s_or_b64 exec, exec, s[8:9]
	s_andn2_b64 vcc, exec, s[6:7]
	s_mov_b64 s[6:7], -1
	s_cbranch_vccnz .LBB0_1428
	s_andn2_b64 vcc, exec, s[10:11]
	s_cbranch_vccnz .LBB0_1427
	s_barrier
	s_branch .LBB0_1427

.LBB0_1501:
	s_and_b64 vcc, exec, s[4:5]
	s_cbranch_vccnz .LBB0_1541
	s_waitcnt lgkmcnt(0)
	v_ashrrev_i32_e32 v1, 31, v8
	v_lshrrev_b32_e32 v1, 26, v1
	v_add_u32_e32 v1, v8, v1
	v_ashrrev_i32_e32 v9, 6, v1
	v_bfe_i32 v1, v8, 27, 1
	v_lshlrev_b32_e32 v0, 4, v8
	v_lshrrev_b32_e32 v1, 22, v1
	v_add_u32_e32 v1, v0, v1
	v_and_b32_e32 v1, 0xfffffc00, v1
	v_sub_u32_e32 v1, v0, v1
	v_lshrrev_b32_e32 v2, 4, v1
	v_bitop3_b32 v2, v2, v1, 32 bitop3:0x6c
	v_ashrrev_i32_e32 v1, 31, v1
	v_lshrrev_b32_e32 v1, 26, v1
	v_lshlrev_b32_e32 v3, 3, v9
	v_add_u32_e32 v1, v2, v1
	v_and_b32_e32 v3, 0xfffff0, v3
	v_ashrrev_i32_e32 v11, 6, v1
	v_add_u32_e32 v1, v11, v3
	v_lshlrev_b32_e32 v3, 5, v9
	v_and_b32_e32 v10, 32, v3
	v_mul_i32_i24_e32 v3, 64, v11
	v_sub_u32_e32 v2, v2, v3
	v_mov_b32_e32 v3, 1
	s_movk_i32 s9, 0xb00
	v_ashrrev_i16_sdwa v2, v3, sext(v2) dst_sel:DWORD dst_unused:UNUSED_PAD src0_sel:DWORD src1_sel:BYTE_0
	v_mul_lo_u32 v1, v1, s9
	v_bfe_i32 v12, v2, 0, 16
	v_or_b32_e32 v1, v1, v10
	v_add_u32_e32 v0, 0x2000, v0
	v_add_lshl_u32 v128, v1, v12, 1
	v_ashrrev_i32_e32 v1, 31, v0
	v_lshrrev_b32_e32 v1, 22, v1
	s_load_dwordx2 s[6:7], s[6:7], 0x120
	v_add_u32_e32 v1, v0, v1
	v_ashrrev_i32_e32 v13, 10, v1
	v_mul_i32_i24_e32 v1, 0x400, v13
	v_sub_u32_e32 v0, v0, v1
	v_lshrrev_b32_e32 v1, 4, v0
	s_waitcnt lgkmcnt(0)
	s_add_u32 s34, s6, 0x17c4b200
	v_bitop3_b32 v0, v1, v0, 32 bitop3:0x6c
	s_addc_u32 s35, s7, 0
	v_ashrrev_i32_e32 v2, 31, v0
	s_add_u32 s36, s6, 0x1300000
	v_lshrrev_b32_e32 v2, 26, v2
	s_addc_u32 s37, s7, 0
	s_ashr_i32 s18, s8, 6
	v_add_u32_e32 v2, v0, v2
	v_lshlrev_b32_e32 v1, 3, v13
	v_ashrrev_i32_e32 v14, 6, v2
	v_and_b32_e32 v2, 0xc0, v2
	s_ashr_i32 s19, s8, 8
	s_lshl_b32 s38, s18, 10
	s_mul_i32 s11, s54, 0x160000
	v_and_b32_e32 v1, 0xfffff0, v1
	v_sub_u32_e32 v0, v0, v2
	s_mul_hi_i32 s10, s54, 0x160000
	s_add_u32 s26, s36, s11
	v_add_u32_e32 v1, v14, v1
	v_lshlrev_b32_e32 v4, 5, v13
	v_ashrrev_i16_sdwa v0, v3, sext(v0) dst_sel:DWORD dst_unused:UNUSED_PAD src0_sel:DWORD src1_sel:BYTE_0
	s_addc_u32 s27, s37, s10
	s_add_i32 s39, s38, 0
	s_waitcnt vmcnt(0)
	v_and_b32_e32 v15, 32, v4
	v_bfe_i32 v16, v0, 0, 16
	v_mul_lo_u32 v0, v1, s9
	s_add_i32 m0, s39, 0x10000
	v_or_b32_e32 v0, v0, v15
	global_load_lds_dwordx4 v128, s[26:27]
	s_add_i32 m0, s39, 0x12000
	v_add_lshl_u32 v130, v0, v16, 1
	s_add_u32 s10, s26, 0xb0000
	global_load_lds_dwordx4 v130, s[26:27]
	s_addc_u32 s11, s27, 0
	s_add_i32 m0, s39, 0x14000
	s_mul_i32 s13, s55, 0x160000
	global_load_lds_dwordx4 v128, s[10:11]
	s_add_i32 m0, s39, 0x16000
	s_mul_hi_i32 s12, s55, 0x160000
	s_add_u32 s24, s34, s13
	s_addc_u32 s25, s35, s12
	s_add_i32 s40, s39, 0x2000
	global_load_lds_dwordx4 v130, s[10:11]
	s_mov_b32 m0, s39
	s_add_u32 s10, s24, 0xb0000
	global_load_lds_dwordx4 v128, s[24:25]
	s_mov_b32 m0, s40
	s_addc_u32 s11, s25, 0
	s_add_i32 s41, s39, 0x4000
	global_load_lds_dwordx4 v130, s[24:25]
	s_mov_b32 m0, s41
	s_add_i32 s42, s39, 0x6000
	global_load_lds_dwordx4 v128, s[10:11]
	s_mov_b32 m0, s42
	v_mov_b32_e32 v129, 0
	global_load_lds_dwordx4 v130, s[10:11]
	v_mov_b32_e32 v131, v129
	s_cmp_eq_u32 s19, 1
	s_mov_b32 s43, 0
	s_mov_b32 s101, 0xf
	s_mov_b32 s100, 0xf
	v_lshl_add_u64 v[6:7], s[26:27], 0, v[128:129]
	v_lshl_add_u64 v[4:5], s[26:27], 0, v[130:131]
	v_lshl_add_u64 v[0:1], s[24:25], 0, v[128:129]
	s_cselect_b64 s[10:11], -1, 0
	s_cmp_lg_u32 s19, 1
	v_lshl_add_u64 v[2:3], s[24:25], 0, v[130:131]
	s_cbranch_scc1 .LBB0_1504
	s_barrier

.LBB0_1506:
	s_mov_b32 s101, s100
	s_andn2_b64 vcc, exec, s[6:7]
	s_mov_b32 s54, s52
	s_mov_b32 s55, s53
	s_mov_b64 s[26:27], s[22:23]
	s_mov_b64 s[24:25], s[8:9]
	s_cbranch_vccz .LBB0_1540
.LBB0_1507:
	s_add_i32 s43, s43, 1
	s_mul_i32 s6, s43, s47
	s_mul_hi_u32 s7, s43, s46
	s_add_i32 s7, s7, s6
	s_mul_i32 s6, s43, s46
	s_add_u32 s6, s6, s94
	s_addc_u32 s7, s7, s95
	s_mov_b32 s100, 0xf
	s_cmp_eq_u32 s46, 0x100
	s_cbranch_scc0 .Lqs_done_8
	s_cmp_eq_u32 s43, 4
	s_cbranch_scc0 .Lqs_done_8
	s_mov_b32 s7, 0
	s_mov_b32 s6, 0x7fffffff
	s_cmp_lt_u32 s94, 16
	s_cbranch_scc0 .Lqs_done_8
	s_lshr_b32 s6, s94, 2
	s_add_i32 s6, s6, 0x400
	s_and_b32 s98, s94, 3
	s_lshl_b32 s100, 1, s98
	s_lshl_b32 s98, s98, 4
	s_or_b32 s100, s100, s98
	s_or_b32 s100, s100, 0x40
.Lqs_done_8:
	v_cmp_gt_i64_e32 vcc, s[6:7], v[138:139]
	v_cmp_lt_i64_e64 s[8:9], s[6:7], v[136:137]
	s_cbranch_vccnz .LBB0_1513
	s_ashr_i32 s7, s6, 31
	s_lshr_b32 s7, s7, 29
	s_add_i32 s22, s6, s7
	s_and_b32 s7, s22, -8
	s_sub_i32 s23, s6, s7
	s_cmp_gt_i32 s23, 3
	s_mov_b64 s[6:7], -1
	s_cbranch_scc0 .LBB0_1510
	s_lshl_b32 s6, s23, 7
	s_or_b32 s28, s6, 4
	s_mov_b64 s[6:7], 0

.LBB0_1518:
	ds_read_b128 v[140:143], v182
	ds_read_b128 v[144:147], v182 offset:1024
	ds_read_b128 v[148:151], v182 offset:2048
	ds_read_b128 v[152:155], v182 offset:3072
	ds_read_b128 v[156:159], v183
	ds_read_b128 v[160:163], v183 offset:1024
	ds_read_b128 v[164:167], v183 offset:2048
	ds_read_b128 v[168:171], v183 offset:3072
	s_add_u32 s26, s24, 0x100
	s_addc_u32 s27, s25, 0
	s_cmp_eq_u32 s58, 40
	s_cselect_b32 s31, s9, s27
	s_cselect_b32 s30, s8, s26
	s_cselect_b32 s29, s23, s57
	s_cselect_b32 s28, s22, s56
	v_lshl_add_u64 v[210:211], s[24:25], 0, v[132:133]
	s_add_i32 m0, s39, 0xc000
	ds_read_b128 v[172:175], v184
	ds_read_b128 v[176:179], v184 offset:1024
	ds_read_b128 v[186:189], v184 offset:2048
	ds_read_b128 v[190:193], v184 offset:3072
	ds_read_b128 v[194:197], v184 offset:4096
	ds_read_b128 v[198:201], v184 offset:5120
	ds_read_b128 v[202:205], v184 offset:6144
	ds_read_b128 v[206:209], v184 offset:7168
	global_load_lds_dwordx4 v[210:211], off
	v_lshl_add_u64 v[210:211], s[24:25], 0, v[134:135]
	s_add_i32 m0, s39, 0xe000
	s_nop 0
	global_load_lds_dwordx4 v[210:211], off
	s_waitcnt vmcnt(8)
	s_waitcnt lgkmcnt(0)
	s_barrier
	s_setprio 1
	s_waitcnt lgkmcnt(0)
	s_bitcmp1_b32 s101, 0
	s_cbranch_scc0 .Lmm_8_0
	v_mfma_f32_16x16x32_bf16 v[124:127], v[140:143], v[172:175], v[124:127]
	v_mfma_f32_16x16x32_bf16 v[120:123], v[148:151], v[172:175], v[120:123]
	v_mfma_f32_16x16x32_bf16 v[108:111], v[140:143], v[186:189], v[108:111]
	v_mfma_f32_16x16x32_bf16 v[104:107], v[148:151], v[186:189], v[104:107]
	v_mfma_f32_16x16x32_bf16 v[92:95], v[140:143], v[194:197], v[92:95]
	v_mfma_f32_16x16x32_bf16 v[88:91], v[148:151], v[194:197], v[88:91]
	v_mfma_f32_16x16x32_bf16 v[76:79], v[140:143], v[202:205], v[76:79]
	v_mfma_f32_16x16x32_bf16 v[72:75], v[148:151], v[202:205], v[72:75]
	v_mfma_f32_16x16x32_bf16 v[124:127], v[144:147], v[176:179], v[124:127]
	v_mfma_f32_16x16x32_bf16 v[120:123], v[152:155], v[176:179], v[120:123]
	v_mfma_f32_16x16x32_bf16 v[108:111], v[144:147], v[190:193], v[108:111]
	v_mfma_f32_16x16x32_bf16 v[104:107], v[152:155], v[190:193], v[104:107]
	v_mfma_f32_16x16x32_bf16 v[92:95], v[144:147], v[198:201], v[92:95]
	v_mfma_f32_16x16x32_bf16 v[88:91], v[152:155], v[198:201], v[88:91]
	v_mfma_f32_16x16x32_bf16 v[76:79], v[144:147], v[206:209], v[76:79]
	v_mfma_f32_16x16x32_bf16 v[72:75], v[152:155], v[206:209], v[72:75]
.Lmm_8_0:
	s_setprio 0
	s_setprio 1
	s_bitcmp1_b32 s101, 1
	s_cbranch_scc0 .Lmm_8_1
	v_mfma_f32_16x16x32_bf16 v[116:119], v[156:159], v[172:175], v[116:119]
	v_mfma_f32_16x16x32_bf16 v[112:115], v[164:167], v[172:175], v[112:115]
	v_mfma_f32_16x16x32_bf16 v[100:103], v[156:159], v[186:189], v[100:103]
	v_mfma_f32_16x16x32_bf16 v[96:99], v[164:167], v[186:189], v[96:99]
	v_mfma_f32_16x16x32_bf16 v[84:87], v[156:159], v[194:197], v[84:87]
	v_mfma_f32_16x16x32_bf16 v[80:83], v[164:167], v[194:197], v[80:83]
	v_mfma_f32_16x16x32_bf16 v[68:71], v[156:159], v[202:205], v[68:71]
	v_mfma_f32_16x16x32_bf16 v[64:67], v[164:167], v[202:205], v[64:67]
	v_mfma_f32_16x16x32_bf16 v[116:119], v[160:163], v[176:179], v[116:119]
	v_mfma_f32_16x16x32_bf16 v[112:115], v[168:171], v[176:179], v[112:115]
	v_mfma_f32_16x16x32_bf16 v[100:103], v[160:163], v[190:193], v[100:103]
	v_mfma_f32_16x16x32_bf16 v[96:99], v[168:171], v[190:193], v[96:99]
	v_mfma_f32_16x16x32_bf16 v[84:87], v[160:163], v[198:201], v[84:87]
	v_mfma_f32_16x16x32_bf16 v[80:83], v[168:171], v[198:201], v[80:83]
	v_mfma_f32_16x16x32_bf16 v[68:71], v[160:163], v[206:209], v[68:71]
	v_mfma_f32_16x16x32_bf16 v[64:67], v[168:171], v[206:209], v[64:67]
.Lmm_8_1:
	s_setprio 0
	s_barrier
	s_add_i32 s24, s50, s38
	v_lshl_add_u64 v[210:211], s[28:29], 0, v[128:129]
	s_mov_b32 m0, s24
	ds_read_b128 v[172:175], v184 offset:16384
	ds_read_b128 v[176:179], v184 offset:17408
	ds_read_b128 v[186:189], v184 offset:18432
	ds_read_b128 v[190:193], v184 offset:19456
	ds_read_b128 v[194:197], v184 offset:20480
	ds_read_b128 v[198:201], v184 offset:21504
	ds_read_b128 v[202:205], v184 offset:22528
	ds_read_b128 v[206:209], v184 offset:23552
	global_load_lds_dwordx4 v[210:211], off
	s_add_i32 m0, s24, 0x2000
	s_add_u32 s24, s28, 0xb0000
	v_lshl_add_u64 v[212:213], s[28:29], 0, v[130:131]
	s_addc_u32 s25, s29, 0
	s_add_i32 s59, s51, s38
	global_load_lds_dwordx4 v[212:213], off
	v_lshl_add_u64 v[214:215], s[24:25], 0, v[128:129]
	s_mov_b32 m0, s59
	v_lshl_add_u64 v[216:217], s[30:31], 0, v[130:131]
	global_load_lds_dwordx4 v[214:215], off
	v_lshl_add_u64 v[214:215], s[24:25], 0, v[130:131]
	s_add_i32 m0, s59, 0x2000
	s_nop 0
	global_load_lds_dwordx4 v[214:215], off
	v_lshl_add_u64 v[214:215], s[30:31], 0, v[128:129]
	s_mov_b32 m0, s39
	s_nop 0
	global_load_lds_dwordx4 v[214:215], off
	s_mov_b32 m0, s40
	s_nop 0
	global_load_lds_dwordx4 v[216:217], off
	s_waitcnt vmcnt(8)
	s_waitcnt lgkmcnt(0)
	s_barrier
	s_setprio 1
	s_waitcnt lgkmcnt(0)
	s_bitcmp1_b32 s101, 2
	s_cbranch_scc0 .Lmm_8_2
	v_mfma_f32_16x16x32_bf16 v[60:63], v[140:143], v[172:175], v[60:63]
	v_mfma_f32_16x16x32_bf16 v[56:59], v[148:151], v[172:175], v[56:59]
	v_mfma_f32_16x16x32_bf16 v[44:47], v[140:143], v[186:189], v[44:47]
	v_mfma_f32_16x16x32_bf16 v[40:43], v[148:151], v[186:189], v[40:43]
	v_mfma_f32_16x16x32_bf16 v[28:31], v[140:143], v[194:197], v[28:31]
	v_mfma_f32_16x16x32_bf16 v[24:27], v[148:151], v[194:197], v[24:27]
	v_mfma_f32_16x16x32_bf16 v[12:15], v[140:143], v[202:205], v[12:15]
	v_mfma_f32_16x16x32_bf16 v[8:11], v[148:151], v[202:205], v[8:11]
	v_mfma_f32_16x16x32_bf16 v[60:63], v[144:147], v[176:179], v[60:63]
	v_mfma_f32_16x16x32_bf16 v[56:59], v[152:155], v[176:179], v[56:59]
	v_mfma_f32_16x16x32_bf16 v[44:47], v[144:147], v[190:193], v[44:47]
	v_mfma_f32_16x16x32_bf16 v[40:43], v[152:155], v[190:193], v[40:43]
	v_mfma_f32_16x16x32_bf16 v[28:31], v[144:147], v[198:201], v[28:31]
	v_mfma_f32_16x16x32_bf16 v[24:27], v[152:155], v[198:201], v[24:27]
	v_mfma_f32_16x16x32_bf16 v[12:15], v[144:147], v[206:209], v[12:15]
	v_mfma_f32_16x16x32_bf16 v[8:11], v[152:155], v[206:209], v[8:11]
.Lmm_8_2:
	s_setprio 0
	s_setprio 1
	s_bitcmp1_b32 s101, 3
	s_cbranch_scc0 .Lmm_8_3
	v_mfma_f32_16x16x32_bf16 v[52:55], v[156:159], v[172:175], v[52:55]
	v_mfma_f32_16x16x32_bf16 v[48:51], v[164:167], v[172:175], v[48:51]
	v_mfma_f32_16x16x32_bf16 v[36:39], v[156:159], v[186:189], v[36:39]
	v_mfma_f32_16x16x32_bf16 v[32:35], v[164:167], v[186:189], v[32:35]
	v_mfma_f32_16x16x32_bf16 v[20:23], v[156:159], v[194:197], v[20:23]
	v_mfma_f32_16x16x32_bf16 v[16:19], v[164:167], v[194:197], v[16:19]
	v_mfma_f32_16x16x32_bf16 v[4:7], v[156:159], v[202:205], v[4:7]
	v_mfma_f32_16x16x32_bf16 v[0:3], v[164:167], v[202:205], v[0:3]
	v_mfma_f32_16x16x32_bf16 v[52:55], v[160:163], v[176:179], v[52:55]
	v_mfma_f32_16x16x32_bf16 v[48:51], v[168:171], v[176:179], v[48:51]
	v_mfma_f32_16x16x32_bf16 v[36:39], v[160:163], v[190:193], v[36:39]
	v_mfma_f32_16x16x32_bf16 v[32:35], v[168:171], v[190:193], v[32:35]
	v_mfma_f32_16x16x32_bf16 v[20:23], v[160:163], v[198:201], v[20:23]
	v_mfma_f32_16x16x32_bf16 v[16:19], v[168:171], v[198:201], v[16:19]
	v_mfma_f32_16x16x32_bf16 v[4:7], v[160:163], v[206:209], v[4:7]
	v_mfma_f32_16x16x32_bf16 v[0:3], v[168:171], v[206:209], v[0:3]
.Lmm_8_3:
	s_setprio 0
	s_barrier
	s_add_i32 s59, 0, 0x18000
	s_add_i32 s63, 0, 0x1c000
	v_add_u32_e32 v152, s59, v181
	v_add_u32_e32 v168, s63, v181
	ds_read_b128 v[140:143], v152
	ds_read_b128 v[144:147], v152 offset:1024
	ds_read_b128 v[148:151], v152 offset:2048
	ds_read_b128 v[152:155], v152 offset:3072
	ds_read_b128 v[156:159], v168
	ds_read_b128 v[160:163], v168 offset:1024
	ds_read_b128 v[164:167], v168 offset:2048
	ds_read_b128 v[168:171], v168 offset:3072
	s_add_u32 s24, s30, 0xb0000
	s_addc_u32 s25, s31, 0
	s_mov_b32 m0, s41
	v_lshl_add_u64 v[218:219], s[24:25], 0, v[128:129]
	ds_read_b128 v[172:175], v184 offset:32768
	ds_read_b128 v[176:179], v184 offset:33792
	ds_read_b128 v[186:189], v184 offset:34816
	ds_read_b128 v[190:193], v184 offset:35840
	ds_read_b128 v[194:197], v184 offset:36864
	ds_read_b128 v[198:201], v184 offset:37888
	ds_read_b128 v[202:205], v184 offset:38912
	ds_read_b128 v[206:209], v184 offset:39936
	global_load_lds_dwordx4 v[218:219], off
	v_lshl_add_u64 v[218:219], s[24:25], 0, v[130:131]
	s_mov_b32 m0, s42
	s_nop 0
	global_load_lds_dwordx4 v[218:219], off
	s_waitcnt vmcnt(8)
	s_waitcnt lgkmcnt(0)
	s_barrier
	s_setprio 1
	s_waitcnt lgkmcnt(0)
	s_bitcmp1_b32 s101, 0
	s_cbranch_scc0 .Lmm_8_4
	v_mfma_f32_16x16x32_bf16 v[124:127], v[140:143], v[172:175], v[124:127]
	v_mfma_f32_16x16x32_bf16 v[120:123], v[148:151], v[172:175], v[120:123]
	v_mfma_f32_16x16x32_bf16 v[108:111], v[140:143], v[186:189], v[108:111]
	v_mfma_f32_16x16x32_bf16 v[104:107], v[148:151], v[186:189], v[104:107]
	v_mfma_f32_16x16x32_bf16 v[92:95], v[140:143], v[194:197], v[92:95]
	v_mfma_f32_16x16x32_bf16 v[88:91], v[148:151], v[194:197], v[88:91]
	v_mfma_f32_16x16x32_bf16 v[76:79], v[140:143], v[202:205], v[76:79]
	v_mfma_f32_16x16x32_bf16 v[72:75], v[148:151], v[202:205], v[72:75]
	v_mfma_f32_16x16x32_bf16 v[124:127], v[144:147], v[176:179], v[124:127]
	v_mfma_f32_16x16x32_bf16 v[120:123], v[152:155], v[176:179], v[120:123]
	v_mfma_f32_16x16x32_bf16 v[108:111], v[144:147], v[190:193], v[108:111]
	v_mfma_f32_16x16x32_bf16 v[104:107], v[152:155], v[190:193], v[104:107]
	v_mfma_f32_16x16x32_bf16 v[92:95], v[144:147], v[198:201], v[92:95]
	v_mfma_f32_16x16x32_bf16 v[88:91], v[152:155], v[198:201], v[88:91]
	v_mfma_f32_16x16x32_bf16 v[76:79], v[144:147], v[206:209], v[76:79]
	v_mfma_f32_16x16x32_bf16 v[72:75], v[152:155], v[206:209], v[72:75]

.Lmm_8_5:
	s_setprio 0
	s_barrier
	s_add_i32 s24, s59, s38
	v_lshl_add_u64 v[210:211], v[210:211], 0, s[18:19]
	s_mov_b32 m0, s24
	ds_read_b128 v[172:175], v184 offset:49152
	ds_read_b128 v[176:179], v184 offset:50176
	ds_read_b128 v[186:189], v184 offset:51200
	ds_read_b128 v[190:193], v184 offset:52224
	ds_read_b128 v[194:197], v184 offset:53248
	ds_read_b128 v[198:201], v184 offset:54272
	ds_read_b128 v[202:205], v184 offset:55296
	ds_read_b128 v[206:209], v184 offset:56320
	global_load_lds_dwordx4 v[210:211], off
	s_add_i32 m0, s24, 0x2000
	s_add_u32 s24, s28, 0xb0080
	v_lshl_add_u64 v[210:211], v[212:213], 0, s[18:19]
	s_addc_u32 s25, s29, 0
	s_add_i32 s28, s63, s38
	global_load_lds_dwordx4 v[210:211], off
	v_lshl_add_u64 v[210:211], s[24:25], 0, v[128:129]
	s_mov_b32 m0, s28
	s_nop 0
	global_load_lds_dwordx4 v[210:211], off
	v_lshl_add_u64 v[210:211], s[24:25], 0, v[130:131]
	s_add_i32 m0, s28, 0x2000
	s_nop 0
	global_load_lds_dwordx4 v[210:211], off
	v_lshl_add_u64 v[210:211], v[214:215], 0, s[18:19]
	s_mov_b32 m0, s48
	s_nop 0
	global_load_lds_dwordx4 v[210:211], off
	v_lshl_add_u64 v[210:211], v[216:217], 0, s[18:19]
	s_mov_b32 m0, s49
	s_nop 0
	global_load_lds_dwordx4 v[210:211], off
	s_waitcnt vmcnt(8)
	s_waitcnt lgkmcnt(0)
	s_barrier
	s_setprio 1
	s_waitcnt lgkmcnt(0)
	s_bitcmp1_b32 s101, 2
	s_cbranch_scc0 .Lmm_8_6
	v_mfma_f32_16x16x32_bf16 v[60:63], v[140:143], v[172:175], v[60:63]
	v_mfma_f32_16x16x32_bf16 v[56:59], v[148:151], v[172:175], v[56:59]
	v_mfma_f32_16x16x32_bf16 v[44:47], v[140:143], v[186:189], v[44:47]
	v_mfma_f32_16x16x32_bf16 v[40:43], v[148:151], v[186:189], v[40:43]
	v_mfma_f32_16x16x32_bf16 v[28:31], v[140:143], v[194:197], v[28:31]
	v_mfma_f32_16x16x32_bf16 v[24:27], v[148:151], v[194:197], v[24:27]
	v_mfma_f32_16x16x32_bf16 v[12:15], v[140:143], v[202:205], v[12:15]
	v_mfma_f32_16x16x32_bf16 v[8:11], v[148:151], v[202:205], v[8:11]
	v_mfma_f32_16x16x32_bf16 v[60:63], v[144:147], v[176:179], v[60:63]
	v_mfma_f32_16x16x32_bf16 v[56:59], v[152:155], v[176:179], v[56:59]
	v_mfma_f32_16x16x32_bf16 v[44:47], v[144:147], v[190:193], v[44:47]
	v_mfma_f32_16x16x32_bf16 v[40:43], v[152:155], v[190:193], v[40:43]
	v_mfma_f32_16x16x32_bf16 v[28:31], v[144:147], v[198:201], v[28:31]
	v_mfma_f32_16x16x32_bf16 v[24:27], v[152:155], v[198:201], v[24:27]
	v_mfma_f32_16x16x32_bf16 v[12:15], v[144:147], v[206:209], v[12:15]
	v_mfma_f32_16x16x32_bf16 v[8:11], v[152:155], v[206:209], v[8:11]

.Lmm_8_7:
	s_setprio 0
	s_barrier
	s_add_i32 s58, s58, 2
	s_add_u32 s56, s56, 0x100
	s_addc_u32 s57, s57, 0
	s_cmp_gt_u32 s58, 41
	s_mov_b64 s[24:25], s[26:27]
	s_cbranch_scc0 .LBB0_1518
	s_and_b64 vcc, exec, s[20:21]
	s_cbranch_vccz .LBB0_1521
	s_barrier
.LBB0_1521:
	s_bitcmp1_b32 s101, 6
	s_cbranch_scc1 .Lqepi_8
	v_and_b32_e32 v146, 63, v180
	v_and_b32_e32 v147, 15, v180
	v_bfe_u32 v148, v180, 4, 2
	v_lshrrev_b32_e32 v149, 6, v180
	v_lshlrev_b32_e32 v149, 12, v149
	v_add_u32_e32 v149, 0x20000, v149
	v_and_b32_e32 v150, 7, v147
	v_xor_b32_e32 v150, v148, v150
	v_lshlrev_b32_e32 v150, 4, v150
	v_lshl_add_u32 v150, v147, 8, v150
	v_add_u32_e32 v140, v149, v150
	v_xor_b32_e32 v141, 64, v140
	v_lshrrev_b32_e32 v151, 2, v146
	v_and_b32_e32 v152, 3, v146
	v_and_b32_e32 v153, 7, v151
	v_lshlrev_b32_e32 v154, 1, v152
	v_xor_b32_e32 v154, v154, v153
	v_lshlrev_b32_e32 v154, 4, v154
	v_lshl_add_u32 v154, v151, 8, v154
	v_add_u32_e32 v142, v149, v154
	v_xor_b32_e32 v143, 16, v142
	s_lshl_b32 s24, s55, 8
	s_add_i32 s24, s24, s44
	v_add_u32_e32 v155, s24, v151
	v_lshlrev_b32_e32 v145, 2, v155
	v_lshlrev_b32_e32 v155, 11, v155
	s_lshl_b32 s24, s54, 8
	s_add_i32 s24, s24, s45
	v_lshl_add_u32 v156, v152, 3, s24
	v_lshl_add_u32 v144, v156, 1, v155
	v_cmp_eq_u32_e32 vcc, 0, v152
	s_mov_b64 s[98:99], s[12:13]
	global_load_dwordx4 v[188:191], v144, s[98:99]
	global_load_dwordx4 v[192:195], v144, s[98:99] offset:256
	s_add_u32 s98, s98, 0x8000
	s_addc_u32 s99, s99, 0
	global_load_dwordx4 v[196:199], v144, s[98:99]
	global_load_dwordx4 v[200:203], v144, s[98:99] offset:256
	s_add_u32 s98, s98, 0x8000
	s_addc_u32 s99, s99, 0
	global_load_dwordx4 v[204:207], v144, s[98:99]
	global_load_dwordx4 v[208:211], v144, s[98:99] offset:256
	s_add_u32 s98, s98, 0x8000
	s_addc_u32 s99, s99, 0
	global_load_dwordx4 v[212:215], v144, s[98:99]
	global_load_dwordx4 v[216:219], v144, s[98:99] offset:256
	s_add_u32 s98, s98, 0x28000
	s_addc_u32 s99, s99, 0
	global_load_dwordx4 v[220:223], v144, s[98:99]
	global_load_dwordx4 v[224:227], v144, s[98:99] offset:256
	s_add_u32 s98, s98, 0x8000
	s_addc_u32 s99, s99, 0
	global_load_dwordx4 v[228:231], v144, s[98:99]
	global_load_dwordx4 v[232:235], v144, s[98:99] offset:256
	s_add_u32 s98, s98, 0x8000
	s_addc_u32 s99, s99, 0
	global_load_dwordx4 v[236:239], v144, s[98:99]
	global_load_dwordx4 v[240:243], v144, s[98:99] offset:256
	s_add_u32 s98, s98, 0x8000
	s_addc_u32 s99, s99, 0
	global_load_dwordx4 v[244:247], v144, s[98:99]
	global_load_dwordx4 v[248:251], v144, s[98:99] offset:256
	s_mov_b64 s[24:25], exec
	s_mov_b64 s[98:99], s[12:13]
	ds_write_b128 v140, v[124:127]
	ds_write_b128 v141, v[120:123]
	ds_write_b128 v140, v[116:119] offset:128
	ds_write_b128 v141, v[112:115] offset:128
	s_waitcnt lgkmcnt(0)
	ds_read_b128 v[146:149], v142
	ds_read_b128 v[150:153], v143
	ds_read_b128 v[154:157], v142 offset:128
	ds_read_b128 v[158:161], v143 offset:128
	s_waitcnt lgkmcnt(0)
	ds_write_b128 v140, v[108:111]
	ds_write_b128 v141, v[104:107]
	ds_write_b128 v140, v[100:103] offset:128
	ds_write_b128 v141, v[96:99] offset:128
	s_waitcnt vmcnt(14)
	v_lshlrev_b32_e32 v162, 16, v188
	v_and_b32_e32 v163, 0xffff0000, v188
	v_lshlrev_b32_e32 v164, 16, v189
	v_and_b32_e32 v165, 0xffff0000, v189
	v_lshlrev_b32_e32 v166, 16, v190
	v_and_b32_e32 v167, 0xffff0000, v190
	v_lshlrev_b32_e32 v168, 16, v191
	v_and_b32_e32 v169, 0xffff0000, v191
	v_pk_add_f32 v[146:147], v[146:147], v[162:163]
	v_pk_add_f32 v[148:149], v[148:149], v[164:165]
	v_pk_add_f32 v[150:151], v[150:151], v[166:167]
	v_pk_add_f32 v[152:153], v[152:153], v[168:169]
	v_pk_mul_f32 v[170:171], v[146:147], v[146:147]
	v_pk_fma_f32 v[170:171], v[148:149], v[148:149], v[170:171]
	v_pk_fma_f32 v[170:171], v[150:151], v[150:151], v[170:171]
	v_pk_fma_f32 v[170:171], v[152:153], v[152:153], v[170:171]
	v_cvt_pk_bf16_f32 v172, v146, v147
	v_cvt_pk_bf16_f32 v173, v148, v149
	v_cvt_pk_bf16_f32 v174, v150, v151
	v_cvt_pk_bf16_f32 v175, v152, v153
	global_store_dwordx4 v144, v[172:175], s[98:99]
	v_lshlrev_b32_e32 v162, 16, v192
	v_and_b32_e32 v163, 0xffff0000, v192
	v_lshlrev_b32_e32 v164, 16, v193
	v_and_b32_e32 v165, 0xffff0000, v193
	v_lshlrev_b32_e32 v166, 16, v194
	v_and_b32_e32 v167, 0xffff0000, v194
	v_lshlrev_b32_e32 v168, 16, v195
	v_and_b32_e32 v169, 0xffff0000, v195
	v_pk_add_f32 v[154:155], v[154:155], v[162:163]
	v_pk_add_f32 v[156:157], v[156:157], v[164:165]
	v_pk_add_f32 v[158:159], v[158:159], v[166:167]
	v_pk_add_f32 v[160:161], v[160:161], v[168:169]
	v_pk_fma_f32 v[170:171], v[154:155], v[154:155], v[170:171]
	v_pk_fma_f32 v[170:171], v[156:157], v[156:157], v[170:171]
	v_pk_fma_f32 v[170:171], v[158:159], v[158:159], v[170:171]
	v_pk_fma_f32 v[170:171], v[160:161], v[160:161], v[170:171]
	v_cvt_pk_bf16_f32 v176, v154, v155
	v_cvt_pk_bf16_f32 v177, v156, v157
	v_cvt_pk_bf16_f32 v178, v158, v159
	v_cvt_pk_bf16_f32 v179, v160, v161
	global_store_dwordx4 v144, v[176:179], s[98:99] offset:256
	v_add_f32_e32 v162, v170, v171
	s_nop 1
	v_add_f32_dpp v163, v162, v162 quad_perm:[1,0,3,2] row_mask:0xf bank_mask:0xf
	s_nop 1
	v_add_f32_dpp v164, v163, v163 quad_perm:[2,3,0,1] row_mask:0xf bank_mask:0xf
	s_mov_b64 exec, vcc
	global_atomic_add_f32 v145, v164, s[14:15] offset:0
	s_mov_b64 exec, s[24:25]
	s_add_u32 s98, s98, 0x8000
	s_addc_u32 s99, s99, 0
	s_waitcnt lgkmcnt(0)
	ds_read_b128 v[146:149], v142
	ds_read_b128 v[150:153], v143
	ds_read_b128 v[154:157], v142 offset:128
	ds_read_b128 v[158:161], v143 offset:128
	s_waitcnt lgkmcnt(0)
	ds_write_b128 v140, v[92:95]
	ds_write_b128 v141, v[88:91]
	ds_write_b128 v140, v[84:87] offset:128
	ds_write_b128 v141, v[80:83] offset:128
	s_waitcnt vmcnt(15)
	v_lshlrev_b32_e32 v162, 16, v196
	v_and_b32_e32 v163, 0xffff0000, v196
	v_lshlrev_b32_e32 v164, 16, v197
	v_and_b32_e32 v165, 0xffff0000, v197
	v_lshlrev_b32_e32 v166, 16, v198
	v_and_b32_e32 v167, 0xffff0000, v198
	v_lshlrev_b32_e32 v168, 16, v199
	v_and_b32_e32 v169, 0xffff0000, v199
	v_pk_add_f32 v[146:147], v[146:147], v[162:163]
	v_pk_add_f32 v[148:149], v[148:149], v[164:165]
	v_pk_add_f32 v[150:151], v[150:151], v[166:167]
	v_pk_add_f32 v[152:153], v[152:153], v[168:169]
	v_pk_mul_f32 v[170:171], v[146:147], v[146:147]
	v_pk_fma_f32 v[170:171], v[148:149], v[148:149], v[170:171]
	v_pk_fma_f32 v[170:171], v[150:151], v[150:151], v[170:171]
	v_pk_fma_f32 v[170:171], v[152:153], v[152:153], v[170:171]
	v_cvt_pk_bf16_f32 v172, v146, v147
	v_cvt_pk_bf16_f32 v173, v148, v149
	v_cvt_pk_bf16_f32 v174, v150, v151
	v_cvt_pk_bf16_f32 v175, v152, v153
	global_store_dwordx4 v144, v[172:175], s[98:99]
	v_lshlrev_b32_e32 v162, 16, v200
	v_and_b32_e32 v163, 0xffff0000, v200
	v_lshlrev_b32_e32 v164, 16, v201
	v_and_b32_e32 v165, 0xffff0000, v201
	v_lshlrev_b32_e32 v166, 16, v202
	v_and_b32_e32 v167, 0xffff0000, v202
	v_lshlrev_b32_e32 v168, 16, v203
	v_and_b32_e32 v169, 0xffff0000, v203
	v_pk_add_f32 v[154:155], v[154:155], v[162:163]
	v_pk_add_f32 v[156:157], v[156:157], v[164:165]
	v_pk_add_f32 v[158:159], v[158:159], v[166:167]
	v_pk_add_f32 v[160:161], v[160:161], v[168:169]
	v_pk_fma_f32 v[170:171], v[154:155], v[154:155], v[170:171]
	v_pk_fma_f32 v[170:171], v[156:157], v[156:157], v[170:171]
	v_pk_fma_f32 v[170:171], v[158:159], v[158:159], v[170:171]
	v_pk_fma_f32 v[170:171], v[160:161], v[160:161], v[170:171]
	v_cvt_pk_bf16_f32 v176, v154, v155
	v_cvt_pk_bf16_f32 v177, v156, v157
	v_cvt_pk_bf16_f32 v178, v158, v159
	v_cvt_pk_bf16_f32 v179, v160, v161
	global_store_dwordx4 v144, v[176:179], s[98:99] offset:256
	v_add_f32_e32 v162, v170, v171
	s_nop 1
	v_add_f32_dpp v163, v162, v162 quad_perm:[1,0,3,2] row_mask:0xf bank_mask:0xf
	s_nop 1
	v_add_f32_dpp v164, v163, v163 quad_perm:[2,3,0,1] row_mask:0xf bank_mask:0xf
	s_mov_b64 exec, vcc
	global_atomic_add_f32 v145, v164, s[14:15] offset:64
	s_mov_b64 exec, s[24:25]
	s_add_u32 s98, s98, 0x8000
	s_addc_u32 s99, s99, 0
	s_waitcnt lgkmcnt(0)
	ds_read_b128 v[146:149], v142
	ds_read_b128 v[150:153], v143
	ds_read_b128 v[154:157], v142 offset:128
	ds_read_b128 v[158:161], v143 offset:128
	s_waitcnt lgkmcnt(0)
	ds_write_b128 v140, v[76:79]
	ds_write_b128 v141, v[72:75]
	ds_write_b128 v140, v[68:71] offset:128
	ds_write_b128 v141, v[64:67] offset:128
	s_waitcnt vmcnt(16)
	v_lshlrev_b32_e32 v162, 16, v204
	v_and_b32_e32 v163, 0xffff0000, v204
	v_lshlrev_b32_e32 v164, 16, v205
	v_and_b32_e32 v165, 0xffff0000, v205
	v_lshlrev_b32_e32 v166, 16, v206
	v_and_b32_e32 v167, 0xffff0000, v206
	v_lshlrev_b32_e32 v168, 16, v207
	v_and_b32_e32 v169, 0xffff0000, v207
	v_pk_add_f32 v[146:147], v[146:147], v[162:163]
	v_pk_add_f32 v[148:149], v[148:149], v[164:165]
	v_pk_add_f32 v[150:151], v[150:151], v[166:167]
	v_pk_add_f32 v[152:153], v[152:153], v[168:169]
	v_pk_mul_f32 v[170:171], v[146:147], v[146:147]
	v_pk_fma_f32 v[170:171], v[148:149], v[148:149], v[170:171]
	v_pk_fma_f32 v[170:171], v[150:151], v[150:151], v[170:171]
	v_pk_fma_f32 v[170:171], v[152:153], v[152:153], v[170:171]
	v_cvt_pk_bf16_f32 v172, v146, v147
	v_cvt_pk_bf16_f32 v173, v148, v149
	v_cvt_pk_bf16_f32 v174, v150, v151
	v_cvt_pk_bf16_f32 v175, v152, v153
	global_store_dwordx4 v144, v[172:175], s[98:99]
	v_lshlrev_b32_e32 v162, 16, v208
	v_and_b32_e32 v163, 0xffff0000, v208
	v_lshlrev_b32_e32 v164, 16, v209
	v_and_b32_e32 v165, 0xffff0000, v209
	v_lshlrev_b32_e32 v166, 16, v210
	v_and_b32_e32 v167, 0xffff0000, v210
	v_lshlrev_b32_e32 v168, 16, v211
	v_and_b32_e32 v169, 0xffff0000, v211
	v_pk_add_f32 v[154:155], v[154:155], v[162:163]
	v_pk_add_f32 v[156:157], v[156:157], v[164:165]
	v_pk_add_f32 v[158:159], v[158:159], v[166:167]
	v_pk_add_f32 v[160:161], v[160:161], v[168:169]
	v_pk_fma_f32 v[170:171], v[154:155], v[154:155], v[170:171]
	v_pk_fma_f32 v[170:171], v[156:157], v[156:157], v[170:171]
	v_pk_fma_f32 v[170:171], v[158:159], v[158:159], v[170:171]
	v_pk_fma_f32 v[170:171], v[160:161], v[160:161], v[170:171]
	v_cvt_pk_bf16_f32 v176, v154, v155
	v_cvt_pk_bf16_f32 v177, v156, v157
	v_cvt_pk_bf16_f32 v178, v158, v159
	v_cvt_pk_bf16_f32 v179, v160, v161
	global_store_dwordx4 v144, v[176:179], s[98:99] offset:256
	v_add_f32_e32 v162, v170, v171
	s_nop 1
	v_add_f32_dpp v163, v162, v162 quad_perm:[1,0,3,2] row_mask:0xf bank_mask:0xf
	s_nop 1
	v_add_f32_dpp v164, v163, v163 quad_perm:[2,3,0,1] row_mask:0xf bank_mask:0xf
	s_mov_b64 exec, vcc
	global_atomic_add_f32 v145, v164, s[14:15] offset:128
	s_mov_b64 exec, s[24:25]
	s_add_u32 s98, s98, 0x8000
	s_addc_u32 s99, s99, 0
	s_waitcnt lgkmcnt(0)
	ds_read_b128 v[146:149], v142
	ds_read_b128 v[150:153], v143
	ds_read_b128 v[154:157], v142 offset:128
	ds_read_b128 v[158:161], v143 offset:128
	s_waitcnt lgkmcnt(0)
	ds_write_b128 v140, v[60:63]
	ds_write_b128 v141, v[56:59]
	ds_write_b128 v140, v[52:55] offset:128
	ds_write_b128 v141, v[48:51] offset:128
	s_waitcnt vmcnt(17)
	v_lshlrev_b32_e32 v162, 16, v212
	v_and_b32_e32 v163, 0xffff0000, v212
	v_lshlrev_b32_e32 v164, 16, v213
	v_and_b32_e32 v165, 0xffff0000, v213
	v_lshlrev_b32_e32 v166, 16, v214
	v_and_b32_e32 v167, 0xffff0000, v214
	v_lshlrev_b32_e32 v168, 16, v215
	v_and_b32_e32 v169, 0xffff0000, v215
	v_pk_add_f32 v[146:147], v[146:147], v[162:163]
	v_pk_add_f32 v[148:149], v[148:149], v[164:165]
	v_pk_add_f32 v[150:151], v[150:151], v[166:167]
	v_pk_add_f32 v[152:153], v[152:153], v[168:169]
	v_pk_mul_f32 v[170:171], v[146:147], v[146:147]
	v_pk_fma_f32 v[170:171], v[148:149], v[148:149], v[170:171]
	v_pk_fma_f32 v[170:171], v[150:151], v[150:151], v[170:171]
	v_pk_fma_f32 v[170:171], v[152:153], v[152:153], v[170:171]
	v_cvt_pk_bf16_f32 v172, v146, v147
	v_cvt_pk_bf16_f32 v173, v148, v149
	v_cvt_pk_bf16_f32 v174, v150, v151
	v_cvt_pk_bf16_f32 v175, v152, v153
	global_store_dwordx4 v144, v[172:175], s[98:99]
	v_lshlrev_b32_e32 v162, 16, v216
	v_and_b32_e32 v163, 0xffff0000, v216
	v_lshlrev_b32_e32 v164, 16, v217
	v_and_b32_e32 v165, 0xffff0000, v217
	v_lshlrev_b32_e32 v166, 16, v218
	v_and_b32_e32 v167, 0xffff0000, v218
	v_lshlrev_b32_e32 v168, 16, v219
	v_and_b32_e32 v169, 0xffff0000, v219
	v_pk_add_f32 v[154:155], v[154:155], v[162:163]
	v_pk_add_f32 v[156:157], v[156:157], v[164:165]
	v_pk_add_f32 v[158:159], v[158:159], v[166:167]
	v_pk_add_f32 v[160:161], v[160:161], v[168:169]
	v_pk_fma_f32 v[170:171], v[154:155], v[154:155], v[170:171]
	v_pk_fma_f32 v[170:171], v[156:157], v[156:157], v[170:171]
	v_pk_fma_f32 v[170:171], v[158:159], v[158:159], v[170:171]
	v_pk_fma_f32 v[170:171], v[160:161], v[160:161], v[170:171]
	v_cvt_pk_bf16_f32 v176, v154, v155
	v_cvt_pk_bf16_f32 v177, v156, v157
	v_cvt_pk_bf16_f32 v178, v158, v159
	v_cvt_pk_bf16_f32 v179, v160, v161
	global_store_dwordx4 v144, v[176:179], s[98:99] offset:256
	v_add_f32_e32 v162, v170, v171
	s_nop 1
	v_add_f32_dpp v163, v162, v162 quad_perm:[1,0,3,2] row_mask:0xf bank_mask:0xf
	s_nop 1
	v_add_f32_dpp v164, v163, v163 quad_perm:[2,3,0,1] row_mask:0xf bank_mask:0xf
	s_mov_b64 exec, vcc
	global_atomic_add_f32 v145, v164, s[14:15] offset:192
	s_mov_b64 exec, s[24:25]
	s_add_u32 s98, s98, 0x28000
	s_addc_u32 s99, s99, 0
	s_waitcnt lgkmcnt(0)
	ds_read_b128 v[146:149], v142
	ds_read_b128 v[150:153], v143
	ds_read_b128 v[154:157], v142 offset:128
	ds_read_b128 v[158:161], v143 offset:128
	s_waitcnt lgkmcnt(0)
	ds_write_b128 v140, v[44:47]
	ds_write_b128 v141, v[40:43]
	ds_write_b128 v140, v[36:39] offset:128
	ds_write_b128 v141, v[32:35] offset:128
	s_waitcnt vmcnt(18)
	v_lshlrev_b32_e32 v162, 16, v220
	v_and_b32_e32 v163, 0xffff0000, v220
	v_lshlrev_b32_e32 v164, 16, v221
	v_and_b32_e32 v165, 0xffff0000, v221
	v_lshlrev_b32_e32 v166, 16, v222
	v_and_b32_e32 v167, 0xffff0000, v222
	v_lshlrev_b32_e32 v168, 16, v223
	v_and_b32_e32 v169, 0xffff0000, v223
	v_pk_add_f32 v[146:147], v[146:147], v[162:163]
	v_pk_add_f32 v[148:149], v[148:149], v[164:165]
	v_pk_add_f32 v[150:151], v[150:151], v[166:167]
	v_pk_add_f32 v[152:153], v[152:153], v[168:169]
	v_pk_mul_f32 v[170:171], v[146:147], v[146:147]
	v_pk_fma_f32 v[170:171], v[148:149], v[148:149], v[170:171]
	v_pk_fma_f32 v[170:171], v[150:151], v[150:151], v[170:171]
	v_pk_fma_f32 v[170:171], v[152:153], v[152:153], v[170:171]
	v_cvt_pk_bf16_f32 v172, v146, v147
	v_cvt_pk_bf16_f32 v173, v148, v149
	v_cvt_pk_bf16_f32 v174, v150, v151
	v_cvt_pk_bf16_f32 v175, v152, v153
	global_store_dwordx4 v144, v[172:175], s[98:99]
	v_lshlrev_b32_e32 v162, 16, v224
	v_and_b32_e32 v163, 0xffff0000, v224
	v_lshlrev_b32_e32 v164, 16, v225
	v_and_b32_e32 v165, 0xffff0000, v225
	v_lshlrev_b32_e32 v166, 16, v226
	v_and_b32_e32 v167, 0xffff0000, v226
	v_lshlrev_b32_e32 v168, 16, v227
	v_and_b32_e32 v169, 0xffff0000, v227
	v_pk_add_f32 v[154:155], v[154:155], v[162:163]
	v_pk_add_f32 v[156:157], v[156:157], v[164:165]
	v_pk_add_f32 v[158:159], v[158:159], v[166:167]
	v_pk_add_f32 v[160:161], v[160:161], v[168:169]
	v_pk_fma_f32 v[170:171], v[154:155], v[154:155], v[170:171]
	v_pk_fma_f32 v[170:171], v[156:157], v[156:157], v[170:171]
	v_pk_fma_f32 v[170:171], v[158:159], v[158:159], v[170:171]
	v_pk_fma_f32 v[170:171], v[160:161], v[160:161], v[170:171]
	v_cvt_pk_bf16_f32 v176, v154, v155
	v_cvt_pk_bf16_f32 v177, v156, v157
	v_cvt_pk_bf16_f32 v178, v158, v159
	v_cvt_pk_bf16_f32 v179, v160, v161
	global_store_dwordx4 v144, v[176:179], s[98:99] offset:256
	v_add_f32_e32 v162, v170, v171
	s_nop 1
	v_add_f32_dpp v163, v162, v162 quad_perm:[1,0,3,2] row_mask:0xf bank_mask:0xf
	s_nop 1
	v_add_f32_dpp v164, v163, v163 quad_perm:[2,3,0,1] row_mask:0xf bank_mask:0xf
	s_mov_b64 exec, vcc
	global_atomic_add_f32 v145, v164, s[14:15] offset:512
	s_mov_b64 exec, s[24:25]
	s_add_u32 s98, s98, 0x8000
	s_addc_u32 s99, s99, 0
	s_waitcnt lgkmcnt(0)
	ds_read_b128 v[146:149], v142
	ds_read_b128 v[150:153], v143
	ds_read_b128 v[154:157], v142 offset:128
	ds_read_b128 v[158:161], v143 offset:128
	s_waitcnt lgkmcnt(0)
	ds_write_b128 v140, v[28:31]
	ds_write_b128 v141, v[24:27]
	ds_write_b128 v140, v[20:23] offset:128
	ds_write_b128 v141, v[16:19] offset:128
	s_waitcnt vmcnt(19)
	v_lshlrev_b32_e32 v162, 16, v228
	v_and_b32_e32 v163, 0xffff0000, v228
	v_lshlrev_b32_e32 v164, 16, v229
	v_and_b32_e32 v165, 0xffff0000, v229
	v_lshlrev_b32_e32 v166, 16, v230
	v_and_b32_e32 v167, 0xffff0000, v230
	v_lshlrev_b32_e32 v168, 16, v231
	v_and_b32_e32 v169, 0xffff0000, v231
	v_pk_add_f32 v[146:147], v[146:147], v[162:163]
	v_pk_add_f32 v[148:149], v[148:149], v[164:165]
	v_pk_add_f32 v[150:151], v[150:151], v[166:167]
	v_pk_add_f32 v[152:153], v[152:153], v[168:169]
	v_pk_mul_f32 v[170:171], v[146:147], v[146:147]
	v_pk_fma_f32 v[170:171], v[148:149], v[148:149], v[170:171]
	v_pk_fma_f32 v[170:171], v[150:151], v[150:151], v[170:171]
	v_pk_fma_f32 v[170:171], v[152:153], v[152:153], v[170:171]
	v_cvt_pk_bf16_f32 v172, v146, v147
	v_cvt_pk_bf16_f32 v173, v148, v149
	v_cvt_pk_bf16_f32 v174, v150, v151
	v_cvt_pk_bf16_f32 v175, v152, v153
	global_store_dwordx4 v144, v[172:175], s[98:99]
	v_lshlrev_b32_e32 v162, 16, v232
	v_and_b32_e32 v163, 0xffff0000, v232
	v_lshlrev_b32_e32 v164, 16, v233
	v_and_b32_e32 v165, 0xffff0000, v233
	v_lshlrev_b32_e32 v166, 16, v234
	v_and_b32_e32 v167, 0xffff0000, v234
	v_lshlrev_b32_e32 v168, 16, v235
	v_and_b32_e32 v169, 0xffff0000, v235
	v_pk_add_f32 v[154:155], v[154:155], v[162:163]
	v_pk_add_f32 v[156:157], v[156:157], v[164:165]
	v_pk_add_f32 v[158:159], v[158:159], v[166:167]
	v_pk_add_f32 v[160:161], v[160:161], v[168:169]
	v_pk_fma_f32 v[170:171], v[154:155], v[154:155], v[170:171]
	v_pk_fma_f32 v[170:171], v[156:157], v[156:157], v[170:171]
	v_pk_fma_f32 v[170:171], v[158:159], v[158:159], v[170:171]
	v_pk_fma_f32 v[170:171], v[160:161], v[160:161], v[170:171]
	v_cvt_pk_bf16_f32 v176, v154, v155
	v_cvt_pk_bf16_f32 v177, v156, v157
	v_cvt_pk_bf16_f32 v178, v158, v159
	v_cvt_pk_bf16_f32 v179, v160, v161
	global_store_dwordx4 v144, v[176:179], s[98:99] offset:256
	v_add_f32_e32 v162, v170, v171
	s_nop 1
	v_add_f32_dpp v163, v162, v162 quad_perm:[1,0,3,2] row_mask:0xf bank_mask:0xf
	s_nop 1
	v_add_f32_dpp v164, v163, v163 quad_perm:[2,3,0,1] row_mask:0xf bank_mask:0xf
	s_mov_b64 exec, vcc
	global_atomic_add_f32 v145, v164, s[14:15] offset:576
	s_mov_b64 exec, s[24:25]
	s_add_u32 s98, s98, 0x8000
	s_addc_u32 s99, s99, 0
	s_waitcnt lgkmcnt(0)
	ds_read_b128 v[146:149], v142
	ds_read_b128 v[150:153], v143
	ds_read_b128 v[154:157], v142 offset:128
	ds_read_b128 v[158:161], v143 offset:128
	s_waitcnt lgkmcnt(0)
	ds_write_b128 v140, v[12:15]
	ds_write_b128 v141, v[8:11]
	ds_write_b128 v140, v[4:7] offset:128
	ds_write_b128 v141, v[0:3] offset:128
	s_waitcnt vmcnt(20)
	v_lshlrev_b32_e32 v162, 16, v236
	v_and_b32_e32 v163, 0xffff0000, v236
	v_lshlrev_b32_e32 v164, 16, v237
	v_and_b32_e32 v165, 0xffff0000, v237
	v_lshlrev_b32_e32 v166, 16, v238
	v_and_b32_e32 v167, 0xffff0000, v238
	v_lshlrev_b32_e32 v168, 16, v239
	v_and_b32_e32 v169, 0xffff0000, v239
	v_pk_add_f32 v[146:147], v[146:147], v[162:163]
	v_pk_add_f32 v[148:149], v[148:149], v[164:165]
	v_pk_add_f32 v[150:151], v[150:151], v[166:167]
	v_pk_add_f32 v[152:153], v[152:153], v[168:169]
	v_pk_mul_f32 v[170:171], v[146:147], v[146:147]
	v_pk_fma_f32 v[170:171], v[148:149], v[148:149], v[170:171]
	v_pk_fma_f32 v[170:171], v[150:151], v[150:151], v[170:171]
	v_pk_fma_f32 v[170:171], v[152:153], v[152:153], v[170:171]
	v_cvt_pk_bf16_f32 v172, v146, v147
	v_cvt_pk_bf16_f32 v173, v148, v149
	v_cvt_pk_bf16_f32 v174, v150, v151
	v_cvt_pk_bf16_f32 v175, v152, v153
	global_store_dwordx4 v144, v[172:175], s[98:99]
	v_lshlrev_b32_e32 v162, 16, v240
	v_and_b32_e32 v163, 0xffff0000, v240
	v_lshlrev_b32_e32 v164, 16, v241
	v_and_b32_e32 v165, 0xffff0000, v241
	v_lshlrev_b32_e32 v166, 16, v242
	v_and_b32_e32 v167, 0xffff0000, v242
	v_lshlrev_b32_e32 v168, 16, v243
	v_and_b32_e32 v169, 0xffff0000, v243
	v_pk_add_f32 v[154:155], v[154:155], v[162:163]
	v_pk_add_f32 v[156:157], v[156:157], v[164:165]
	v_pk_add_f32 v[158:159], v[158:159], v[166:167]
	v_pk_add_f32 v[160:161], v[160:161], v[168:169]
	v_pk_fma_f32 v[170:171], v[154:155], v[154:155], v[170:171]
	v_pk_fma_f32 v[170:171], v[156:157], v[156:157], v[170:171]
	v_pk_fma_f32 v[170:171], v[158:159], v[158:159], v[170:171]
	v_pk_fma_f32 v[170:171], v[160:161], v[160:161], v[170:171]
	v_cvt_pk_bf16_f32 v176, v154, v155
	v_cvt_pk_bf16_f32 v177, v156, v157
	v_cvt_pk_bf16_f32 v178, v158, v159
	v_cvt_pk_bf16_f32 v179, v160, v161
	global_store_dwordx4 v144, v[176:179], s[98:99] offset:256
	v_add_f32_e32 v162, v170, v171
	s_nop 1
	v_add_f32_dpp v163, v162, v162 quad_perm:[1,0,3,2] row_mask:0xf bank_mask:0xf
	s_nop 1
	v_add_f32_dpp v164, v163, v163 quad_perm:[2,3,0,1] row_mask:0xf bank_mask:0xf
	s_mov_b64 exec, vcc
	global_atomic_add_f32 v145, v164, s[14:15] offset:640
	s_mov_b64 exec, s[24:25]
	s_add_u32 s98, s98, 0x8000
	s_addc_u32 s99, s99, 0
	s_waitcnt lgkmcnt(0)
	ds_read_b128 v[146:149], v142
	ds_read_b128 v[150:153], v143
	ds_read_b128 v[154:157], v142 offset:128
	ds_read_b128 v[158:161], v143 offset:128
	s_waitcnt lgkmcnt(0)
	s_waitcnt vmcnt(21)
	v_lshlrev_b32_e32 v162, 16, v244
	v_and_b32_e32 v163, 0xffff0000, v244
	v_lshlrev_b32_e32 v164, 16, v245
	v_and_b32_e32 v165, 0xffff0000, v245
	v_lshlrev_b32_e32 v166, 16, v246
	v_and_b32_e32 v167, 0xffff0000, v246
	v_lshlrev_b32_e32 v168, 16, v247
	v_and_b32_e32 v169, 0xffff0000, v247
	v_pk_add_f32 v[146:147], v[146:147], v[162:163]
	v_pk_add_f32 v[148:149], v[148:149], v[164:165]
	v_pk_add_f32 v[150:151], v[150:151], v[166:167]
	v_pk_add_f32 v[152:153], v[152:153], v[168:169]
	v_pk_mul_f32 v[170:171], v[146:147], v[146:147]
	v_pk_fma_f32 v[170:171], v[148:149], v[148:149], v[170:171]
	v_pk_fma_f32 v[170:171], v[150:151], v[150:151], v[170:171]
	v_pk_fma_f32 v[170:171], v[152:153], v[152:153], v[170:171]
	v_cvt_pk_bf16_f32 v172, v146, v147
	v_cvt_pk_bf16_f32 v173, v148, v149
	v_cvt_pk_bf16_f32 v174, v150, v151
	v_cvt_pk_bf16_f32 v175, v152, v153
	global_store_dwordx4 v144, v[172:175], s[98:99]
	v_lshlrev_b32_e32 v162, 16, v248
	v_and_b32_e32 v163, 0xffff0000, v248
	v_lshlrev_b32_e32 v164, 16, v249
	v_and_b32_e32 v165, 0xffff0000, v249
	v_lshlrev_b32_e32 v166, 16, v250
	v_and_b32_e32 v167, 0xffff0000, v250
	v_lshlrev_b32_e32 v168, 16, v251
	v_and_b32_e32 v169, 0xffff0000, v251
	v_pk_add_f32 v[154:155], v[154:155], v[162:163]
	v_pk_add_f32 v[156:157], v[156:157], v[164:165]
	v_pk_add_f32 v[158:159], v[158:159], v[166:167]
	v_pk_add_f32 v[160:161], v[160:161], v[168:169]
	v_pk_fma_f32 v[170:171], v[154:155], v[154:155], v[170:171]
	v_pk_fma_f32 v[170:171], v[156:157], v[156:157], v[170:171]
	v_pk_fma_f32 v[170:171], v[158:159], v[158:159], v[170:171]
	v_pk_fma_f32 v[170:171], v[160:161], v[160:161], v[170:171]
	v_cvt_pk_bf16_f32 v176, v154, v155
	v_cvt_pk_bf16_f32 v177, v156, v157
	v_cvt_pk_bf16_f32 v178, v158, v159
	v_cvt_pk_bf16_f32 v179, v160, v161
	global_store_dwordx4 v144, v[176:179], s[98:99] offset:256
	v_add_f32_e32 v162, v170, v171
	s_nop 1
	v_add_f32_dpp v163, v162, v162 quad_perm:[1,0,3,2] row_mask:0xf bank_mask:0xf
	s_nop 1
	v_add_f32_dpp v164, v163, v163 quad_perm:[2,3,0,1] row_mask:0xf bank_mask:0xf
	s_mov_b64 exec, vcc
	global_atomic_add_f32 v145, v164, s[14:15] offset:704
	s_mov_b64 exec, s[24:25]
	s_branch .Lqepi_end_8

.Lqn_done_ph8:
	v_and_b32_e32 v146, 63, v180
	v_and_b32_e32 v147, 15, v180
	v_bfe_u32 v148, v180, 4, 2
	v_lshrrev_b32_e32 v149, 6, v180
	v_lshlrev_b32_e32 v149, 12, v149
	v_add_u32_e32 v149, 0x20000, v149
	v_and_b32_e32 v150, 7, v147
	v_xor_b32_e32 v150, v148, v150
	v_lshlrev_b32_e32 v150, 4, v150
	v_lshl_add_u32 v150, v147, 8, v150
	v_add_u32_e32 v140, v149, v150
	v_xor_b32_e32 v141, 64, v140
	v_lshrrev_b32_e32 v151, 2, v146
	v_and_b32_e32 v152, 3, v146
	v_and_b32_e32 v153, 7, v151
	v_lshlrev_b32_e32 v154, 1, v152
	v_xor_b32_e32 v154, v154, v153
	v_lshlrev_b32_e32 v154, 4, v154
	v_lshl_add_u32 v154, v151, 8, v154
	v_add_u32_e32 v142, v149, v154
	v_xor_b32_e32 v143, 16, v142
	s_lshr_b32 s99, s98, 1
	s_lshl_b32 s99, s99, 7
	s_lshl_b32 s24, s55, 8
	s_add_i32 s24, s24, s44
	s_add_i32 s24, s24, s99
	v_add_u32_e32 v155, s24, v151
	v_lshlrev_b32_e32 v145, 2, v155
	v_lshlrev_b32_e32 v155, 11, v155
	s_and_b32 s99, s98, 1
	s_lshl_b32 s99, s99, 7
	s_lshl_b32 s24, s54, 8
	s_add_i32 s24, s24, s45
	s_add_i32 s24, s24, s99
	v_lshl_add_u32 v156, v152, 3, s24
	v_lshl_add_u32 v144, v156, 1, v155
	v_cmp_eq_u32_e32 vcc, 0, v152
	s_mov_b64 s[98:99], s[12:13]
	global_load_dwordx4 v[188:191], v144, s[98:99]
	s_add_u32 s98, s98, 0x8000
	s_addc_u32 s99, s99, 0
	global_load_dwordx4 v[192:195], v144, s[98:99]
	s_add_u32 s98, s98, 0x8000
	s_addc_u32 s99, s99, 0
	global_load_dwordx4 v[196:199], v144, s[98:99]
	s_add_u32 s98, s98, 0x8000
	s_addc_u32 s99, s99, 0
	global_load_dwordx4 v[200:203], v144, s[98:99]
	s_mov_b64 s[24:25], exec
	s_mov_b64 s[98:99], s[12:13]
	ds_write_b128 v140, v[124:127]
	ds_write_b128 v141, v[120:123]
	s_waitcnt lgkmcnt(0)
	ds_read_b128 v[146:149], v142
	ds_read_b128 v[150:153], v143
	s_waitcnt vmcnt(0)
	s_waitcnt lgkmcnt(0)
	v_lshlrev_b32_e32 v162, 16, v188
	v_and_b32_e32 v163, 0xffff0000, v188
	v_lshlrev_b32_e32 v164, 16, v189
	v_and_b32_e32 v165, 0xffff0000, v189
	v_lshlrev_b32_e32 v166, 16, v190
	v_and_b32_e32 v167, 0xffff0000, v190
	v_lshlrev_b32_e32 v168, 16, v191
	v_and_b32_e32 v169, 0xffff0000, v191
	v_pk_add_f32 v[146:147], v[146:147], v[162:163]
	v_pk_add_f32 v[148:149], v[148:149], v[164:165]
	v_pk_add_f32 v[150:151], v[150:151], v[166:167]
	v_pk_add_f32 v[152:153], v[152:153], v[168:169]
	v_pk_mul_f32 v[170:171], v[146:147], v[146:147]
	v_pk_fma_f32 v[170:171], v[148:149], v[148:149], v[170:171]
	v_pk_fma_f32 v[170:171], v[150:151], v[150:151], v[170:171]
	v_pk_fma_f32 v[170:171], v[152:153], v[152:153], v[170:171]
	v_cvt_pk_bf16_f32 v172, v146, v147
	v_cvt_pk_bf16_f32 v173, v148, v149
	v_cvt_pk_bf16_f32 v174, v150, v151
	v_cvt_pk_bf16_f32 v175, v152, v153
	global_store_dwordx4 v144, v[172:175], s[98:99]
	v_add_f32_e32 v162, v170, v171
	s_nop 1
	v_add_f32_dpp v163, v162, v162 quad_perm:[1,0,3,2] row_mask:0xf bank_mask:0xf
	s_nop 1
	v_add_f32_dpp v164, v163, v163 quad_perm:[2,3,0,1] row_mask:0xf bank_mask:0xf
	s_mov_b64 exec, vcc
	global_atomic_add_f32 v145, v164, s[14:15] offset:0
	s_mov_b64 exec, s[24:25]
	s_add_u32 s98, s98, 0x8000
	s_addc_u32 s99, s99, 0
	ds_write_b128 v140, v[108:111]
	ds_write_b128 v141, v[104:107]
	s_waitcnt lgkmcnt(0)
	ds_read_b128 v[146:149], v142
	ds_read_b128 v[150:153], v143
	s_waitcnt vmcnt(0)
	s_waitcnt lgkmcnt(0)
	v_lshlrev_b32_e32 v162, 16, v192
	v_and_b32_e32 v163, 0xffff0000, v192
	v_lshlrev_b32_e32 v164, 16, v193
	v_and_b32_e32 v165, 0xffff0000, v193
	v_lshlrev_b32_e32 v166, 16, v194
	v_and_b32_e32 v167, 0xffff0000, v194
	v_lshlrev_b32_e32 v168, 16, v195
	v_and_b32_e32 v169, 0xffff0000, v195
	v_pk_add_f32 v[146:147], v[146:147], v[162:163]
	v_pk_add_f32 v[148:149], v[148:149], v[164:165]
	v_pk_add_f32 v[150:151], v[150:151], v[166:167]
	v_pk_add_f32 v[152:153], v[152:153], v[168:169]
	v_pk_mul_f32 v[170:171], v[146:147], v[146:147]
	v_pk_fma_f32 v[170:171], v[148:149], v[148:149], v[170:171]
	v_pk_fma_f32 v[170:171], v[150:151], v[150:151], v[170:171]
	v_pk_fma_f32 v[170:171], v[152:153], v[152:153], v[170:171]
	v_cvt_pk_bf16_f32 v172, v146, v147
	v_cvt_pk_bf16_f32 v173, v148, v149
	v_cvt_pk_bf16_f32 v174, v150, v151
	v_cvt_pk_bf16_f32 v175, v152, v153
	global_store_dwordx4 v144, v[172:175], s[98:99]
	v_add_f32_e32 v162, v170, v171
	s_nop 1
	v_add_f32_dpp v163, v162, v162 quad_perm:[1,0,3,2] row_mask:0xf bank_mask:0xf
	s_nop 1
	v_add_f32_dpp v164, v163, v163 quad_perm:[2,3,0,1] row_mask:0xf bank_mask:0xf
	s_mov_b64 exec, vcc
	global_atomic_add_f32 v145, v164, s[14:15] offset:64
	s_mov_b64 exec, s[24:25]
	s_add_u32 s98, s98, 0x8000
	s_addc_u32 s99, s99, 0
	ds_write_b128 v140, v[92:95]
	ds_write_b128 v141, v[88:91]
	s_waitcnt lgkmcnt(0)
	ds_read_b128 v[146:149], v142
	ds_read_b128 v[150:153], v143
	s_waitcnt vmcnt(0)
	s_waitcnt lgkmcnt(0)
	v_lshlrev_b32_e32 v162, 16, v196
	v_and_b32_e32 v163, 0xffff0000, v196
	v_lshlrev_b32_e32 v164, 16, v197
	v_and_b32_e32 v165, 0xffff0000, v197
	v_lshlrev_b32_e32 v166, 16, v198
	v_and_b32_e32 v167, 0xffff0000, v198
	v_lshlrev_b32_e32 v168, 16, v199
	v_and_b32_e32 v169, 0xffff0000, v199
	v_pk_add_f32 v[146:147], v[146:147], v[162:163]
	v_pk_add_f32 v[148:149], v[148:149], v[164:165]
	v_pk_add_f32 v[150:151], v[150:151], v[166:167]
	v_pk_add_f32 v[152:153], v[152:153], v[168:169]
	v_pk_mul_f32 v[170:171], v[146:147], v[146:147]
	v_pk_fma_f32 v[170:171], v[148:149], v[148:149], v[170:171]
	v_pk_fma_f32 v[170:171], v[150:151], v[150:151], v[170:171]
	v_pk_fma_f32 v[170:171], v[152:153], v[152:153], v[170:171]
	v_cvt_pk_bf16_f32 v172, v146, v147
	v_cvt_pk_bf16_f32 v173, v148, v149
	v_cvt_pk_bf16_f32 v174, v150, v151
	v_cvt_pk_bf16_f32 v175, v152, v153
	global_store_dwordx4 v144, v[172:175], s[98:99]
	v_add_f32_e32 v162, v170, v171
	s_nop 1
	v_add_f32_dpp v163, v162, v162 quad_perm:[1,0,3,2] row_mask:0xf bank_mask:0xf
	s_nop 1
	v_add_f32_dpp v164, v163, v163 quad_perm:[2,3,0,1] row_mask:0xf bank_mask:0xf
	s_mov_b64 exec, vcc
	global_atomic_add_f32 v145, v164, s[14:15] offset:128
	s_mov_b64 exec, s[24:25]
	s_add_u32 s98, s98, 0x8000
	s_addc_u32 s99, s99, 0
	ds_write_b128 v140, v[76:79]
	ds_write_b128 v141, v[72:75]
	s_waitcnt lgkmcnt(0)
	ds_read_b128 v[146:149], v142
	ds_read_b128 v[150:153], v143
	s_waitcnt vmcnt(0)
	s_waitcnt lgkmcnt(0)
	v_lshlrev_b32_e32 v162, 16, v200
	v_and_b32_e32 v163, 0xffff0000, v200
	v_lshlrev_b32_e32 v164, 16, v201
	v_and_b32_e32 v165, 0xffff0000, v201
	v_lshlrev_b32_e32 v166, 16, v202
	v_and_b32_e32 v167, 0xffff0000, v202
	v_lshlrev_b32_e32 v168, 16, v203
	v_and_b32_e32 v169, 0xffff0000, v203
	v_pk_add_f32 v[146:147], v[146:147], v[162:163]
	v_pk_add_f32 v[148:149], v[148:149], v[164:165]
	v_pk_add_f32 v[150:151], v[150:151], v[166:167]
	v_pk_add_f32 v[152:153], v[152:153], v[168:169]
	v_pk_mul_f32 v[170:171], v[146:147], v[146:147]
	v_pk_fma_f32 v[170:171], v[148:149], v[148:149], v[170:171]
	v_pk_fma_f32 v[170:171], v[150:151], v[150:151], v[170:171]
	v_pk_fma_f32 v[170:171], v[152:153], v[152:153], v[170:171]
	v_cvt_pk_bf16_f32 v172, v146, v147
	v_cvt_pk_bf16_f32 v173, v148, v149
	v_cvt_pk_bf16_f32 v174, v150, v151
	v_cvt_pk_bf16_f32 v175, v152, v153
	global_store_dwordx4 v144, v[172:175], s[98:99]
	v_add_f32_e32 v162, v170, v171
	s_nop 1
	v_add_f32_dpp v163, v162, v162 quad_perm:[1,0,3,2] row_mask:0xf bank_mask:0xf
	s_nop 1
	v_add_f32_dpp v164, v163, v163 quad_perm:[2,3,0,1] row_mask:0xf bank_mask:0xf
	s_mov_b64 exec, vcc
	global_atomic_add_f32 v145, v164, s[14:15] offset:192
	s_mov_b64 exec, s[24:25]
.Lqepi_end_8:
.LBB0_1537:
	s_or_b64 exec, exec, s[24:25]
	s_and_b64 vcc, exec, s[6:7]
	s_mov_b64 s[6:7], -1
	s_cbranch_vccnz .LBB0_1506
	s_andn2_b64 vcc, exec, s[10:11]
	s_cbranch_vccnz .LBB0_1505
	s_barrier
	s_branch .LBB0_1505

.LBB0_1822:
	s_and_b64 vcc, exec, s[4:5]
	s_cbranch_vccnz .LBB0_1858
	s_waitcnt lgkmcnt(0)
	v_ashrrev_i32_e32 v1, 31, v8
	v_lshrrev_b32_e32 v1, 26, v1
	v_add_u32_e32 v1, v8, v1
	v_ashrrev_i32_e32 v9, 6, v1
	v_bfe_i32 v1, v8, 27, 1
	v_lshlrev_b32_e32 v0, 4, v8
	v_lshrrev_b32_e32 v1, 22, v1
	v_add_u32_e32 v1, v0, v1
	v_and_b32_e32 v1, 0xfffffc00, v1
	v_sub_u32_e32 v1, v0, v1
	v_lshrrev_b32_e32 v2, 4, v1
	v_bitop3_b32 v2, v2, v1, 32 bitop3:0x6c
	v_ashrrev_i32_e32 v1, 31, v1
	v_lshrrev_b32_e32 v1, 26, v1
	v_add_u32_e32 v1, v2, v1
	v_ashrrev_i32_e32 v10, 6, v1
	v_mul_i32_i24_e32 v4, 64, v10
	v_sub_u32_e32 v2, v2, v4
	v_mov_b32_e32 v4, 1
	v_lshlrev_b32_e32 v3, 3, v9
	v_lshlrev_b32_e32 v1, 5, v9
	v_ashrrev_i16_sdwa v2, v4, sext(v2) dst_sel:DWORD dst_unused:UNUSED_PAD src0_sel:DWORD src1_sel:BYTE_0
	v_and_b32_e32 v3, 0x1ffff0, v3
	v_and_b32_e32 v1, 32, v1
	v_bfe_i32 v11, v2, 0, 16
	v_add_u32_e32 v1, v1, v11
	v_add_lshl_u32 v2, v10, v3, 11
	v_add_u32_e32 v0, 0x2000, v0
	v_lshl_add_u32 v128, v1, 1, v2
	v_ashrrev_i32_e32 v1, 31, v0
	v_lshrrev_b32_e32 v1, 22, v1
	s_load_dwordx2 s[6:7], s[6:7], 0x120
	v_add_u32_e32 v1, v0, v1
	v_ashrrev_i32_e32 v12, 10, v1
	v_mul_i32_i24_e32 v1, 0x400, v12
	v_sub_u32_e32 v0, v0, v1
	v_lshrrev_b32_e32 v1, 4, v0
	s_waitcnt lgkmcnt(0)
	s_add_u32 s40, s6, 0xbb8b200
	v_bitop3_b32 v0, v1, v0, 32 bitop3:0x6c
	s_addc_u32 s41, s7, 0
	v_ashrrev_i32_e32 v2, 31, v0
	s_add_u32 s42, s6, 0x1b80000
	v_lshrrev_b32_e32 v2, 26, v2
	s_addc_u32 s43, s7, 0
	s_ashr_i32 s14, s18, 6
	v_add_u32_e32 v2, v0, v2
	s_ashr_i32 s31, s30, 31
	s_ashr_i32 s29, s28, 31
	v_ashrrev_i32_e32 v13, 6, v2
	v_and_b32_e32 v2, 0xc0, v2
	s_ashr_i32 s15, s18, 8
	s_lshl_b32 s44, s14, 10
	s_lshl_b64 s[8:9], s[30:31], 19
	s_lshl_b64 s[10:11], s[28:29], 19
	v_sub_u32_e32 v0, v0, v2
	s_add_u32 s36, s42, s10
	v_lshlrev_b32_e32 v1, 3, v12
	v_lshlrev_b32_e32 v3, 5, v12
	v_ashrrev_i16_sdwa v0, v4, sext(v0) dst_sel:DWORD dst_unused:UNUSED_PAD src0_sel:DWORD src1_sel:BYTE_0
	s_addc_u32 s37, s43, s11
	s_add_i32 s31, s44, 0
	v_and_b32_e32 v1, 0x1ffff0, v1
	v_and_b32_e32 v3, 32, v3
	v_bfe_i32 v14, v0, 0, 16
	s_add_i32 m0, s31, 0x10000
	v_add_u32_e32 v0, v3, v14
	v_add_lshl_u32 v1, v13, v1, 11
	global_load_lds_dwordx4 v128, s[36:37]
	s_add_i32 m0, s31, 0x12000
	v_lshl_add_u32 v130, v0, 1, v1
	s_add_u32 s10, s36, 0x40000
	global_load_lds_dwordx4 v130, s[36:37]
	s_addc_u32 s11, s37, 0
	s_add_i32 m0, s31, 0x14000
	v_mov_b32_e32 v129, 0
	global_load_lds_dwordx4 v128, s[10:11]
	s_add_i32 m0, s31, 0x16000
	s_add_u32 s34, s40, s8
	s_addc_u32 s35, s41, s9
	s_add_i32 s45, s31, 0x2000
	global_load_lds_dwordx4 v130, s[10:11]
	s_mov_b32 m0, s31
	s_add_u32 s8, s34, 0x40000
	global_load_lds_dwordx4 v128, s[34:35]
	s_mov_b32 m0, s45
	s_addc_u32 s9, s35, 0
	s_add_i32 s48, s31, 0x4000
	global_load_lds_dwordx4 v130, s[34:35]
	s_mov_b32 m0, s48
	s_add_i32 s49, s31, 0x6000
	global_load_lds_dwordx4 v128, s[8:9]
	s_mov_b32 m0, s49
	v_mov_b32_e32 v131, v129
	global_load_lds_dwordx4 v130, s[8:9]
	s_cmp_eq_u32 s15, 1
	s_mov_b32 s50, 0
	s_mov_b32 s101, 0xf
	s_mov_b32 s100, 0xf
	v_lshl_add_u64 v[6:7], s[36:37], 0, v[128:129]
	v_lshl_add_u64 v[4:5], s[36:37], 0, v[130:131]
	v_lshl_add_u64 v[0:1], s[34:35], 0, v[128:129]
	s_cselect_b64 s[8:9], -1, 0
	s_cmp_lg_u32 s15, 1
	v_lshl_add_u64 v[2:3], s[34:35], 0, v[130:131]
	s_cbranch_scc1 .LBB0_1825
	s_barrier

.LBB0_1827:
	s_mov_b32 s101, s100
	s_andn2_b64 vcc, exec, s[6:7]
	s_mov_b32 s28, s20
	s_mov_b32 s30, s22
	s_mov_b64 s[36:37], s[26:27]
	s_mov_b64 s[34:35], s[24:25]
	s_cbranch_vccz .LBB0_1857
.LBB0_1828:
	s_add_i32 s50, s50, 1
	s_mul_i32 s6, s50, s47
	s_mul_hi_u32 s7, s50, s46
	s_add_i32 s7, s7, s6
	s_mul_i32 s6, s50, s46
	s_add_u32 s24, s6, s94
	s_addc_u32 s25, s7, s95
	s_mov_b32 s100, 0xf
	s_cmp_eq_u32 s46, 0x100
	s_cbranch_scc0 .Lqs_done_11
	s_cmp_eq_u32 s50, 4
	s_cbranch_scc0 .Lqs_done_11
	s_mov_b32 s25, 0
	s_mov_b32 s24, 0x7fffffff
	s_cmp_lt_u32 s94, 16
	s_cbranch_scc0 .Lqs_done_11
	s_lshr_b32 s24, s94, 2
	s_add_i32 s24, s24, 0x400
	s_and_b32 s98, s94, 3
	s_lshl_b32 s100, 1, s98
	s_lshl_b32 s98, s98, 4
	s_or_b32 s100, s100, s98
	s_or_b32 s100, s100, 0x40
.Lqs_done_11:
	v_cmp_gt_i64_e32 vcc, s[24:25], v[138:139]
	v_cmp_lt_i64_e64 s[6:7], s[24:25], v[136:137]
	s_cbranch_vccnz .LBB0_1834
	s_ashr_i32 s20, s24, 31
	s_lshr_b32 s20, s20, 29
	s_add_i32 s22, s24, s20
	s_and_b32 s20, s22, -8
	s_sub_i32 s23, s24, s20
	s_cmp_gt_i32 s23, 3
	s_mov_b64 s[20:21], -1
	s_cbranch_scc0 .LBB0_1831
	s_lshl_b32 s20, s23, 7
	s_or_b32 s24, s20, 4
	s_mov_b64 s[20:21], 0

.LBB0_1835:
	ds_read_b128 v[140:143], v182
	ds_read_b128 v[144:147], v182 offset:1024
	ds_read_b128 v[148:151], v182 offset:2048
	ds_read_b128 v[152:155], v182 offset:3072
	ds_read_b128 v[156:159], v183
	ds_read_b128 v[160:163], v183 offset:1024
	ds_read_b128 v[164:167], v183 offset:2048
	ds_read_b128 v[168:171], v183 offset:3072
	s_add_u32 s36, s34, 0xfffc0080
	s_addc_u32 s37, s35, -1
	s_cmp_eq_u32 s63, 12
	s_cselect_b32 s39, s23, s37
	s_cselect_b32 s38, s29, s36
	s_cselect_b32 s37, s21, s59
	s_cselect_b32 s36, s57, s58
	v_lshl_add_u64 v[210:211], s[34:35], 0, v[132:133]
	s_add_i32 m0, s31, 0xc000
	ds_read_b128 v[172:175], v184
	ds_read_b128 v[176:179], v184 offset:1024
	ds_read_b128 v[186:189], v184 offset:2048
	ds_read_b128 v[190:193], v184 offset:3072
	ds_read_b128 v[194:197], v184 offset:4096
	ds_read_b128 v[198:201], v184 offset:5120
	ds_read_b128 v[202:205], v184 offset:6144
	ds_read_b128 v[206:209], v184 offset:7168
	global_load_lds_dwordx4 v[210:211], off
	v_lshl_add_u64 v[210:211], s[34:35], 0, v[134:135]
	s_add_i32 m0, s31, 0xe000
	s_nop 0
	global_load_lds_dwordx4 v[210:211], off
	s_waitcnt vmcnt(8)
	s_waitcnt lgkmcnt(0)
	s_barrier
	s_setprio 1
	s_waitcnt lgkmcnt(0)
	s_bitcmp1_b32 s101, 0
	s_cbranch_scc0 .Lmm_11_0
	v_mfma_f32_16x16x32_bf16 v[124:127], v[140:143], v[172:175], v[124:127]
	v_mfma_f32_16x16x32_bf16 v[120:123], v[148:151], v[172:175], v[120:123]
	v_mfma_f32_16x16x32_bf16 v[108:111], v[140:143], v[186:189], v[108:111]
	v_mfma_f32_16x16x32_bf16 v[104:107], v[148:151], v[186:189], v[104:107]
	v_mfma_f32_16x16x32_bf16 v[92:95], v[140:143], v[194:197], v[92:95]
	v_mfma_f32_16x16x32_bf16 v[88:91], v[148:151], v[194:197], v[88:91]
	v_mfma_f32_16x16x32_bf16 v[76:79], v[140:143], v[202:205], v[76:79]
	v_mfma_f32_16x16x32_bf16 v[72:75], v[148:151], v[202:205], v[72:75]
	v_mfma_f32_16x16x32_bf16 v[124:127], v[144:147], v[176:179], v[124:127]
	v_mfma_f32_16x16x32_bf16 v[120:123], v[152:155], v[176:179], v[120:123]
	v_mfma_f32_16x16x32_bf16 v[108:111], v[144:147], v[190:193], v[108:111]
	v_mfma_f32_16x16x32_bf16 v[104:107], v[152:155], v[190:193], v[104:107]
	v_mfma_f32_16x16x32_bf16 v[92:95], v[144:147], v[198:201], v[92:95]
	v_mfma_f32_16x16x32_bf16 v[88:91], v[152:155], v[198:201], v[88:91]
	v_mfma_f32_16x16x32_bf16 v[76:79], v[144:147], v[206:209], v[76:79]
	v_mfma_f32_16x16x32_bf16 v[72:75], v[152:155], v[206:209], v[72:75]

.Lmm_11_1:
	s_setprio 0
	s_barrier
	s_add_i32 s64, s55, s44
	v_lshl_add_u64 v[210:211], s[36:37], 0, v[128:129]
	s_mov_b32 m0, s64
	ds_read_b128 v[172:175], v184 offset:16384
	ds_read_b128 v[176:179], v184 offset:17408
	ds_read_b128 v[186:189], v184 offset:18432
	ds_read_b128 v[190:193], v184 offset:19456
	ds_read_b128 v[194:197], v184 offset:20480
	ds_read_b128 v[198:201], v184 offset:21504
	ds_read_b128 v[202:205], v184 offset:22528
	ds_read_b128 v[206:209], v184 offset:23552
	global_load_lds_dwordx4 v[210:211], off
	s_add_i32 m0, s64, 0x2000
	s_add_u32 s64, s36, 0x40000
	v_lshl_add_u64 v[212:213], s[36:37], 0, v[130:131]
	s_addc_u32 s65, s37, 0
	s_add_i32 s66, s56, s44
	global_load_lds_dwordx4 v[212:213], off
	v_lshl_add_u64 v[214:215], s[64:65], 0, v[128:129]
	s_mov_b32 m0, s66
	v_lshl_add_u64 v[216:217], s[38:39], 0, v[130:131]
	global_load_lds_dwordx4 v[214:215], off
	v_lshl_add_u64 v[214:215], s[64:65], 0, v[130:131]
	s_add_i32 m0, s66, 0x2000
	s_nop 0
	global_load_lds_dwordx4 v[214:215], off
	v_lshl_add_u64 v[214:215], s[38:39], 0, v[128:129]
	s_mov_b32 m0, s31
	s_nop 0
	global_load_lds_dwordx4 v[214:215], off
	s_mov_b32 m0, s45
	s_nop 0
	global_load_lds_dwordx4 v[216:217], off
	s_waitcnt vmcnt(8)
	s_waitcnt lgkmcnt(0)
	s_barrier
	s_setprio 1
	s_waitcnt lgkmcnt(0)
	s_bitcmp1_b32 s101, 2
	s_cbranch_scc0 .Lmm_11_2
	v_mfma_f32_16x16x32_bf16 v[60:63], v[140:143], v[172:175], v[60:63]
	v_mfma_f32_16x16x32_bf16 v[56:59], v[148:151], v[172:175], v[56:59]
	v_mfma_f32_16x16x32_bf16 v[44:47], v[140:143], v[186:189], v[44:47]
	v_mfma_f32_16x16x32_bf16 v[40:43], v[148:151], v[186:189], v[40:43]
	v_mfma_f32_16x16x32_bf16 v[28:31], v[140:143], v[194:197], v[28:31]
	v_mfma_f32_16x16x32_bf16 v[24:27], v[148:151], v[194:197], v[24:27]
	v_mfma_f32_16x16x32_bf16 v[12:15], v[140:143], v[202:205], v[12:15]
	v_mfma_f32_16x16x32_bf16 v[8:11], v[148:151], v[202:205], v[8:11]
	v_mfma_f32_16x16x32_bf16 v[60:63], v[144:147], v[176:179], v[60:63]
	v_mfma_f32_16x16x32_bf16 v[56:59], v[152:155], v[176:179], v[56:59]
	v_mfma_f32_16x16x32_bf16 v[44:47], v[144:147], v[190:193], v[44:47]
	v_mfma_f32_16x16x32_bf16 v[40:43], v[152:155], v[190:193], v[40:43]
	v_mfma_f32_16x16x32_bf16 v[28:31], v[144:147], v[198:201], v[28:31]
	v_mfma_f32_16x16x32_bf16 v[24:27], v[152:155], v[198:201], v[24:27]
	v_mfma_f32_16x16x32_bf16 v[12:15], v[144:147], v[206:209], v[12:15]
	v_mfma_f32_16x16x32_bf16 v[8:11], v[152:155], v[206:209], v[8:11]

.Lmm_11_3:
	s_setprio 0
	s_barrier
	s_add_i32 s64, 0, 0x18000
	s_add_i32 s65, 0, 0x1c000
	v_add_u32_e32 v152, s64, v181
	v_add_u32_e32 v168, s65, v181
	ds_read_b128 v[140:143], v152
	ds_read_b128 v[144:147], v152 offset:1024
	ds_read_b128 v[148:151], v152 offset:2048
	ds_read_b128 v[152:155], v152 offset:3072
	ds_read_b128 v[156:159], v168
	ds_read_b128 v[160:163], v168 offset:1024
	ds_read_b128 v[164:167], v168 offset:2048
	ds_read_b128 v[168:171], v168 offset:3072
	s_add_u32 s38, s38, 0x40000
	s_addc_u32 s39, s39, 0
	s_mov_b32 m0, s48
	v_lshl_add_u64 v[218:219], s[38:39], 0, v[128:129]
	ds_read_b128 v[172:175], v184 offset:32768
	ds_read_b128 v[176:179], v184 offset:33792
	ds_read_b128 v[186:189], v184 offset:34816
	ds_read_b128 v[190:193], v184 offset:35840
	ds_read_b128 v[194:197], v184 offset:36864
	ds_read_b128 v[198:201], v184 offset:37888
	ds_read_b128 v[202:205], v184 offset:38912
	ds_read_b128 v[206:209], v184 offset:39936
	global_load_lds_dwordx4 v[218:219], off
	v_lshl_add_u64 v[218:219], s[38:39], 0, v[130:131]
	s_mov_b32 m0, s49
	s_nop 0
	global_load_lds_dwordx4 v[218:219], off
	s_waitcnt vmcnt(8)
	s_waitcnt lgkmcnt(0)
	s_barrier
	s_setprio 1
	s_waitcnt lgkmcnt(0)
	s_bitcmp1_b32 s101, 0
	s_cbranch_scc0 .Lmm_11_4
	v_mfma_f32_16x16x32_bf16 v[124:127], v[140:143], v[172:175], v[124:127]
	v_mfma_f32_16x16x32_bf16 v[120:123], v[148:151], v[172:175], v[120:123]
	v_mfma_f32_16x16x32_bf16 v[108:111], v[140:143], v[186:189], v[108:111]
	v_mfma_f32_16x16x32_bf16 v[104:107], v[148:151], v[186:189], v[104:107]
	v_mfma_f32_16x16x32_bf16 v[92:95], v[140:143], v[194:197], v[92:95]
	v_mfma_f32_16x16x32_bf16 v[88:91], v[148:151], v[194:197], v[88:91]
	v_mfma_f32_16x16x32_bf16 v[76:79], v[140:143], v[202:205], v[76:79]
	v_mfma_f32_16x16x32_bf16 v[72:75], v[148:151], v[202:205], v[72:75]
	v_mfma_f32_16x16x32_bf16 v[124:127], v[144:147], v[176:179], v[124:127]
	v_mfma_f32_16x16x32_bf16 v[120:123], v[152:155], v[176:179], v[120:123]
	v_mfma_f32_16x16x32_bf16 v[108:111], v[144:147], v[190:193], v[108:111]
	v_mfma_f32_16x16x32_bf16 v[104:107], v[152:155], v[190:193], v[104:107]
	v_mfma_f32_16x16x32_bf16 v[92:95], v[144:147], v[198:201], v[92:95]
	v_mfma_f32_16x16x32_bf16 v[88:91], v[152:155], v[198:201], v[88:91]
	v_mfma_f32_16x16x32_bf16 v[76:79], v[144:147], v[206:209], v[76:79]
	v_mfma_f32_16x16x32_bf16 v[72:75], v[152:155], v[206:209], v[72:75]

.Lmm_11_5:
	s_setprio 0
	s_barrier
	s_add_i32 s38, s64, s44
	v_lshl_add_u64 v[210:211], v[210:211], 0, s[14:15]
	s_mov_b32 m0, s38
	ds_read_b128 v[172:175], v184 offset:49152
	ds_read_b128 v[176:179], v184 offset:50176
	ds_read_b128 v[186:189], v184 offset:51200
	ds_read_b128 v[190:193], v184 offset:52224
	ds_read_b128 v[194:197], v184 offset:53248
	ds_read_b128 v[198:201], v184 offset:54272
	ds_read_b128 v[202:205], v184 offset:55296
	ds_read_b128 v[206:209], v184 offset:56320
	global_load_lds_dwordx4 v[210:211], off
	s_add_i32 m0, s38, 0x2000
	s_add_u32 s36, s36, 0x40080
	v_lshl_add_u64 v[210:211], v[212:213], 0, s[14:15]
	s_addc_u32 s37, s37, 0
	s_add_i32 s38, s65, s44
	global_load_lds_dwordx4 v[210:211], off
	v_lshl_add_u64 v[210:211], s[36:37], 0, v[128:129]
	s_mov_b32 m0, s38
	s_nop 0
	global_load_lds_dwordx4 v[210:211], off
	v_lshl_add_u64 v[210:211], s[36:37], 0, v[130:131]
	s_add_i32 m0, s38, 0x2000
	s_nop 0
	global_load_lds_dwordx4 v[210:211], off
	v_lshl_add_u64 v[210:211], v[214:215], 0, s[14:15]
	s_mov_b32 m0, s53
	s_nop 0
	global_load_lds_dwordx4 v[210:211], off
	v_lshl_add_u64 v[210:211], v[216:217], 0, s[14:15]
	s_mov_b32 m0, s54
	s_nop 0
	global_load_lds_dwordx4 v[210:211], off
	s_waitcnt vmcnt(8)
	s_waitcnt lgkmcnt(0)
	s_barrier
	s_setprio 1
	s_waitcnt lgkmcnt(0)
	s_bitcmp1_b32 s101, 2
	s_cbranch_scc0 .Lmm_11_6
	v_mfma_f32_16x16x32_bf16 v[60:63], v[140:143], v[172:175], v[60:63]
	v_mfma_f32_16x16x32_bf16 v[56:59], v[148:151], v[172:175], v[56:59]
	v_mfma_f32_16x16x32_bf16 v[44:47], v[140:143], v[186:189], v[44:47]
	v_mfma_f32_16x16x32_bf16 v[40:43], v[148:151], v[186:189], v[40:43]
	v_mfma_f32_16x16x32_bf16 v[28:31], v[140:143], v[194:197], v[28:31]
	v_mfma_f32_16x16x32_bf16 v[24:27], v[148:151], v[194:197], v[24:27]
	v_mfma_f32_16x16x32_bf16 v[12:15], v[140:143], v[202:205], v[12:15]
	v_mfma_f32_16x16x32_bf16 v[8:11], v[148:151], v[202:205], v[8:11]
	v_mfma_f32_16x16x32_bf16 v[60:63], v[144:147], v[176:179], v[60:63]
	v_mfma_f32_16x16x32_bf16 v[56:59], v[152:155], v[176:179], v[56:59]
	v_mfma_f32_16x16x32_bf16 v[44:47], v[144:147], v[190:193], v[44:47]
	v_mfma_f32_16x16x32_bf16 v[40:43], v[152:155], v[190:193], v[40:43]
	v_mfma_f32_16x16x32_bf16 v[28:31], v[144:147], v[198:201], v[28:31]
	v_mfma_f32_16x16x32_bf16 v[24:27], v[152:155], v[198:201], v[24:27]
	v_mfma_f32_16x16x32_bf16 v[12:15], v[144:147], v[206:209], v[12:15]
	v_mfma_f32_16x16x32_bf16 v[8:11], v[152:155], v[206:209], v[8:11]

.Lmm_11_7:
	s_setprio 0
	s_barrier
	s_add_i32 s63, s63, 2
	s_add_u32 s34, s34, 0x100
	s_addc_u32 s35, s35, 0
	s_add_u32 s58, s58, 0x100
	s_addc_u32 s59, s59, 0
	s_cmp_gt_u32 s63, 13
	s_cbranch_scc0 .LBB0_1835
	s_and_b64 vcc, exec, s[18:19]
	s_cbranch_vccz .LBB0_1838
	s_barrier
.LBB0_1838:
	s_bitcmp1_b32 s101, 6
	s_cbranch_scc1 .Lqepi_11
	v_and_b32_e32 v146, 63, v180
	v_and_b32_e32 v147, 15, v180
	v_bfe_u32 v148, v180, 4, 2
	v_lshrrev_b32_e32 v149, 6, v180
	v_lshlrev_b32_e32 v149, 12, v149
	v_add_u32_e32 v149, 0x20000, v149
	v_and_b32_e32 v150, 7, v147
	v_xor_b32_e32 v150, v148, v150
	v_lshlrev_b32_e32 v150, 4, v150
	v_lshl_add_u32 v150, v147, 8, v150
	v_add_u32_e32 v140, v149, v150
	v_xor_b32_e32 v141, 64, v140
	v_lshrrev_b32_e32 v151, 2, v146
	v_and_b32_e32 v152, 3, v146
	v_and_b32_e32 v153, 7, v151
	v_lshlrev_b32_e32 v154, 1, v152
	v_xor_b32_e32 v154, v154, v153
	v_lshlrev_b32_e32 v154, 4, v154
	v_lshl_add_u32 v154, v151, 8, v154
	v_add_u32_e32 v142, v149, v154
	v_xor_b32_e32 v143, 16, v142
	s_lshl_b32 s21, s30, 8
	s_add_i32 s21, s21, s51
	v_add_u32_e32 v155, s21, v151
	v_lshlrev_b32_e32 v145, 2, v155
	v_lshlrev_b32_e32 v155, 11, v155
	s_lshl_b32 s21, s28, 8
	s_add_i32 s21, s21, s52
	v_lshl_add_u32 v156, v152, 3, s21
	v_lshl_add_u32 v144, v156, 1, v155
	v_cmp_eq_u32_e32 vcc, 0, v152
	s_mov_b64 s[98:99], s[10:11]
	global_load_dwordx4 v[188:191], v144, s[98:99]
	global_load_dwordx4 v[192:195], v144, s[98:99] offset:256
	s_add_u32 s98, s98, 0x8000
	s_addc_u32 s99, s99, 0
	global_load_dwordx4 v[196:199], v144, s[98:99]
	global_load_dwordx4 v[200:203], v144, s[98:99] offset:256
	s_add_u32 s98, s98, 0x8000
	s_addc_u32 s99, s99, 0
	global_load_dwordx4 v[204:207], v144, s[98:99]
	global_load_dwordx4 v[208:211], v144, s[98:99] offset:256
	s_add_u32 s98, s98, 0x8000
	s_addc_u32 s99, s99, 0
	global_load_dwordx4 v[212:215], v144, s[98:99]
	global_load_dwordx4 v[216:219], v144, s[98:99] offset:256
	s_add_u32 s98, s98, 0x28000
	s_addc_u32 s99, s99, 0
	global_load_dwordx4 v[220:223], v144, s[98:99]
	global_load_dwordx4 v[224:227], v144, s[98:99] offset:256
	s_add_u32 s98, s98, 0x8000
	s_addc_u32 s99, s99, 0
	global_load_dwordx4 v[228:231], v144, s[98:99]
	global_load_dwordx4 v[232:235], v144, s[98:99] offset:256
	s_add_u32 s98, s98, 0x8000
	s_addc_u32 s99, s99, 0
	global_load_dwordx4 v[236:239], v144, s[98:99]
	global_load_dwordx4 v[240:243], v144, s[98:99] offset:256
	s_add_u32 s98, s98, 0x8000
	s_addc_u32 s99, s99, 0
	global_load_dwordx4 v[244:247], v144, s[98:99]
	global_load_dwordx4 v[248:251], v144, s[98:99] offset:256
	s_mov_b64 s[28:29], exec
	s_mov_b64 s[98:99], s[10:11]
	ds_write_b128 v140, v[124:127]
	ds_write_b128 v141, v[120:123]
	ds_write_b128 v140, v[116:119] offset:128
	ds_write_b128 v141, v[112:115] offset:128
	s_waitcnt lgkmcnt(0)
	ds_read_b128 v[146:149], v142
	ds_read_b128 v[150:153], v143
	ds_read_b128 v[154:157], v142 offset:128
	ds_read_b128 v[158:161], v143 offset:128
	s_waitcnt lgkmcnt(0)
	ds_write_b128 v140, v[108:111]
	ds_write_b128 v141, v[104:107]
	ds_write_b128 v140, v[100:103] offset:128
	ds_write_b128 v141, v[96:99] offset:128
	s_waitcnt vmcnt(14)
	v_lshlrev_b32_e32 v162, 16, v188
	v_and_b32_e32 v163, 0xffff0000, v188
	v_lshlrev_b32_e32 v164, 16, v189
	v_and_b32_e32 v165, 0xffff0000, v189
	v_lshlrev_b32_e32 v166, 16, v190
	v_and_b32_e32 v167, 0xffff0000, v190
	v_lshlrev_b32_e32 v168, 16, v191
	v_and_b32_e32 v169, 0xffff0000, v191
	v_pk_add_f32 v[146:147], v[146:147], v[162:163]
	v_pk_add_f32 v[148:149], v[148:149], v[164:165]
	v_pk_add_f32 v[150:151], v[150:151], v[166:167]
	v_pk_add_f32 v[152:153], v[152:153], v[168:169]
	v_pk_mul_f32 v[170:171], v[146:147], v[146:147]
	v_pk_fma_f32 v[170:171], v[148:149], v[148:149], v[170:171]
	v_pk_fma_f32 v[170:171], v[150:151], v[150:151], v[170:171]
	v_pk_fma_f32 v[170:171], v[152:153], v[152:153], v[170:171]
	v_cvt_pk_bf16_f32 v172, v146, v147
	v_cvt_pk_bf16_f32 v173, v148, v149
	v_cvt_pk_bf16_f32 v174, v150, v151
	v_cvt_pk_bf16_f32 v175, v152, v153
	global_store_dwordx4 v144, v[172:175], s[98:99]
	v_lshlrev_b32_e32 v162, 16, v192
	v_and_b32_e32 v163, 0xffff0000, v192
	v_lshlrev_b32_e32 v164, 16, v193
	v_and_b32_e32 v165, 0xffff0000, v193
	v_lshlrev_b32_e32 v166, 16, v194
	v_and_b32_e32 v167, 0xffff0000, v194
	v_lshlrev_b32_e32 v168, 16, v195
	v_and_b32_e32 v169, 0xffff0000, v195
	v_pk_add_f32 v[154:155], v[154:155], v[162:163]
	v_pk_add_f32 v[156:157], v[156:157], v[164:165]
	v_pk_add_f32 v[158:159], v[158:159], v[166:167]
	v_pk_add_f32 v[160:161], v[160:161], v[168:169]
	v_pk_fma_f32 v[170:171], v[154:155], v[154:155], v[170:171]
	v_pk_fma_f32 v[170:171], v[156:157], v[156:157], v[170:171]
	v_pk_fma_f32 v[170:171], v[158:159], v[158:159], v[170:171]
	v_pk_fma_f32 v[170:171], v[160:161], v[160:161], v[170:171]
	v_cvt_pk_bf16_f32 v176, v154, v155
	v_cvt_pk_bf16_f32 v177, v156, v157
	v_cvt_pk_bf16_f32 v178, v158, v159
	v_cvt_pk_bf16_f32 v179, v160, v161
	global_store_dwordx4 v144, v[176:179], s[98:99] offset:256
	v_add_f32_e32 v162, v170, v171
	s_nop 1
	v_add_f32_dpp v163, v162, v162 quad_perm:[1,0,3,2] row_mask:0xf bank_mask:0xf
	s_nop 1
	v_add_f32_dpp v164, v163, v163 quad_perm:[2,3,0,1] row_mask:0xf bank_mask:0xf
	s_mov_b64 exec, vcc
	global_atomic_add_f32 v145, v164, s[12:13] offset:0
	s_mov_b64 exec, s[28:29]
	s_add_u32 s98, s98, 0x8000
	s_addc_u32 s99, s99, 0
	s_waitcnt lgkmcnt(0)
	ds_read_b128 v[146:149], v142
	ds_read_b128 v[150:153], v143
	ds_read_b128 v[154:157], v142 offset:128
	ds_read_b128 v[158:161], v143 offset:128
	s_waitcnt lgkmcnt(0)
	ds_write_b128 v140, v[92:95]
	ds_write_b128 v141, v[88:91]
	ds_write_b128 v140, v[84:87] offset:128
	ds_write_b128 v141, v[80:83] offset:128
	s_waitcnt vmcnt(15)
	v_lshlrev_b32_e32 v162, 16, v196
	v_and_b32_e32 v163, 0xffff0000, v196
	v_lshlrev_b32_e32 v164, 16, v197
	v_and_b32_e32 v165, 0xffff0000, v197
	v_lshlrev_b32_e32 v166, 16, v198
	v_and_b32_e32 v167, 0xffff0000, v198
	v_lshlrev_b32_e32 v168, 16, v199
	v_and_b32_e32 v169, 0xffff0000, v199
	v_pk_add_f32 v[146:147], v[146:147], v[162:163]
	v_pk_add_f32 v[148:149], v[148:149], v[164:165]
	v_pk_add_f32 v[150:151], v[150:151], v[166:167]
	v_pk_add_f32 v[152:153], v[152:153], v[168:169]
	v_pk_mul_f32 v[170:171], v[146:147], v[146:147]
	v_pk_fma_f32 v[170:171], v[148:149], v[148:149], v[170:171]
	v_pk_fma_f32 v[170:171], v[150:151], v[150:151], v[170:171]
	v_pk_fma_f32 v[170:171], v[152:153], v[152:153], v[170:171]
	v_cvt_pk_bf16_f32 v172, v146, v147
	v_cvt_pk_bf16_f32 v173, v148, v149
	v_cvt_pk_bf16_f32 v174, v150, v151
	v_cvt_pk_bf16_f32 v175, v152, v153
	global_store_dwordx4 v144, v[172:175], s[98:99]
	v_lshlrev_b32_e32 v162, 16, v200
	v_and_b32_e32 v163, 0xffff0000, v200
	v_lshlrev_b32_e32 v164, 16, v201
	v_and_b32_e32 v165, 0xffff0000, v201
	v_lshlrev_b32_e32 v166, 16, v202
	v_and_b32_e32 v167, 0xffff0000, v202
	v_lshlrev_b32_e32 v168, 16, v203
	v_and_b32_e32 v169, 0xffff0000, v203
	v_pk_add_f32 v[154:155], v[154:155], v[162:163]
	v_pk_add_f32 v[156:157], v[156:157], v[164:165]
	v_pk_add_f32 v[158:159], v[158:159], v[166:167]
	v_pk_add_f32 v[160:161], v[160:161], v[168:169]
	v_pk_fma_f32 v[170:171], v[154:155], v[154:155], v[170:171]
	v_pk_fma_f32 v[170:171], v[156:157], v[156:157], v[170:171]
	v_pk_fma_f32 v[170:171], v[158:159], v[158:159], v[170:171]
	v_pk_fma_f32 v[170:171], v[160:161], v[160:161], v[170:171]
	v_cvt_pk_bf16_f32 v176, v154, v155
	v_cvt_pk_bf16_f32 v177, v156, v157
	v_cvt_pk_bf16_f32 v178, v158, v159
	v_cvt_pk_bf16_f32 v179, v160, v161
	global_store_dwordx4 v144, v[176:179], s[98:99] offset:256
	v_add_f32_e32 v162, v170, v171
	s_nop 1
	v_add_f32_dpp v163, v162, v162 quad_perm:[1,0,3,2] row_mask:0xf bank_mask:0xf
	s_nop 1
	v_add_f32_dpp v164, v163, v163 quad_perm:[2,3,0,1] row_mask:0xf bank_mask:0xf
	s_mov_b64 exec, vcc
	global_atomic_add_f32 v145, v164, s[12:13] offset:64
	s_mov_b64 exec, s[28:29]
	s_add_u32 s98, s98, 0x8000
	s_addc_u32 s99, s99, 0
	s_waitcnt lgkmcnt(0)
	ds_read_b128 v[146:149], v142
	ds_read_b128 v[150:153], v143
	ds_read_b128 v[154:157], v142 offset:128
	ds_read_b128 v[158:161], v143 offset:128
	s_waitcnt lgkmcnt(0)
	ds_write_b128 v140, v[76:79]
	ds_write_b128 v141, v[72:75]
	ds_write_b128 v140, v[68:71] offset:128
	ds_write_b128 v141, v[64:67] offset:128
	s_waitcnt vmcnt(16)
	v_lshlrev_b32_e32 v162, 16, v204
	v_and_b32_e32 v163, 0xffff0000, v204
	v_lshlrev_b32_e32 v164, 16, v205
	v_and_b32_e32 v165, 0xffff0000, v205
	v_lshlrev_b32_e32 v166, 16, v206
	v_and_b32_e32 v167, 0xffff0000, v206
	v_lshlrev_b32_e32 v168, 16, v207
	v_and_b32_e32 v169, 0xffff0000, v207
	v_pk_add_f32 v[146:147], v[146:147], v[162:163]
	v_pk_add_f32 v[148:149], v[148:149], v[164:165]
	v_pk_add_f32 v[150:151], v[150:151], v[166:167]
	v_pk_add_f32 v[152:153], v[152:153], v[168:169]
	v_pk_mul_f32 v[170:171], v[146:147], v[146:147]
	v_pk_fma_f32 v[170:171], v[148:149], v[148:149], v[170:171]
	v_pk_fma_f32 v[170:171], v[150:151], v[150:151], v[170:171]
	v_pk_fma_f32 v[170:171], v[152:153], v[152:153], v[170:171]
	v_cvt_pk_bf16_f32 v172, v146, v147
	v_cvt_pk_bf16_f32 v173, v148, v149
	v_cvt_pk_bf16_f32 v174, v150, v151
	v_cvt_pk_bf16_f32 v175, v152, v153
	global_store_dwordx4 v144, v[172:175], s[98:99]
	v_lshlrev_b32_e32 v162, 16, v208
	v_and_b32_e32 v163, 0xffff0000, v208
	v_lshlrev_b32_e32 v164, 16, v209
	v_and_b32_e32 v165, 0xffff0000, v209
	v_lshlrev_b32_e32 v166, 16, v210
	v_and_b32_e32 v167, 0xffff0000, v210
	v_lshlrev_b32_e32 v168, 16, v211
	v_and_b32_e32 v169, 0xffff0000, v211
	v_pk_add_f32 v[154:155], v[154:155], v[162:163]
	v_pk_add_f32 v[156:157], v[156:157], v[164:165]
	v_pk_add_f32 v[158:159], v[158:159], v[166:167]
	v_pk_add_f32 v[160:161], v[160:161], v[168:169]
	v_pk_fma_f32 v[170:171], v[154:155], v[154:155], v[170:171]
	v_pk_fma_f32 v[170:171], v[156:157], v[156:157], v[170:171]
	v_pk_fma_f32 v[170:171], v[158:159], v[158:159], v[170:171]
	v_pk_fma_f32 v[170:171], v[160:161], v[160:161], v[170:171]
	v_cvt_pk_bf16_f32 v176, v154, v155
	v_cvt_pk_bf16_f32 v177, v156, v157
	v_cvt_pk_bf16_f32 v178, v158, v159
	v_cvt_pk_bf16_f32 v179, v160, v161
	global_store_dwordx4 v144, v[176:179], s[98:99] offset:256
	v_add_f32_e32 v162, v170, v171
	s_nop 1
	v_add_f32_dpp v163, v162, v162 quad_perm:[1,0,3,2] row_mask:0xf bank_mask:0xf
	s_nop 1
	v_add_f32_dpp v164, v163, v163 quad_perm:[2,3,0,1] row_mask:0xf bank_mask:0xf
	s_mov_b64 exec, vcc
	global_atomic_add_f32 v145, v164, s[12:13] offset:128
	s_mov_b64 exec, s[28:29]
	s_add_u32 s98, s98, 0x8000
	s_addc_u32 s99, s99, 0
	s_waitcnt lgkmcnt(0)
	ds_read_b128 v[146:149], v142
	ds_read_b128 v[150:153], v143
	ds_read_b128 v[154:157], v142 offset:128
	ds_read_b128 v[158:161], v143 offset:128
	s_waitcnt lgkmcnt(0)
	ds_write_b128 v140, v[60:63]
	ds_write_b128 v141, v[56:59]
	ds_write_b128 v140, v[52:55] offset:128
	ds_write_b128 v141, v[48:51] offset:128
	s_waitcnt vmcnt(17)
	v_lshlrev_b32_e32 v162, 16, v212
	v_and_b32_e32 v163, 0xffff0000, v212
	v_lshlrev_b32_e32 v164, 16, v213
	v_and_b32_e32 v165, 0xffff0000, v213
	v_lshlrev_b32_e32 v166, 16, v214
	v_and_b32_e32 v167, 0xffff0000, v214
	v_lshlrev_b32_e32 v168, 16, v215
	v_and_b32_e32 v169, 0xffff0000, v215
	v_pk_add_f32 v[146:147], v[146:147], v[162:163]
	v_pk_add_f32 v[148:149], v[148:149], v[164:165]
	v_pk_add_f32 v[150:151], v[150:151], v[166:167]
	v_pk_add_f32 v[152:153], v[152:153], v[168:169]
	v_pk_mul_f32 v[170:171], v[146:147], v[146:147]
	v_pk_fma_f32 v[170:171], v[148:149], v[148:149], v[170:171]
	v_pk_fma_f32 v[170:171], v[150:151], v[150:151], v[170:171]
	v_pk_fma_f32 v[170:171], v[152:153], v[152:153], v[170:171]
	v_cvt_pk_bf16_f32 v172, v146, v147
	v_cvt_pk_bf16_f32 v173, v148, v149
	v_cvt_pk_bf16_f32 v174, v150, v151
	v_cvt_pk_bf16_f32 v175, v152, v153
	global_store_dwordx4 v144, v[172:175], s[98:99]
	v_lshlrev_b32_e32 v162, 16, v216
	v_and_b32_e32 v163, 0xffff0000, v216
	v_lshlrev_b32_e32 v164, 16, v217
	v_and_b32_e32 v165, 0xffff0000, v217
	v_lshlrev_b32_e32 v166, 16, v218
	v_and_b32_e32 v167, 0xffff0000, v218
	v_lshlrev_b32_e32 v168, 16, v219
	v_and_b32_e32 v169, 0xffff0000, v219
	v_pk_add_f32 v[154:155], v[154:155], v[162:163]
	v_pk_add_f32 v[156:157], v[156:157], v[164:165]
	v_pk_add_f32 v[158:159], v[158:159], v[166:167]
	v_pk_add_f32 v[160:161], v[160:161], v[168:169]
	v_pk_fma_f32 v[170:171], v[154:155], v[154:155], v[170:171]
	v_pk_fma_f32 v[170:171], v[156:157], v[156:157], v[170:171]
	v_pk_fma_f32 v[170:171], v[158:159], v[158:159], v[170:171]
	v_pk_fma_f32 v[170:171], v[160:161], v[160:161], v[170:171]
	v_cvt_pk_bf16_f32 v176, v154, v155
	v_cvt_pk_bf16_f32 v177, v156, v157
	v_cvt_pk_bf16_f32 v178, v158, v159
	v_cvt_pk_bf16_f32 v179, v160, v161
	global_store_dwordx4 v144, v[176:179], s[98:99] offset:256
	v_add_f32_e32 v162, v170, v171
	s_nop 1
	v_add_f32_dpp v163, v162, v162 quad_perm:[1,0,3,2] row_mask:0xf bank_mask:0xf
	s_nop 1
	v_add_f32_dpp v164, v163, v163 quad_perm:[2,3,0,1] row_mask:0xf bank_mask:0xf
	s_mov_b64 exec, vcc
	global_atomic_add_f32 v145, v164, s[12:13] offset:192
	s_mov_b64 exec, s[28:29]
	s_add_u32 s98, s98, 0x28000
	s_addc_u32 s99, s99, 0
	s_waitcnt lgkmcnt(0)
	ds_read_b128 v[146:149], v142
	ds_read_b128 v[150:153], v143
	ds_read_b128 v[154:157], v142 offset:128
	ds_read_b128 v[158:161], v143 offset:128
	s_waitcnt lgkmcnt(0)
	ds_write_b128 v140, v[44:47]
	ds_write_b128 v141, v[40:43]
	ds_write_b128 v140, v[36:39] offset:128
	ds_write_b128 v141, v[32:35] offset:128
	s_waitcnt vmcnt(18)
	v_lshlrev_b32_e32 v162, 16, v220
	v_and_b32_e32 v163, 0xffff0000, v220
	v_lshlrev_b32_e32 v164, 16, v221
	v_and_b32_e32 v165, 0xffff0000, v221
	v_lshlrev_b32_e32 v166, 16, v222
	v_and_b32_e32 v167, 0xffff0000, v222
	v_lshlrev_b32_e32 v168, 16, v223
	v_and_b32_e32 v169, 0xffff0000, v223
	v_pk_add_f32 v[146:147], v[146:147], v[162:163]
	v_pk_add_f32 v[148:149], v[148:149], v[164:165]
	v_pk_add_f32 v[150:151], v[150:151], v[166:167]
	v_pk_add_f32 v[152:153], v[152:153], v[168:169]
	v_pk_mul_f32 v[170:171], v[146:147], v[146:147]
	v_pk_fma_f32 v[170:171], v[148:149], v[148:149], v[170:171]
	v_pk_fma_f32 v[170:171], v[150:151], v[150:151], v[170:171]
	v_pk_fma_f32 v[170:171], v[152:153], v[152:153], v[170:171]
	v_cvt_pk_bf16_f32 v172, v146, v147
	v_cvt_pk_bf16_f32 v173, v148, v149
	v_cvt_pk_bf16_f32 v174, v150, v151
	v_cvt_pk_bf16_f32 v175, v152, v153
	global_store_dwordx4 v144, v[172:175], s[98:99]
	v_lshlrev_b32_e32 v162, 16, v224
	v_and_b32_e32 v163, 0xffff0000, v224
	v_lshlrev_b32_e32 v164, 16, v225
	v_and_b32_e32 v165, 0xffff0000, v225
	v_lshlrev_b32_e32 v166, 16, v226
	v_and_b32_e32 v167, 0xffff0000, v226
	v_lshlrev_b32_e32 v168, 16, v227
	v_and_b32_e32 v169, 0xffff0000, v227
	v_pk_add_f32 v[154:155], v[154:155], v[162:163]
	v_pk_add_f32 v[156:157], v[156:157], v[164:165]
	v_pk_add_f32 v[158:159], v[158:159], v[166:167]
	v_pk_add_f32 v[160:161], v[160:161], v[168:169]
	v_pk_fma_f32 v[170:171], v[154:155], v[154:155], v[170:171]
	v_pk_fma_f32 v[170:171], v[156:157], v[156:157], v[170:171]
	v_pk_fma_f32 v[170:171], v[158:159], v[158:159], v[170:171]
	v_pk_fma_f32 v[170:171], v[160:161], v[160:161], v[170:171]
	v_cvt_pk_bf16_f32 v176, v154, v155
	v_cvt_pk_bf16_f32 v177, v156, v157
	v_cvt_pk_bf16_f32 v178, v158, v159
	v_cvt_pk_bf16_f32 v179, v160, v161
	global_store_dwordx4 v144, v[176:179], s[98:99] offset:256
	v_add_f32_e32 v162, v170, v171
	s_nop 1
	v_add_f32_dpp v163, v162, v162 quad_perm:[1,0,3,2] row_mask:0xf bank_mask:0xf
	s_nop 1
	v_add_f32_dpp v164, v163, v163 quad_perm:[2,3,0,1] row_mask:0xf bank_mask:0xf
	s_mov_b64 exec, vcc
	global_atomic_add_f32 v145, v164, s[12:13] offset:512
	s_mov_b64 exec, s[28:29]
	s_add_u32 s98, s98, 0x8000
	s_addc_u32 s99, s99, 0
	s_waitcnt lgkmcnt(0)
	ds_read_b128 v[146:149], v142
	ds_read_b128 v[150:153], v143
	ds_read_b128 v[154:157], v142 offset:128
	ds_read_b128 v[158:161], v143 offset:128
	s_waitcnt lgkmcnt(0)
	ds_write_b128 v140, v[28:31]
	ds_write_b128 v141, v[24:27]
	ds_write_b128 v140, v[20:23] offset:128
	ds_write_b128 v141, v[16:19] offset:128
	s_waitcnt vmcnt(19)
	v_lshlrev_b32_e32 v162, 16, v228
	v_and_b32_e32 v163, 0xffff0000, v228
	v_lshlrev_b32_e32 v164, 16, v229
	v_and_b32_e32 v165, 0xffff0000, v229
	v_lshlrev_b32_e32 v166, 16, v230
	v_and_b32_e32 v167, 0xffff0000, v230
	v_lshlrev_b32_e32 v168, 16, v231
	v_and_b32_e32 v169, 0xffff0000, v231
	v_pk_add_f32 v[146:147], v[146:147], v[162:163]
	v_pk_add_f32 v[148:149], v[148:149], v[164:165]
	v_pk_add_f32 v[150:151], v[150:151], v[166:167]
	v_pk_add_f32 v[152:153], v[152:153], v[168:169]
	v_pk_mul_f32 v[170:171], v[146:147], v[146:147]
	v_pk_fma_f32 v[170:171], v[148:149], v[148:149], v[170:171]
	v_pk_fma_f32 v[170:171], v[150:151], v[150:151], v[170:171]
	v_pk_fma_f32 v[170:171], v[152:153], v[152:153], v[170:171]
	v_cvt_pk_bf16_f32 v172, v146, v147
	v_cvt_pk_bf16_f32 v173, v148, v149
	v_cvt_pk_bf16_f32 v174, v150, v151
	v_cvt_pk_bf16_f32 v175, v152, v153
	global_store_dwordx4 v144, v[172:175], s[98:99]
	v_lshlrev_b32_e32 v162, 16, v232
	v_and_b32_e32 v163, 0xffff0000, v232
	v_lshlrev_b32_e32 v164, 16, v233
	v_and_b32_e32 v165, 0xffff0000, v233
	v_lshlrev_b32_e32 v166, 16, v234
	v_and_b32_e32 v167, 0xffff0000, v234
	v_lshlrev_b32_e32 v168, 16, v235
	v_and_b32_e32 v169, 0xffff0000, v235
	v_pk_add_f32 v[154:155], v[154:155], v[162:163]
	v_pk_add_f32 v[156:157], v[156:157], v[164:165]
	v_pk_add_f32 v[158:159], v[158:159], v[166:167]
	v_pk_add_f32 v[160:161], v[160:161], v[168:169]
	v_pk_fma_f32 v[170:171], v[154:155], v[154:155], v[170:171]
	v_pk_fma_f32 v[170:171], v[156:157], v[156:157], v[170:171]
	v_pk_fma_f32 v[170:171], v[158:159], v[158:159], v[170:171]
	v_pk_fma_f32 v[170:171], v[160:161], v[160:161], v[170:171]
	v_cvt_pk_bf16_f32 v176, v154, v155
	v_cvt_pk_bf16_f32 v177, v156, v157
	v_cvt_pk_bf16_f32 v178, v158, v159
	v_cvt_pk_bf16_f32 v179, v160, v161
	global_store_dwordx4 v144, v[176:179], s[98:99] offset:256
	v_add_f32_e32 v162, v170, v171
	s_nop 1
	v_add_f32_dpp v163, v162, v162 quad_perm:[1,0,3,2] row_mask:0xf bank_mask:0xf
	s_nop 1
	v_add_f32_dpp v164, v163, v163 quad_perm:[2,3,0,1] row_mask:0xf bank_mask:0xf
	s_mov_b64 exec, vcc
	global_atomic_add_f32 v145, v164, s[12:13] offset:576
	s_mov_b64 exec, s[28:29]
	s_add_u32 s98, s98, 0x8000
	s_addc_u32 s99, s99, 0
	s_waitcnt lgkmcnt(0)
	ds_read_b128 v[146:149], v142
	ds_read_b128 v[150:153], v143
	ds_read_b128 v[154:157], v142 offset:128
	ds_read_b128 v[158:161], v143 offset:128
	s_waitcnt lgkmcnt(0)
	ds_write_b128 v140, v[12:15]
	ds_write_b128 v141, v[8:11]
	ds_write_b128 v140, v[4:7] offset:128
	ds_write_b128 v141, v[0:3] offset:128
	s_waitcnt vmcnt(20)
	v_lshlrev_b32_e32 v162, 16, v236
	v_and_b32_e32 v163, 0xffff0000, v236
	v_lshlrev_b32_e32 v164, 16, v237
	v_and_b32_e32 v165, 0xffff0000, v237
	v_lshlrev_b32_e32 v166, 16, v238
	v_and_b32_e32 v167, 0xffff0000, v238
	v_lshlrev_b32_e32 v168, 16, v239
	v_and_b32_e32 v169, 0xffff0000, v239
	v_pk_add_f32 v[146:147], v[146:147], v[162:163]
	v_pk_add_f32 v[148:149], v[148:149], v[164:165]
	v_pk_add_f32 v[150:151], v[150:151], v[166:167]
	v_pk_add_f32 v[152:153], v[152:153], v[168:169]
	v_pk_mul_f32 v[170:171], v[146:147], v[146:147]
	v_pk_fma_f32 v[170:171], v[148:149], v[148:149], v[170:171]
	v_pk_fma_f32 v[170:171], v[150:151], v[150:151], v[170:171]
	v_pk_fma_f32 v[170:171], v[152:153], v[152:153], v[170:171]
	v_cvt_pk_bf16_f32 v172, v146, v147
	v_cvt_pk_bf16_f32 v173, v148, v149
	v_cvt_pk_bf16_f32 v174, v150, v151
	v_cvt_pk_bf16_f32 v175, v152, v153
	global_store_dwordx4 v144, v[172:175], s[98:99]
	v_lshlrev_b32_e32 v162, 16, v240
	v_and_b32_e32 v163, 0xffff0000, v240
	v_lshlrev_b32_e32 v164, 16, v241
	v_and_b32_e32 v165, 0xffff0000, v241
	v_lshlrev_b32_e32 v166, 16, v242
	v_and_b32_e32 v167, 0xffff0000, v242
	v_lshlrev_b32_e32 v168, 16, v243
	v_and_b32_e32 v169, 0xffff0000, v243
	v_pk_add_f32 v[154:155], v[154:155], v[162:163]
	v_pk_add_f32 v[156:157], v[156:157], v[164:165]
	v_pk_add_f32 v[158:159], v[158:159], v[166:167]
	v_pk_add_f32 v[160:161], v[160:161], v[168:169]
	v_pk_fma_f32 v[170:171], v[154:155], v[154:155], v[170:171]
	v_pk_fma_f32 v[170:171], v[156:157], v[156:157], v[170:171]
	v_pk_fma_f32 v[170:171], v[158:159], v[158:159], v[170:171]
	v_pk_fma_f32 v[170:171], v[160:161], v[160:161], v[170:171]
	v_cvt_pk_bf16_f32 v176, v154, v155
	v_cvt_pk_bf16_f32 v177, v156, v157
	v_cvt_pk_bf16_f32 v178, v158, v159
	v_cvt_pk_bf16_f32 v179, v160, v161
	global_store_dwordx4 v144, v[176:179], s[98:99] offset:256
	v_add_f32_e32 v162, v170, v171
	s_nop 1
	v_add_f32_dpp v163, v162, v162 quad_perm:[1,0,3,2] row_mask:0xf bank_mask:0xf
	s_nop 1
	v_add_f32_dpp v164, v163, v163 quad_perm:[2,3,0,1] row_mask:0xf bank_mask:0xf
	s_mov_b64 exec, vcc
	global_atomic_add_f32 v145, v164, s[12:13] offset:640
	s_mov_b64 exec, s[28:29]
	s_add_u32 s98, s98, 0x8000
	s_addc_u32 s99, s99, 0
	s_waitcnt lgkmcnt(0)
	ds_read_b128 v[146:149], v142
	ds_read_b128 v[150:153], v143
	ds_read_b128 v[154:157], v142 offset:128
	ds_read_b128 v[158:161], v143 offset:128
	s_waitcnt lgkmcnt(0)
	s_waitcnt vmcnt(21)
	v_lshlrev_b32_e32 v162, 16, v244
	v_and_b32_e32 v163, 0xffff0000, v244
	v_lshlrev_b32_e32 v164, 16, v245
	v_and_b32_e32 v165, 0xffff0000, v245
	v_lshlrev_b32_e32 v166, 16, v246
	v_and_b32_e32 v167, 0xffff0000, v246
	v_lshlrev_b32_e32 v168, 16, v247
	v_and_b32_e32 v169, 0xffff0000, v247
	v_pk_add_f32 v[146:147], v[146:147], v[162:163]
	v_pk_add_f32 v[148:149], v[148:149], v[164:165]
	v_pk_add_f32 v[150:151], v[150:151], v[166:167]
	v_pk_add_f32 v[152:153], v[152:153], v[168:169]
	v_pk_mul_f32 v[170:171], v[146:147], v[146:147]
	v_pk_fma_f32 v[170:171], v[148:149], v[148:149], v[170:171]
	v_pk_fma_f32 v[170:171], v[150:151], v[150:151], v[170:171]
	v_pk_fma_f32 v[170:171], v[152:153], v[152:153], v[170:171]
	v_cvt_pk_bf16_f32 v172, v146, v147
	v_cvt_pk_bf16_f32 v173, v148, v149
	v_cvt_pk_bf16_f32 v174, v150, v151
	v_cvt_pk_bf16_f32 v175, v152, v153
	global_store_dwordx4 v144, v[172:175], s[98:99]
	v_lshlrev_b32_e32 v162, 16, v248
	v_and_b32_e32 v163, 0xffff0000, v248
	v_lshlrev_b32_e32 v164, 16, v249
	v_and_b32_e32 v165, 0xffff0000, v249
	v_lshlrev_b32_e32 v166, 16, v250
	v_and_b32_e32 v167, 0xffff0000, v250
	v_lshlrev_b32_e32 v168, 16, v251
	v_and_b32_e32 v169, 0xffff0000, v251
	v_pk_add_f32 v[154:155], v[154:155], v[162:163]
	v_pk_add_f32 v[156:157], v[156:157], v[164:165]
	v_pk_add_f32 v[158:159], v[158:159], v[166:167]
	v_pk_add_f32 v[160:161], v[160:161], v[168:169]
	v_pk_fma_f32 v[170:171], v[154:155], v[154:155], v[170:171]
	v_pk_fma_f32 v[170:171], v[156:157], v[156:157], v[170:171]
	v_pk_fma_f32 v[170:171], v[158:159], v[158:159], v[170:171]
	v_pk_fma_f32 v[170:171], v[160:161], v[160:161], v[170:171]
	v_cvt_pk_bf16_f32 v176, v154, v155
	v_cvt_pk_bf16_f32 v177, v156, v157
	v_cvt_pk_bf16_f32 v178, v158, v159
	v_cvt_pk_bf16_f32 v179, v160, v161
	global_store_dwordx4 v144, v[176:179], s[98:99] offset:256
	v_add_f32_e32 v162, v170, v171
	s_nop 1
	v_add_f32_dpp v163, v162, v162 quad_perm:[1,0,3,2] row_mask:0xf bank_mask:0xf
	s_nop 1
	v_add_f32_dpp v164, v163, v163 quad_perm:[2,3,0,1] row_mask:0xf bank_mask:0xf
	s_mov_b64 exec, vcc
	global_atomic_add_f32 v145, v164, s[12:13] offset:704
	s_mov_b64 exec, s[28:29]
	s_branch .Lqepi_end_11

.Lqn_done_ph11:
	v_and_b32_e32 v146, 63, v180
	v_and_b32_e32 v147, 15, v180
	v_bfe_u32 v148, v180, 4, 2
	v_lshrrev_b32_e32 v149, 6, v180
	v_lshlrev_b32_e32 v149, 12, v149
	v_add_u32_e32 v149, 0x20000, v149
	v_and_b32_e32 v150, 7, v147
	v_xor_b32_e32 v150, v148, v150
	v_lshlrev_b32_e32 v150, 4, v150
	v_lshl_add_u32 v150, v147, 8, v150
	v_add_u32_e32 v140, v149, v150
	v_xor_b32_e32 v141, 64, v140
	v_lshrrev_b32_e32 v151, 2, v146
	v_and_b32_e32 v152, 3, v146
	v_and_b32_e32 v153, 7, v151
	v_lshlrev_b32_e32 v154, 1, v152
	v_xor_b32_e32 v154, v154, v153
	v_lshlrev_b32_e32 v154, 4, v154
	v_lshl_add_u32 v154, v151, 8, v154
	v_add_u32_e32 v142, v149, v154
	v_xor_b32_e32 v143, 16, v142
	s_lshr_b32 s99, s98, 1
	s_lshl_b32 s99, s99, 7
	s_lshl_b32 s21, s30, 8
	s_add_i32 s21, s21, s51
	s_add_i32 s21, s21, s99
	v_add_u32_e32 v155, s21, v151
	v_lshlrev_b32_e32 v145, 2, v155
	v_lshlrev_b32_e32 v155, 11, v155
	s_and_b32 s99, s98, 1
	s_lshl_b32 s99, s99, 7
	s_lshl_b32 s21, s28, 8
	s_add_i32 s21, s21, s52
	s_add_i32 s21, s21, s99
	v_lshl_add_u32 v156, v152, 3, s21
	v_lshl_add_u32 v144, v156, 1, v155
	v_cmp_eq_u32_e32 vcc, 0, v152
	s_mov_b64 s[98:99], s[10:11]
	global_load_dwordx4 v[188:191], v144, s[98:99]
	s_add_u32 s98, s98, 0x8000
	s_addc_u32 s99, s99, 0
	global_load_dwordx4 v[192:195], v144, s[98:99]
	s_add_u32 s98, s98, 0x8000
	s_addc_u32 s99, s99, 0
	global_load_dwordx4 v[196:199], v144, s[98:99]
	s_add_u32 s98, s98, 0x8000
	s_addc_u32 s99, s99, 0
	global_load_dwordx4 v[200:203], v144, s[98:99]
	s_mov_b64 s[28:29], exec
	s_mov_b64 s[98:99], s[10:11]
	ds_write_b128 v140, v[124:127]
	ds_write_b128 v141, v[120:123]
	s_waitcnt lgkmcnt(0)
	ds_read_b128 v[146:149], v142
	ds_read_b128 v[150:153], v143
	s_waitcnt vmcnt(0)
	s_waitcnt lgkmcnt(0)
	v_lshlrev_b32_e32 v162, 16, v188
	v_and_b32_e32 v163, 0xffff0000, v188
	v_lshlrev_b32_e32 v164, 16, v189
	v_and_b32_e32 v165, 0xffff0000, v189
	v_lshlrev_b32_e32 v166, 16, v190
	v_and_b32_e32 v167, 0xffff0000, v190
	v_lshlrev_b32_e32 v168, 16, v191
	v_and_b32_e32 v169, 0xffff0000, v191
	v_pk_add_f32 v[146:147], v[146:147], v[162:163]
	v_pk_add_f32 v[148:149], v[148:149], v[164:165]
	v_pk_add_f32 v[150:151], v[150:151], v[166:167]
	v_pk_add_f32 v[152:153], v[152:153], v[168:169]
	v_pk_mul_f32 v[170:171], v[146:147], v[146:147]
	v_pk_fma_f32 v[170:171], v[148:149], v[148:149], v[170:171]
	v_pk_fma_f32 v[170:171], v[150:151], v[150:151], v[170:171]
	v_pk_fma_f32 v[170:171], v[152:153], v[152:153], v[170:171]
	v_cvt_pk_bf16_f32 v172, v146, v147
	v_cvt_pk_bf16_f32 v173, v148, v149
	v_cvt_pk_bf16_f32 v174, v150, v151
	v_cvt_pk_bf16_f32 v175, v152, v153
	global_store_dwordx4 v144, v[172:175], s[98:99]
	v_add_f32_e32 v162, v170, v171
	s_nop 1
	v_add_f32_dpp v163, v162, v162 quad_perm:[1,0,3,2] row_mask:0xf bank_mask:0xf
	s_nop 1
	v_add_f32_dpp v164, v163, v163 quad_perm:[2,3,0,1] row_mask:0xf bank_mask:0xf
	s_mov_b64 exec, vcc
	global_atomic_add_f32 v145, v164, s[12:13] offset:0
	s_mov_b64 exec, s[28:29]
	s_add_u32 s98, s98, 0x8000
	s_addc_u32 s99, s99, 0
	ds_write_b128 v140, v[108:111]
	ds_write_b128 v141, v[104:107]
	s_waitcnt lgkmcnt(0)
	ds_read_b128 v[146:149], v142
	ds_read_b128 v[150:153], v143
	s_waitcnt vmcnt(0)
	s_waitcnt lgkmcnt(0)
	v_lshlrev_b32_e32 v162, 16, v192
	v_and_b32_e32 v163, 0xffff0000, v192
	v_lshlrev_b32_e32 v164, 16, v193
	v_and_b32_e32 v165, 0xffff0000, v193
	v_lshlrev_b32_e32 v166, 16, v194
	v_and_b32_e32 v167, 0xffff0000, v194
	v_lshlrev_b32_e32 v168, 16, v195
	v_and_b32_e32 v169, 0xffff0000, v195
	v_pk_add_f32 v[146:147], v[146:147], v[162:163]
	v_pk_add_f32 v[148:149], v[148:149], v[164:165]
	v_pk_add_f32 v[150:151], v[150:151], v[166:167]
	v_pk_add_f32 v[152:153], v[152:153], v[168:169]
	v_pk_mul_f32 v[170:171], v[146:147], v[146:147]
	v_pk_fma_f32 v[170:171], v[148:149], v[148:149], v[170:171]
	v_pk_fma_f32 v[170:171], v[150:151], v[150:151], v[170:171]
	v_pk_fma_f32 v[170:171], v[152:153], v[152:153], v[170:171]
	v_cvt_pk_bf16_f32 v172, v146, v147
	v_cvt_pk_bf16_f32 v173, v148, v149
	v_cvt_pk_bf16_f32 v174, v150, v151
	v_cvt_pk_bf16_f32 v175, v152, v153
	global_store_dwordx4 v144, v[172:175], s[98:99]
	v_add_f32_e32 v162, v170, v171
	s_nop 1
	v_add_f32_dpp v163, v162, v162 quad_perm:[1,0,3,2] row_mask:0xf bank_mask:0xf
	s_nop 1
	v_add_f32_dpp v164, v163, v163 quad_perm:[2,3,0,1] row_mask:0xf bank_mask:0xf
	s_mov_b64 exec, vcc
	global_atomic_add_f32 v145, v164, s[12:13] offset:64
	s_mov_b64 exec, s[28:29]
	s_add_u32 s98, s98, 0x8000
	s_addc_u32 s99, s99, 0
	ds_write_b128 v140, v[92:95]
	ds_write_b128 v141, v[88:91]
	s_waitcnt lgkmcnt(0)
	ds_read_b128 v[146:149], v142
	ds_read_b128 v[150:153], v143
	s_waitcnt vmcnt(0)
	s_waitcnt lgkmcnt(0)
	v_lshlrev_b32_e32 v162, 16, v196
	v_and_b32_e32 v163, 0xffff0000, v196
	v_lshlrev_b32_e32 v164, 16, v197
	v_and_b32_e32 v165, 0xffff0000, v197
	v_lshlrev_b32_e32 v166, 16, v198
	v_and_b32_e32 v167, 0xffff0000, v198
	v_lshlrev_b32_e32 v168, 16, v199
	v_and_b32_e32 v169, 0xffff0000, v199
	v_pk_add_f32 v[146:147], v[146:147], v[162:163]
	v_pk_add_f32 v[148:149], v[148:149], v[164:165]
	v_pk_add_f32 v[150:151], v[150:151], v[166:167]
	v_pk_add_f32 v[152:153], v[152:153], v[168:169]
	v_pk_mul_f32 v[170:171], v[146:147], v[146:147]
	v_pk_fma_f32 v[170:171], v[148:149], v[148:149], v[170:171]
	v_pk_fma_f32 v[170:171], v[150:151], v[150:151], v[170:171]
	v_pk_fma_f32 v[170:171], v[152:153], v[152:153], v[170:171]
	v_cvt_pk_bf16_f32 v172, v146, v147
	v_cvt_pk_bf16_f32 v173, v148, v149
	v_cvt_pk_bf16_f32 v174, v150, v151
	v_cvt_pk_bf16_f32 v175, v152, v153
	global_store_dwordx4 v144, v[172:175], s[98:99]
	v_add_f32_e32 v162, v170, v171
	s_nop 1
	v_add_f32_dpp v163, v162, v162 quad_perm:[1,0,3,2] row_mask:0xf bank_mask:0xf
	s_nop 1
	v_add_f32_dpp v164, v163, v163 quad_perm:[2,3,0,1] row_mask:0xf bank_mask:0xf
	s_mov_b64 exec, vcc
	global_atomic_add_f32 v145, v164, s[12:13] offset:128
	s_mov_b64 exec, s[28:29]
	s_add_u32 s98, s98, 0x8000
	s_addc_u32 s99, s99, 0
	ds_write_b128 v140, v[76:79]
	ds_write_b128 v141, v[72:75]
	s_waitcnt lgkmcnt(0)
	ds_read_b128 v[146:149], v142
	ds_read_b128 v[150:153], v143
	s_waitcnt vmcnt(0)
	s_waitcnt lgkmcnt(0)
	v_lshlrev_b32_e32 v162, 16, v200
	v_and_b32_e32 v163, 0xffff0000, v200
	v_lshlrev_b32_e32 v164, 16, v201
	v_and_b32_e32 v165, 0xffff0000, v201
	v_lshlrev_b32_e32 v166, 16, v202
	v_and_b32_e32 v167, 0xffff0000, v202
	v_lshlrev_b32_e32 v168, 16, v203
	v_and_b32_e32 v169, 0xffff0000, v203
	v_pk_add_f32 v[146:147], v[146:147], v[162:163]
	v_pk_add_f32 v[148:149], v[148:149], v[164:165]
	v_pk_add_f32 v[150:151], v[150:151], v[166:167]
	v_pk_add_f32 v[152:153], v[152:153], v[168:169]
	v_pk_mul_f32 v[170:171], v[146:147], v[146:147]
	v_pk_fma_f32 v[170:171], v[148:149], v[148:149], v[170:171]
	v_pk_fma_f32 v[170:171], v[150:151], v[150:151], v[170:171]
	v_pk_fma_f32 v[170:171], v[152:153], v[152:153], v[170:171]
	v_cvt_pk_bf16_f32 v172, v146, v147
	v_cvt_pk_bf16_f32 v173, v148, v149
	v_cvt_pk_bf16_f32 v174, v150, v151
	v_cvt_pk_bf16_f32 v175, v152, v153
	global_store_dwordx4 v144, v[172:175], s[98:99]
	v_add_f32_e32 v162, v170, v171
	s_nop 1
	v_add_f32_dpp v163, v162, v162 quad_perm:[1,0,3,2] row_mask:0xf bank_mask:0xf
	s_nop 1
	v_add_f32_dpp v164, v163, v163 quad_perm:[2,3,0,1] row_mask:0xf bank_mask:0xf
	s_mov_b64 exec, vcc
	global_atomic_add_f32 v145, v164, s[12:13] offset:192
	s_mov_b64 exec, s[28:29]
.Lqepi_end_11:
.LBB0_1854:
	s_or_b64 exec, exec, s[28:29]
	s_andn2_b64 vcc, exec, s[6:7]
	s_mov_b64 s[6:7], -1
	s_cbranch_vccnz .LBB0_1827
	s_andn2_b64 vcc, exec, s[8:9]
	s_cbranch_vccnz .LBB0_1826
	s_barrier
	s_branch .LBB0_1826

.LBB0_1900:
	s_and_b64 vcc, exec, s[4:5]
	s_cbranch_vccnz .LBB0_1940
	s_waitcnt lgkmcnt(0)
	v_ashrrev_i32_e32 v1, 31, v8
	v_lshrrev_b32_e32 v1, 26, v1
	v_add_u32_e32 v1, v8, v1
	v_ashrrev_i32_e32 v9, 6, v1
	v_bfe_i32 v1, v8, 27, 1
	v_lshlrev_b32_e32 v0, 4, v8
	v_lshrrev_b32_e32 v1, 22, v1
	v_add_u32_e32 v1, v0, v1
	v_and_b32_e32 v1, 0xfffffc00, v1
	v_sub_u32_e32 v1, v0, v1
	v_lshrrev_b32_e32 v2, 4, v1
	v_bitop3_b32 v2, v2, v1, 32 bitop3:0x6c
	v_ashrrev_i32_e32 v1, 31, v1
	v_lshrrev_b32_e32 v1, 26, v1
	v_lshlrev_b32_e32 v3, 3, v9
	v_add_u32_e32 v1, v2, v1
	v_and_b32_e32 v3, 0xfffff0, v3
	v_ashrrev_i32_e32 v11, 6, v1
	v_add_u32_e32 v1, v11, v3
	v_lshlrev_b32_e32 v3, 5, v9
	v_and_b32_e32 v10, 32, v3
	v_mul_i32_i24_e32 v3, 64, v11
	s_load_dwordx2 s[4:5], s[6:7], 0x120
	v_sub_u32_e32 v2, v2, v3
	v_mov_b32_e32 v3, 1
	s_movk_i32 s6, 0xb00
	v_ashrrev_i16_sdwa v2, v3, sext(v2) dst_sel:DWORD dst_unused:UNUSED_PAD src0_sel:DWORD src1_sel:BYTE_0
	v_mul_lo_u32 v1, v1, s6
	v_bfe_i32 v12, v2, 0, 16
	v_or_b32_e32 v1, v1, v10
	v_add_u32_e32 v0, 0x2000, v0
	v_add_lshl_u32 v128, v1, v12, 1
	v_ashrrev_i32_e32 v1, 31, v0
	v_lshrrev_b32_e32 v1, 22, v1
	v_add_u32_e32 v1, v0, v1
	v_ashrrev_i32_e32 v13, 10, v1
	v_mul_i32_i24_e32 v1, 0x400, v13
	v_sub_u32_e32 v0, v0, v1
	v_lshrrev_b32_e32 v1, 4, v0
	s_waitcnt lgkmcnt(0)
	s_add_u32 s26, s4, 0x17c4b200
	v_bitop3_b32 v0, v1, v0, 32 bitop3:0x6c
	s_addc_u32 s27, s5, 0
	v_ashrrev_i32_e32 v2, 31, v0
	s_add_u32 s28, s4, 0x2880000
	v_lshrrev_b32_e32 v2, 26, v2
	s_addc_u32 s29, s5, 0
	s_ashr_i32 s7, s14, 6
	v_add_u32_e32 v2, v0, v2
	v_lshlrev_b32_e32 v1, 3, v13
	v_ashrrev_i32_e32 v14, 6, v2
	v_and_b32_e32 v2, 0xc0, v2
	s_ashr_i32 s12, s14, 8
	s_lshl_b32 s30, s7, 10
	s_mul_i32 s3, s45, 0x160000
	v_and_b32_e32 v1, 0xfffff0, v1
	v_sub_u32_e32 v0, v0, v2
	s_mul_hi_i32 s2, s45, 0x160000
	s_add_u32 s20, s28, s3
	v_add_u32_e32 v1, v14, v1
	v_lshlrev_b32_e32 v4, 5, v13
	v_ashrrev_i16_sdwa v0, v3, sext(v0) dst_sel:DWORD dst_unused:UNUSED_PAD src0_sel:DWORD src1_sel:BYTE_0
	s_addc_u32 s21, s29, s2
	s_add_i32 s31, s30, 0
	s_waitcnt vmcnt(0)
	v_and_b32_e32 v15, 32, v4
	v_bfe_i32 v16, v0, 0, 16
	v_mul_lo_u32 v0, v1, s6
	s_add_i32 m0, s31, 0x10000
	v_or_b32_e32 v0, v0, v15
	global_load_lds_dwordx4 v128, s[20:21]
	s_add_i32 m0, s31, 0x12000
	v_add_lshl_u32 v130, v0, v16, 1
	s_add_u32 s2, s20, 0xb0000
	global_load_lds_dwordx4 v130, s[20:21]
	s_addc_u32 s3, s21, 0
	s_add_i32 m0, s31, 0x14000
	s_mul_i32 s9, s48, 0x160000
	global_load_lds_dwordx4 v128, s[2:3]
	s_add_i32 m0, s31, 0x16000
	s_mul_hi_i32 s8, s48, 0x160000
	s_add_u32 s18, s26, s9
	s_addc_u32 s19, s27, s8
	s_add_i32 s33, s31, 0x2000
	global_load_lds_dwordx4 v130, s[2:3]
	s_mov_b32 m0, s31
	s_add_u32 s2, s18, 0xb0000
	global_load_lds_dwordx4 v128, s[18:19]
	s_mov_b32 m0, s33
	s_addc_u32 s3, s19, 0
	s_add_i32 s34, s31, 0x4000
	global_load_lds_dwordx4 v130, s[18:19]
	s_mov_b32 m0, s34
	s_add_i32 s35, s31, 0x6000
	global_load_lds_dwordx4 v128, s[2:3]
	s_mov_b32 m0, s35
	v_mov_b32_e32 v129, 0
	global_load_lds_dwordx4 v130, s[2:3]
	v_mov_b32_e32 v131, v129
	s_cmp_eq_u32 s12, 1
	s_mov_b32 s36, 0
	s_mov_b32 s101, 0xf
	s_mov_b32 s100, 0xf
	v_lshl_add_u64 v[6:7], s[20:21], 0, v[128:129]
	v_lshl_add_u64 v[4:5], s[20:21], 0, v[130:131]
	v_lshl_add_u64 v[0:1], s[18:19], 0, v[128:129]
	s_cselect_b64 s[2:3], -1, 0
	s_cmp_lg_u32 s12, 1
	v_lshl_add_u64 v[2:3], s[18:19], 0, v[130:131]
	s_cbranch_scc1 .LBB0_1903
	s_barrier

.LBB0_1905:
	s_mov_b32 s101, s100
	s_andn2_b64 vcc, exec, s[4:5]
	s_mov_b32 s45, s43
	s_mov_b32 s48, s44
	s_mov_b64 s[20:21], s[16:17]
	s_mov_b64 s[18:19], s[6:7]
	s_cbranch_vccz .LBB0_1939
.LBB0_1906:
	s_add_i32 s36, s36, 1
	s_mul_i32 s4, s36, s47
	s_mul_hi_u32 s5, s36, s46
	s_add_i32 s5, s5, s4
	s_mul_i32 s4, s36, s46
	s_add_u32 s4, s4, s94
	s_addc_u32 s5, s5, s95
	s_mov_b32 s100, 0xf
	s_cmp_eq_u32 s46, 0x100
	s_cbranch_scc0 .Lqs_done_13
	s_cmp_eq_u32 s36, 4
	s_cbranch_scc0 .Lqs_done_13
	s_mov_b32 s5, 0
	s_mov_b32 s4, 0x7fffffff
	s_cmp_lt_u32 s94, 16
	s_cbranch_scc0 .Lqs_done_13
	s_lshr_b32 s4, s94, 2
	s_add_i32 s4, s4, 0x400
	s_and_b32 s98, s94, 3
	s_lshl_b32 s100, 1, s98
	s_lshl_b32 s98, s98, 4
	s_or_b32 s100, s100, s98
	s_or_b32 s100, s100, 0x40
.Lqs_done_13:
	v_cmp_gt_i64_e32 vcc, s[4:5], v[138:139]
	v_cmp_lt_i64_e64 s[6:7], s[4:5], v[136:137]
	s_cbranch_vccnz .LBB0_1912
	s_ashr_i32 s5, s4, 31
	s_lshr_b32 s5, s5, 29
	s_add_i32 s16, s4, s5
	s_and_b32 s5, s16, -8
	s_sub_i32 s17, s4, s5
	s_cmp_gt_i32 s17, 3
	s_mov_b64 s[4:5], -1
	s_cbranch_scc0 .LBB0_1909
	s_lshl_b32 s4, s17, 7
	s_or_b32 s22, s4, 4
	s_mov_b64 s[4:5], 0

.LBB0_1917:
	ds_read_b128 v[140:143], v182
	ds_read_b128 v[144:147], v182 offset:1024
	ds_read_b128 v[148:151], v182 offset:2048
	ds_read_b128 v[152:155], v182 offset:3072
	ds_read_b128 v[156:159], v183
	ds_read_b128 v[160:163], v183 offset:1024
	ds_read_b128 v[164:167], v183 offset:2048
	ds_read_b128 v[168:171], v183 offset:3072
	s_add_u32 s20, s18, 0x100
	s_addc_u32 s21, s19, 0
	s_cmp_eq_u32 s51, 40
	s_cselect_b32 s25, s7, s21
	s_cselect_b32 s24, s6, s20
	s_cselect_b32 s23, s17, s50
	s_cselect_b32 s22, s16, s49
	v_lshl_add_u64 v[210:211], s[18:19], 0, v[132:133]
	s_add_i32 m0, s31, 0xc000
	ds_read_b128 v[172:175], v184
	ds_read_b128 v[176:179], v184 offset:1024
	ds_read_b128 v[186:189], v184 offset:2048
	ds_read_b128 v[190:193], v184 offset:3072
	ds_read_b128 v[194:197], v184 offset:4096
	ds_read_b128 v[198:201], v184 offset:5120
	ds_read_b128 v[202:205], v184 offset:6144
	ds_read_b128 v[206:209], v184 offset:7168
	global_load_lds_dwordx4 v[210:211], off
	v_lshl_add_u64 v[210:211], s[18:19], 0, v[134:135]
	s_add_i32 m0, s31, 0xe000
	s_nop 0
	global_load_lds_dwordx4 v[210:211], off
	s_waitcnt vmcnt(8)
	s_waitcnt lgkmcnt(0)
	s_barrier
	s_setprio 1
	s_waitcnt lgkmcnt(0)
	s_bitcmp1_b32 s101, 0
	s_cbranch_scc0 .Lmm_13_0
	v_mfma_f32_16x16x32_bf16 v[124:127], v[140:143], v[172:175], v[124:127]
	v_mfma_f32_16x16x32_bf16 v[120:123], v[148:151], v[172:175], v[120:123]
	v_mfma_f32_16x16x32_bf16 v[108:111], v[140:143], v[186:189], v[108:111]
	v_mfma_f32_16x16x32_bf16 v[104:107], v[148:151], v[186:189], v[104:107]
	v_mfma_f32_16x16x32_bf16 v[92:95], v[140:143], v[194:197], v[92:95]
	v_mfma_f32_16x16x32_bf16 v[88:91], v[148:151], v[194:197], v[88:91]
	v_mfma_f32_16x16x32_bf16 v[76:79], v[140:143], v[202:205], v[76:79]
	v_mfma_f32_16x16x32_bf16 v[72:75], v[148:151], v[202:205], v[72:75]
	v_mfma_f32_16x16x32_bf16 v[124:127], v[144:147], v[176:179], v[124:127]
	v_mfma_f32_16x16x32_bf16 v[120:123], v[152:155], v[176:179], v[120:123]
	v_mfma_f32_16x16x32_bf16 v[108:111], v[144:147], v[190:193], v[108:111]
	v_mfma_f32_16x16x32_bf16 v[104:107], v[152:155], v[190:193], v[104:107]
	v_mfma_f32_16x16x32_bf16 v[92:95], v[144:147], v[198:201], v[92:95]
	v_mfma_f32_16x16x32_bf16 v[88:91], v[152:155], v[198:201], v[88:91]
	v_mfma_f32_16x16x32_bf16 v[76:79], v[144:147], v[206:209], v[76:79]
	v_mfma_f32_16x16x32_bf16 v[72:75], v[152:155], v[206:209], v[72:75]

.Lmm_13_1:
	s_setprio 0
	s_barrier
	s_add_i32 s18, s41, s30
	v_lshl_add_u64 v[210:211], s[22:23], 0, v[128:129]
	s_mov_b32 m0, s18
	ds_read_b128 v[172:175], v184 offset:16384
	ds_read_b128 v[176:179], v184 offset:17408
	ds_read_b128 v[186:189], v184 offset:18432
	ds_read_b128 v[190:193], v184 offset:19456
	ds_read_b128 v[194:197], v184 offset:20480
	ds_read_b128 v[198:201], v184 offset:21504
	ds_read_b128 v[202:205], v184 offset:22528
	ds_read_b128 v[206:209], v184 offset:23552
	global_load_lds_dwordx4 v[210:211], off
	s_add_i32 m0, s18, 0x2000
	s_add_u32 s18, s22, 0xb0000
	v_lshl_add_u64 v[212:213], s[22:23], 0, v[130:131]
	s_addc_u32 s19, s23, 0
	s_add_i32 s52, s42, s30
	global_load_lds_dwordx4 v[212:213], off
	v_lshl_add_u64 v[214:215], s[18:19], 0, v[128:129]
	s_mov_b32 m0, s52
	v_lshl_add_u64 v[216:217], s[24:25], 0, v[130:131]
	global_load_lds_dwordx4 v[214:215], off
	v_lshl_add_u64 v[214:215], s[18:19], 0, v[130:131]
	s_add_i32 m0, s52, 0x2000
	s_nop 0
	global_load_lds_dwordx4 v[214:215], off
	v_lshl_add_u64 v[214:215], s[24:25], 0, v[128:129]
	s_mov_b32 m0, s31
	s_nop 0
	global_load_lds_dwordx4 v[214:215], off
	s_mov_b32 m0, s33
	s_nop 0
	global_load_lds_dwordx4 v[216:217], off
	s_waitcnt vmcnt(8)
	s_waitcnt lgkmcnt(0)
	s_barrier
	s_setprio 1
	s_waitcnt lgkmcnt(0)
	s_bitcmp1_b32 s101, 2
	s_cbranch_scc0 .Lmm_13_2
	v_mfma_f32_16x16x32_bf16 v[60:63], v[140:143], v[172:175], v[60:63]
	v_mfma_f32_16x16x32_bf16 v[56:59], v[148:151], v[172:175], v[56:59]
	v_mfma_f32_16x16x32_bf16 v[44:47], v[140:143], v[186:189], v[44:47]
	v_mfma_f32_16x16x32_bf16 v[40:43], v[148:151], v[186:189], v[40:43]
	v_mfma_f32_16x16x32_bf16 v[28:31], v[140:143], v[194:197], v[28:31]
	v_mfma_f32_16x16x32_bf16 v[24:27], v[148:151], v[194:197], v[24:27]
	v_mfma_f32_16x16x32_bf16 v[12:15], v[140:143], v[202:205], v[12:15]
	v_mfma_f32_16x16x32_bf16 v[8:11], v[148:151], v[202:205], v[8:11]
	v_mfma_f32_16x16x32_bf16 v[60:63], v[144:147], v[176:179], v[60:63]
	v_mfma_f32_16x16x32_bf16 v[56:59], v[152:155], v[176:179], v[56:59]
	v_mfma_f32_16x16x32_bf16 v[44:47], v[144:147], v[190:193], v[44:47]
	v_mfma_f32_16x16x32_bf16 v[40:43], v[152:155], v[190:193], v[40:43]
	v_mfma_f32_16x16x32_bf16 v[28:31], v[144:147], v[198:201], v[28:31]
	v_mfma_f32_16x16x32_bf16 v[24:27], v[152:155], v[198:201], v[24:27]
	v_mfma_f32_16x16x32_bf16 v[12:15], v[144:147], v[206:209], v[12:15]
	v_mfma_f32_16x16x32_bf16 v[8:11], v[152:155], v[206:209], v[8:11]

.Lmm_13_3:
	s_setprio 0
	s_barrier
	s_add_i32 s52, 0, 0x18000
	s_add_i32 s53, 0, 0x1c000
	v_add_u32_e32 v152, s52, v181
	v_add_u32_e32 v168, s53, v181
	ds_read_b128 v[140:143], v152
	ds_read_b128 v[144:147], v152 offset:1024
	ds_read_b128 v[148:151], v152 offset:2048
	ds_read_b128 v[152:155], v152 offset:3072
	ds_read_b128 v[156:159], v168
	ds_read_b128 v[160:163], v168 offset:1024
	ds_read_b128 v[164:167], v168 offset:2048
	ds_read_b128 v[168:171], v168 offset:3072
	s_add_u32 s18, s24, 0xb0000
	s_addc_u32 s19, s25, 0
	s_mov_b32 m0, s34
	v_lshl_add_u64 v[218:219], s[18:19], 0, v[128:129]
	ds_read_b128 v[172:175], v184 offset:32768
	ds_read_b128 v[176:179], v184 offset:33792
	ds_read_b128 v[186:189], v184 offset:34816
	ds_read_b128 v[190:193], v184 offset:35840
	ds_read_b128 v[194:197], v184 offset:36864
	ds_read_b128 v[198:201], v184 offset:37888
	ds_read_b128 v[202:205], v184 offset:38912
	ds_read_b128 v[206:209], v184 offset:39936
	global_load_lds_dwordx4 v[218:219], off
	v_lshl_add_u64 v[218:219], s[18:19], 0, v[130:131]
	s_mov_b32 m0, s35
	s_nop 0
	global_load_lds_dwordx4 v[218:219], off
	s_waitcnt vmcnt(8)
	s_waitcnt lgkmcnt(0)
	s_barrier
	s_setprio 1
	s_waitcnt lgkmcnt(0)
	s_bitcmp1_b32 s101, 0
	s_cbranch_scc0 .Lmm_13_4
	v_mfma_f32_16x16x32_bf16 v[124:127], v[140:143], v[172:175], v[124:127]
	v_mfma_f32_16x16x32_bf16 v[120:123], v[148:151], v[172:175], v[120:123]
	v_mfma_f32_16x16x32_bf16 v[108:111], v[140:143], v[186:189], v[108:111]
	v_mfma_f32_16x16x32_bf16 v[104:107], v[148:151], v[186:189], v[104:107]
	v_mfma_f32_16x16x32_bf16 v[92:95], v[140:143], v[194:197], v[92:95]
	v_mfma_f32_16x16x32_bf16 v[88:91], v[148:151], v[194:197], v[88:91]
	v_mfma_f32_16x16x32_bf16 v[76:79], v[140:143], v[202:205], v[76:79]
	v_mfma_f32_16x16x32_bf16 v[72:75], v[148:151], v[202:205], v[72:75]
	v_mfma_f32_16x16x32_bf16 v[124:127], v[144:147], v[176:179], v[124:127]
	v_mfma_f32_16x16x32_bf16 v[120:123], v[152:155], v[176:179], v[120:123]
	v_mfma_f32_16x16x32_bf16 v[108:111], v[144:147], v[190:193], v[108:111]
	v_mfma_f32_16x16x32_bf16 v[104:107], v[152:155], v[190:193], v[104:107]
	v_mfma_f32_16x16x32_bf16 v[92:95], v[144:147], v[198:201], v[92:95]
	v_mfma_f32_16x16x32_bf16 v[88:91], v[152:155], v[198:201], v[88:91]
	v_mfma_f32_16x16x32_bf16 v[76:79], v[144:147], v[206:209], v[76:79]
	v_mfma_f32_16x16x32_bf16 v[72:75], v[152:155], v[206:209], v[72:75]

.Lmm_13_5:
	s_setprio 0
	s_barrier
	s_add_i32 s18, s52, s30
	v_lshl_add_u64 v[210:211], v[210:211], 0, s[12:13]
	s_mov_b32 m0, s18
	ds_read_b128 v[172:175], v184 offset:49152
	ds_read_b128 v[176:179], v184 offset:50176
	ds_read_b128 v[186:189], v184 offset:51200
	ds_read_b128 v[190:193], v184 offset:52224
	ds_read_b128 v[194:197], v184 offset:53248
	ds_read_b128 v[198:201], v184 offset:54272
	ds_read_b128 v[202:205], v184 offset:55296
	ds_read_b128 v[206:209], v184 offset:56320
	global_load_lds_dwordx4 v[210:211], off
	s_add_i32 m0, s18, 0x2000
	s_add_u32 s18, s22, 0xb0080
	v_lshl_add_u64 v[210:211], v[212:213], 0, s[12:13]
	s_addc_u32 s19, s23, 0
	s_add_i32 s22, s53, s30
	global_load_lds_dwordx4 v[210:211], off
	v_lshl_add_u64 v[210:211], s[18:19], 0, v[128:129]
	s_mov_b32 m0, s22
	s_nop 0
	global_load_lds_dwordx4 v[210:211], off
	v_lshl_add_u64 v[210:211], s[18:19], 0, v[130:131]
	s_add_i32 m0, s22, 0x2000
	s_nop 0
	global_load_lds_dwordx4 v[210:211], off
	v_lshl_add_u64 v[210:211], v[214:215], 0, s[12:13]
	s_mov_b32 m0, s39
	s_nop 0
	global_load_lds_dwordx4 v[210:211], off
	v_lshl_add_u64 v[210:211], v[216:217], 0, s[12:13]
	s_mov_b32 m0, s40
	s_nop 0
	global_load_lds_dwordx4 v[210:211], off
	s_waitcnt vmcnt(8)
	s_waitcnt lgkmcnt(0)
	s_barrier
	s_setprio 1
	s_waitcnt lgkmcnt(0)
	s_bitcmp1_b32 s101, 2
	s_cbranch_scc0 .Lmm_13_6
	v_mfma_f32_16x16x32_bf16 v[60:63], v[140:143], v[172:175], v[60:63]
	v_mfma_f32_16x16x32_bf16 v[56:59], v[148:151], v[172:175], v[56:59]
	v_mfma_f32_16x16x32_bf16 v[44:47], v[140:143], v[186:189], v[44:47]
	v_mfma_f32_16x16x32_bf16 v[40:43], v[148:151], v[186:189], v[40:43]
	v_mfma_f32_16x16x32_bf16 v[28:31], v[140:143], v[194:197], v[28:31]
	v_mfma_f32_16x16x32_bf16 v[24:27], v[148:151], v[194:197], v[24:27]
	v_mfma_f32_16x16x32_bf16 v[12:15], v[140:143], v[202:205], v[12:15]
	v_mfma_f32_16x16x32_bf16 v[8:11], v[148:151], v[202:205], v[8:11]
	v_mfma_f32_16x16x32_bf16 v[60:63], v[144:147], v[176:179], v[60:63]
	v_mfma_f32_16x16x32_bf16 v[56:59], v[152:155], v[176:179], v[56:59]
	v_mfma_f32_16x16x32_bf16 v[44:47], v[144:147], v[190:193], v[44:47]
	v_mfma_f32_16x16x32_bf16 v[40:43], v[152:155], v[190:193], v[40:43]
	v_mfma_f32_16x16x32_bf16 v[28:31], v[144:147], v[198:201], v[28:31]
	v_mfma_f32_16x16x32_bf16 v[24:27], v[152:155], v[198:201], v[24:27]
	v_mfma_f32_16x16x32_bf16 v[12:15], v[144:147], v[206:209], v[12:15]
	v_mfma_f32_16x16x32_bf16 v[8:11], v[152:155], v[206:209], v[8:11]

.Lmm_13_7:
	s_setprio 0
	s_barrier
	s_add_i32 s51, s51, 2
	s_add_u32 s49, s49, 0x100
	s_addc_u32 s50, s50, 0
	s_cmp_gt_u32 s51, 41
	s_mov_b64 s[18:19], s[20:21]
	s_cbranch_scc0 .LBB0_1917
	s_and_b64 vcc, exec, s[14:15]
	s_cbranch_vccz .LBB0_1920
	s_barrier
.LBB0_1920:
	s_bitcmp1_b32 s101, 6
	s_cbranch_scc1 .Lqepi_13
	v_and_b32_e32 v146, 63, v180
	v_and_b32_e32 v147, 15, v180
	v_bfe_u32 v148, v180, 4, 2
	v_lshrrev_b32_e32 v149, 6, v180
	v_lshlrev_b32_e32 v149, 12, v149
	v_add_u32_e32 v149, 0x20000, v149
	v_and_b32_e32 v150, 7, v147
	v_xor_b32_e32 v150, v148, v150
	v_lshlrev_b32_e32 v150, 4, v150
	v_lshl_add_u32 v150, v147, 8, v150
	v_add_u32_e32 v140, v149, v150
	v_xor_b32_e32 v141, 64, v140
	v_lshrrev_b32_e32 v151, 2, v146
	v_and_b32_e32 v152, 3, v146
	v_and_b32_e32 v153, 7, v151
	v_lshlrev_b32_e32 v154, 1, v152
	v_xor_b32_e32 v154, v154, v153
	v_lshlrev_b32_e32 v154, 4, v154
	v_lshl_add_u32 v154, v151, 8, v154
	v_add_u32_e32 v142, v149, v154
	v_xor_b32_e32 v143, 16, v142
	s_lshl_b32 s18, s48, 8
	s_add_i32 s18, s18, s37
	v_add_u32_e32 v155, s18, v151
	v_lshlrev_b32_e32 v145, 2, v155
	v_lshlrev_b32_e32 v155, 11, v155
	s_lshl_b32 s18, s45, 8
	s_add_i32 s18, s18, s38
	v_lshl_add_u32 v156, v152, 3, s18
	v_lshl_add_u32 v144, v156, 1, v155
	v_cmp_eq_u32_e32 vcc, 0, v152
	s_mov_b64 s[98:99], s[8:9]
	global_load_dwordx4 v[188:191], v144, s[98:99]
	global_load_dwordx4 v[192:195], v144, s[98:99] offset:256
	s_add_u32 s98, s98, 0x8000
	s_addc_u32 s99, s99, 0
	global_load_dwordx4 v[196:199], v144, s[98:99]
	global_load_dwordx4 v[200:203], v144, s[98:99] offset:256
	s_add_u32 s98, s98, 0x8000
	s_addc_u32 s99, s99, 0
	global_load_dwordx4 v[204:207], v144, s[98:99]
	global_load_dwordx4 v[208:211], v144, s[98:99] offset:256
	s_add_u32 s98, s98, 0x8000
	s_addc_u32 s99, s99, 0
	global_load_dwordx4 v[212:215], v144, s[98:99]
	global_load_dwordx4 v[216:219], v144, s[98:99] offset:256
	s_add_u32 s98, s98, 0x28000
	s_addc_u32 s99, s99, 0
	global_load_dwordx4 v[220:223], v144, s[98:99]
	global_load_dwordx4 v[224:227], v144, s[98:99] offset:256
	s_add_u32 s98, s98, 0x8000
	s_addc_u32 s99, s99, 0
	global_load_dwordx4 v[228:231], v144, s[98:99]
	global_load_dwordx4 v[232:235], v144, s[98:99] offset:256
	s_add_u32 s98, s98, 0x8000
	s_addc_u32 s99, s99, 0
	global_load_dwordx4 v[236:239], v144, s[98:99]
	global_load_dwordx4 v[240:243], v144, s[98:99] offset:256
	s_add_u32 s98, s98, 0x8000
	s_addc_u32 s99, s99, 0
	global_load_dwordx4 v[244:247], v144, s[98:99]
	global_load_dwordx4 v[248:251], v144, s[98:99] offset:256
	s_mov_b64 s[18:19], exec
	s_mov_b64 s[98:99], s[8:9]
	ds_write_b128 v140, v[124:127]
	ds_write_b128 v141, v[120:123]
	ds_write_b128 v140, v[116:119] offset:128
	ds_write_b128 v141, v[112:115] offset:128
	s_waitcnt lgkmcnt(0)
	ds_read_b128 v[146:149], v142
	ds_read_b128 v[150:153], v143
	ds_read_b128 v[154:157], v142 offset:128
	ds_read_b128 v[158:161], v143 offset:128
	s_waitcnt lgkmcnt(0)
	ds_write_b128 v140, v[108:111]
	ds_write_b128 v141, v[104:107]
	ds_write_b128 v140, v[100:103] offset:128
	ds_write_b128 v141, v[96:99] offset:128
	s_waitcnt vmcnt(14)
	v_lshlrev_b32_e32 v162, 16, v188
	v_and_b32_e32 v163, 0xffff0000, v188
	v_lshlrev_b32_e32 v164, 16, v189
	v_and_b32_e32 v165, 0xffff0000, v189
	v_lshlrev_b32_e32 v166, 16, v190
	v_and_b32_e32 v167, 0xffff0000, v190
	v_lshlrev_b32_e32 v168, 16, v191
	v_and_b32_e32 v169, 0xffff0000, v191
	v_pk_add_f32 v[146:147], v[146:147], v[162:163]
	v_pk_add_f32 v[148:149], v[148:149], v[164:165]
	v_pk_add_f32 v[150:151], v[150:151], v[166:167]
	v_pk_add_f32 v[152:153], v[152:153], v[168:169]
	v_pk_mul_f32 v[170:171], v[146:147], v[146:147]
	v_pk_fma_f32 v[170:171], v[148:149], v[148:149], v[170:171]
	v_pk_fma_f32 v[170:171], v[150:151], v[150:151], v[170:171]
	v_pk_fma_f32 v[170:171], v[152:153], v[152:153], v[170:171]
	v_cvt_pk_bf16_f32 v172, v146, v147
	v_cvt_pk_bf16_f32 v173, v148, v149
	v_cvt_pk_bf16_f32 v174, v150, v151
	v_cvt_pk_bf16_f32 v175, v152, v153
	global_store_dwordx4 v144, v[172:175], s[98:99]
	v_lshlrev_b32_e32 v162, 16, v192
	v_and_b32_e32 v163, 0xffff0000, v192
	v_lshlrev_b32_e32 v164, 16, v193
	v_and_b32_e32 v165, 0xffff0000, v193
	v_lshlrev_b32_e32 v166, 16, v194
	v_and_b32_e32 v167, 0xffff0000, v194
	v_lshlrev_b32_e32 v168, 16, v195
	v_and_b32_e32 v169, 0xffff0000, v195
	v_pk_add_f32 v[154:155], v[154:155], v[162:163]
	v_pk_add_f32 v[156:157], v[156:157], v[164:165]
	v_pk_add_f32 v[158:159], v[158:159], v[166:167]
	v_pk_add_f32 v[160:161], v[160:161], v[168:169]
	v_pk_fma_f32 v[170:171], v[154:155], v[154:155], v[170:171]
	v_pk_fma_f32 v[170:171], v[156:157], v[156:157], v[170:171]
	v_pk_fma_f32 v[170:171], v[158:159], v[158:159], v[170:171]
	v_pk_fma_f32 v[170:171], v[160:161], v[160:161], v[170:171]
	v_cvt_pk_bf16_f32 v176, v154, v155
	v_cvt_pk_bf16_f32 v177, v156, v157
	v_cvt_pk_bf16_f32 v178, v158, v159
	v_cvt_pk_bf16_f32 v179, v160, v161
	global_store_dwordx4 v144, v[176:179], s[98:99] offset:256
	v_add_f32_e32 v162, v170, v171
	s_nop 1
	v_add_f32_dpp v163, v162, v162 quad_perm:[1,0,3,2] row_mask:0xf bank_mask:0xf
	s_nop 1
	v_add_f32_dpp v164, v163, v163 quad_perm:[2,3,0,1] row_mask:0xf bank_mask:0xf
	s_mov_b64 exec, vcc
	global_atomic_add_f32 v145, v164, s[10:11] offset:0
	s_mov_b64 exec, s[18:19]
	s_add_u32 s98, s98, 0x8000
	s_addc_u32 s99, s99, 0
	s_waitcnt lgkmcnt(0)
	ds_read_b128 v[146:149], v142
	ds_read_b128 v[150:153], v143
	ds_read_b128 v[154:157], v142 offset:128
	ds_read_b128 v[158:161], v143 offset:128
	s_waitcnt lgkmcnt(0)
	ds_write_b128 v140, v[92:95]
	ds_write_b128 v141, v[88:91]
	ds_write_b128 v140, v[84:87] offset:128
	ds_write_b128 v141, v[80:83] offset:128
	s_waitcnt vmcnt(15)
	v_lshlrev_b32_e32 v162, 16, v196
	v_and_b32_e32 v163, 0xffff0000, v196
	v_lshlrev_b32_e32 v164, 16, v197
	v_and_b32_e32 v165, 0xffff0000, v197
	v_lshlrev_b32_e32 v166, 16, v198
	v_and_b32_e32 v167, 0xffff0000, v198
	v_lshlrev_b32_e32 v168, 16, v199
	v_and_b32_e32 v169, 0xffff0000, v199
	v_pk_add_f32 v[146:147], v[146:147], v[162:163]
	v_pk_add_f32 v[148:149], v[148:149], v[164:165]
	v_pk_add_f32 v[150:151], v[150:151], v[166:167]
	v_pk_add_f32 v[152:153], v[152:153], v[168:169]
	v_pk_mul_f32 v[170:171], v[146:147], v[146:147]
	v_pk_fma_f32 v[170:171], v[148:149], v[148:149], v[170:171]
	v_pk_fma_f32 v[170:171], v[150:151], v[150:151], v[170:171]
	v_pk_fma_f32 v[170:171], v[152:153], v[152:153], v[170:171]
	v_cvt_pk_bf16_f32 v172, v146, v147
	v_cvt_pk_bf16_f32 v173, v148, v149
	v_cvt_pk_bf16_f32 v174, v150, v151
	v_cvt_pk_bf16_f32 v175, v152, v153
	global_store_dwordx4 v144, v[172:175], s[98:99]
	v_lshlrev_b32_e32 v162, 16, v200
	v_and_b32_e32 v163, 0xffff0000, v200
	v_lshlrev_b32_e32 v164, 16, v201
	v_and_b32_e32 v165, 0xffff0000, v201
	v_lshlrev_b32_e32 v166, 16, v202
	v_and_b32_e32 v167, 0xffff0000, v202
	v_lshlrev_b32_e32 v168, 16, v203
	v_and_b32_e32 v169, 0xffff0000, v203
	v_pk_add_f32 v[154:155], v[154:155], v[162:163]
	v_pk_add_f32 v[156:157], v[156:157], v[164:165]
	v_pk_add_f32 v[158:159], v[158:159], v[166:167]
	v_pk_add_f32 v[160:161], v[160:161], v[168:169]
	v_pk_fma_f32 v[170:171], v[154:155], v[154:155], v[170:171]
	v_pk_fma_f32 v[170:171], v[156:157], v[156:157], v[170:171]
	v_pk_fma_f32 v[170:171], v[158:159], v[158:159], v[170:171]
	v_pk_fma_f32 v[170:171], v[160:161], v[160:161], v[170:171]
	v_cvt_pk_bf16_f32 v176, v154, v155
	v_cvt_pk_bf16_f32 v177, v156, v157
	v_cvt_pk_bf16_f32 v178, v158, v159
	v_cvt_pk_bf16_f32 v179, v160, v161
	global_store_dwordx4 v144, v[176:179], s[98:99] offset:256
	v_add_f32_e32 v162, v170, v171
	s_nop 1
	v_add_f32_dpp v163, v162, v162 quad_perm:[1,0,3,2] row_mask:0xf bank_mask:0xf
	s_nop 1
	v_add_f32_dpp v164, v163, v163 quad_perm:[2,3,0,1] row_mask:0xf bank_mask:0xf
	s_mov_b64 exec, vcc
	global_atomic_add_f32 v145, v164, s[10:11] offset:64
	s_mov_b64 exec, s[18:19]
	s_add_u32 s98, s98, 0x8000
	s_addc_u32 s99, s99, 0
	s_waitcnt lgkmcnt(0)
	ds_read_b128 v[146:149], v142
	ds_read_b128 v[150:153], v143
	ds_read_b128 v[154:157], v142 offset:128
	ds_read_b128 v[158:161], v143 offset:128
	s_waitcnt lgkmcnt(0)
	ds_write_b128 v140, v[76:79]
	ds_write_b128 v141, v[72:75]
	ds_write_b128 v140, v[68:71] offset:128
	ds_write_b128 v141, v[64:67] offset:128
	s_waitcnt vmcnt(16)
	v_lshlrev_b32_e32 v162, 16, v204
	v_and_b32_e32 v163, 0xffff0000, v204
	v_lshlrev_b32_e32 v164, 16, v205
	v_and_b32_e32 v165, 0xffff0000, v205
	v_lshlrev_b32_e32 v166, 16, v206
	v_and_b32_e32 v167, 0xffff0000, v206
	v_lshlrev_b32_e32 v168, 16, v207
	v_and_b32_e32 v169, 0xffff0000, v207
	v_pk_add_f32 v[146:147], v[146:147], v[162:163]
	v_pk_add_f32 v[148:149], v[148:149], v[164:165]
	v_pk_add_f32 v[150:151], v[150:151], v[166:167]
	v_pk_add_f32 v[152:153], v[152:153], v[168:169]
	v_pk_mul_f32 v[170:171], v[146:147], v[146:147]
	v_pk_fma_f32 v[170:171], v[148:149], v[148:149], v[170:171]
	v_pk_fma_f32 v[170:171], v[150:151], v[150:151], v[170:171]
	v_pk_fma_f32 v[170:171], v[152:153], v[152:153], v[170:171]
	v_cvt_pk_bf16_f32 v172, v146, v147
	v_cvt_pk_bf16_f32 v173, v148, v149
	v_cvt_pk_bf16_f32 v174, v150, v151
	v_cvt_pk_bf16_f32 v175, v152, v153
	global_store_dwordx4 v144, v[172:175], s[98:99]
	v_lshlrev_b32_e32 v162, 16, v208
	v_and_b32_e32 v163, 0xffff0000, v208
	v_lshlrev_b32_e32 v164, 16, v209
	v_and_b32_e32 v165, 0xffff0000, v209
	v_lshlrev_b32_e32 v166, 16, v210
	v_and_b32_e32 v167, 0xffff0000, v210
	v_lshlrev_b32_e32 v168, 16, v211
	v_and_b32_e32 v169, 0xffff0000, v211
	v_pk_add_f32 v[154:155], v[154:155], v[162:163]
	v_pk_add_f32 v[156:157], v[156:157], v[164:165]
	v_pk_add_f32 v[158:159], v[158:159], v[166:167]
	v_pk_add_f32 v[160:161], v[160:161], v[168:169]
	v_pk_fma_f32 v[170:171], v[154:155], v[154:155], v[170:171]
	v_pk_fma_f32 v[170:171], v[156:157], v[156:157], v[170:171]
	v_pk_fma_f32 v[170:171], v[158:159], v[158:159], v[170:171]
	v_pk_fma_f32 v[170:171], v[160:161], v[160:161], v[170:171]
	v_cvt_pk_bf16_f32 v176, v154, v155
	v_cvt_pk_bf16_f32 v177, v156, v157
	v_cvt_pk_bf16_f32 v178, v158, v159
	v_cvt_pk_bf16_f32 v179, v160, v161
	global_store_dwordx4 v144, v[176:179], s[98:99] offset:256
	v_add_f32_e32 v162, v170, v171
	s_nop 1
	v_add_f32_dpp v163, v162, v162 quad_perm:[1,0,3,2] row_mask:0xf bank_mask:0xf
	s_nop 1
	v_add_f32_dpp v164, v163, v163 quad_perm:[2,3,0,1] row_mask:0xf bank_mask:0xf
	s_mov_b64 exec, vcc
	global_atomic_add_f32 v145, v164, s[10:11] offset:128
	s_mov_b64 exec, s[18:19]
	s_add_u32 s98, s98, 0x8000
	s_addc_u32 s99, s99, 0
	s_waitcnt lgkmcnt(0)
	ds_read_b128 v[146:149], v142
	ds_read_b128 v[150:153], v143
	ds_read_b128 v[154:157], v142 offset:128
	ds_read_b128 v[158:161], v143 offset:128
	s_waitcnt lgkmcnt(0)
	ds_write_b128 v140, v[60:63]
	ds_write_b128 v141, v[56:59]
	ds_write_b128 v140, v[52:55] offset:128
	ds_write_b128 v141, v[48:51] offset:128
	s_waitcnt vmcnt(17)
	v_lshlrev_b32_e32 v162, 16, v212
	v_and_b32_e32 v163, 0xffff0000, v212
	v_lshlrev_b32_e32 v164, 16, v213
	v_and_b32_e32 v165, 0xffff0000, v213
	v_lshlrev_b32_e32 v166, 16, v214
	v_and_b32_e32 v167, 0xffff0000, v214
	v_lshlrev_b32_e32 v168, 16, v215
	v_and_b32_e32 v169, 0xffff0000, v215
	v_pk_add_f32 v[146:147], v[146:147], v[162:163]
	v_pk_add_f32 v[148:149], v[148:149], v[164:165]
	v_pk_add_f32 v[150:151], v[150:151], v[166:167]
	v_pk_add_f32 v[152:153], v[152:153], v[168:169]
	v_pk_mul_f32 v[170:171], v[146:147], v[146:147]
	v_pk_fma_f32 v[170:171], v[148:149], v[148:149], v[170:171]
	v_pk_fma_f32 v[170:171], v[150:151], v[150:151], v[170:171]
	v_pk_fma_f32 v[170:171], v[152:153], v[152:153], v[170:171]
	v_cvt_pk_bf16_f32 v172, v146, v147
	v_cvt_pk_bf16_f32 v173, v148, v149
	v_cvt_pk_bf16_f32 v174, v150, v151
	v_cvt_pk_bf16_f32 v175, v152, v153
	global_store_dwordx4 v144, v[172:175], s[98:99]
	v_lshlrev_b32_e32 v162, 16, v216
	v_and_b32_e32 v163, 0xffff0000, v216
	v_lshlrev_b32_e32 v164, 16, v217
	v_and_b32_e32 v165, 0xffff0000, v217
	v_lshlrev_b32_e32 v166, 16, v218
	v_and_b32_e32 v167, 0xffff0000, v218
	v_lshlrev_b32_e32 v168, 16, v219
	v_and_b32_e32 v169, 0xffff0000, v219
	v_pk_add_f32 v[154:155], v[154:155], v[162:163]
	v_pk_add_f32 v[156:157], v[156:157], v[164:165]
	v_pk_add_f32 v[158:159], v[158:159], v[166:167]
	v_pk_add_f32 v[160:161], v[160:161], v[168:169]
	v_pk_fma_f32 v[170:171], v[154:155], v[154:155], v[170:171]
	v_pk_fma_f32 v[170:171], v[156:157], v[156:157], v[170:171]
	v_pk_fma_f32 v[170:171], v[158:159], v[158:159], v[170:171]
	v_pk_fma_f32 v[170:171], v[160:161], v[160:161], v[170:171]
	v_cvt_pk_bf16_f32 v176, v154, v155
	v_cvt_pk_bf16_f32 v177, v156, v157
	v_cvt_pk_bf16_f32 v178, v158, v159
	v_cvt_pk_bf16_f32 v179, v160, v161
	global_store_dwordx4 v144, v[176:179], s[98:99] offset:256
	v_add_f32_e32 v162, v170, v171
	s_nop 1
	v_add_f32_dpp v163, v162, v162 quad_perm:[1,0,3,2] row_mask:0xf bank_mask:0xf
	s_nop 1
	v_add_f32_dpp v164, v163, v163 quad_perm:[2,3,0,1] row_mask:0xf bank_mask:0xf
	s_mov_b64 exec, vcc
	global_atomic_add_f32 v145, v164, s[10:11] offset:192
	s_mov_b64 exec, s[18:19]
	s_add_u32 s98, s98, 0x28000
	s_addc_u32 s99, s99, 0
	s_waitcnt lgkmcnt(0)
	ds_read_b128 v[146:149], v142
	ds_read_b128 v[150:153], v143
	ds_read_b128 v[154:157], v142 offset:128
	ds_read_b128 v[158:161], v143 offset:128
	s_waitcnt lgkmcnt(0)
	ds_write_b128 v140, v[44:47]
	ds_write_b128 v141, v[40:43]
	ds_write_b128 v140, v[36:39] offset:128
	ds_write_b128 v141, v[32:35] offset:128
	s_waitcnt vmcnt(18)
	v_lshlrev_b32_e32 v162, 16, v220
	v_and_b32_e32 v163, 0xffff0000, v220
	v_lshlrev_b32_e32 v164, 16, v221
	v_and_b32_e32 v165, 0xffff0000, v221
	v_lshlrev_b32_e32 v166, 16, v222
	v_and_b32_e32 v167, 0xffff0000, v222
	v_lshlrev_b32_e32 v168, 16, v223
	v_and_b32_e32 v169, 0xffff0000, v223
	v_pk_add_f32 v[146:147], v[146:147], v[162:163]
	v_pk_add_f32 v[148:149], v[148:149], v[164:165]
	v_pk_add_f32 v[150:151], v[150:151], v[166:167]
	v_pk_add_f32 v[152:153], v[152:153], v[168:169]
	v_pk_mul_f32 v[170:171], v[146:147], v[146:147]
	v_pk_fma_f32 v[170:171], v[148:149], v[148:149], v[170:171]
	v_pk_fma_f32 v[170:171], v[150:151], v[150:151], v[170:171]
	v_pk_fma_f32 v[170:171], v[152:153], v[152:153], v[170:171]
	v_cvt_pk_bf16_f32 v172, v146, v147
	v_cvt_pk_bf16_f32 v173, v148, v149
	v_cvt_pk_bf16_f32 v174, v150, v151
	v_cvt_pk_bf16_f32 v175, v152, v153
	global_store_dwordx4 v144, v[172:175], s[98:99]
	v_lshlrev_b32_e32 v162, 16, v224
	v_and_b32_e32 v163, 0xffff0000, v224
	v_lshlrev_b32_e32 v164, 16, v225
	v_and_b32_e32 v165, 0xffff0000, v225
	v_lshlrev_b32_e32 v166, 16, v226
	v_and_b32_e32 v167, 0xffff0000, v226
	v_lshlrev_b32_e32 v168, 16, v227
	v_and_b32_e32 v169, 0xffff0000, v227
	v_pk_add_f32 v[154:155], v[154:155], v[162:163]
	v_pk_add_f32 v[156:157], v[156:157], v[164:165]
	v_pk_add_f32 v[158:159], v[158:159], v[166:167]
	v_pk_add_f32 v[160:161], v[160:161], v[168:169]
	v_pk_fma_f32 v[170:171], v[154:155], v[154:155], v[170:171]
	v_pk_fma_f32 v[170:171], v[156:157], v[156:157], v[170:171]
	v_pk_fma_f32 v[170:171], v[158:159], v[158:159], v[170:171]
	v_pk_fma_f32 v[170:171], v[160:161], v[160:161], v[170:171]
	v_cvt_pk_bf16_f32 v176, v154, v155
	v_cvt_pk_bf16_f32 v177, v156, v157
	v_cvt_pk_bf16_f32 v178, v158, v159
	v_cvt_pk_bf16_f32 v179, v160, v161
	global_store_dwordx4 v144, v[176:179], s[98:99] offset:256
	v_add_f32_e32 v162, v170, v171
	s_nop 1
	v_add_f32_dpp v163, v162, v162 quad_perm:[1,0,3,2] row_mask:0xf bank_mask:0xf
	s_nop 1
	v_add_f32_dpp v164, v163, v163 quad_perm:[2,3,0,1] row_mask:0xf bank_mask:0xf
	s_mov_b64 exec, vcc
	global_atomic_add_f32 v145, v164, s[10:11] offset:512
	s_mov_b64 exec, s[18:19]
	s_add_u32 s98, s98, 0x8000
	s_addc_u32 s99, s99, 0
	s_waitcnt lgkmcnt(0)
	ds_read_b128 v[146:149], v142
	ds_read_b128 v[150:153], v143
	ds_read_b128 v[154:157], v142 offset:128
	ds_read_b128 v[158:161], v143 offset:128
	s_waitcnt lgkmcnt(0)
	ds_write_b128 v140, v[28:31]
	ds_write_b128 v141, v[24:27]
	ds_write_b128 v140, v[20:23] offset:128
	ds_write_b128 v141, v[16:19] offset:128
	s_waitcnt vmcnt(19)
	v_lshlrev_b32_e32 v162, 16, v228
	v_and_b32_e32 v163, 0xffff0000, v228
	v_lshlrev_b32_e32 v164, 16, v229
	v_and_b32_e32 v165, 0xffff0000, v229
	v_lshlrev_b32_e32 v166, 16, v230
	v_and_b32_e32 v167, 0xffff0000, v230
	v_lshlrev_b32_e32 v168, 16, v231
	v_and_b32_e32 v169, 0xffff0000, v231
	v_pk_add_f32 v[146:147], v[146:147], v[162:163]
	v_pk_add_f32 v[148:149], v[148:149], v[164:165]
	v_pk_add_f32 v[150:151], v[150:151], v[166:167]
	v_pk_add_f32 v[152:153], v[152:153], v[168:169]
	v_pk_mul_f32 v[170:171], v[146:147], v[146:147]
	v_pk_fma_f32 v[170:171], v[148:149], v[148:149], v[170:171]
	v_pk_fma_f32 v[170:171], v[150:151], v[150:151], v[170:171]
	v_pk_fma_f32 v[170:171], v[152:153], v[152:153], v[170:171]
	v_cvt_pk_bf16_f32 v172, v146, v147
	v_cvt_pk_bf16_f32 v173, v148, v149
	v_cvt_pk_bf16_f32 v174, v150, v151
	v_cvt_pk_bf16_f32 v175, v152, v153
	global_store_dwordx4 v144, v[172:175], s[98:99]
	v_lshlrev_b32_e32 v162, 16, v232
	v_and_b32_e32 v163, 0xffff0000, v232
	v_lshlrev_b32_e32 v164, 16, v233
	v_and_b32_e32 v165, 0xffff0000, v233
	v_lshlrev_b32_e32 v166, 16, v234
	v_and_b32_e32 v167, 0xffff0000, v234
	v_lshlrev_b32_e32 v168, 16, v235
	v_and_b32_e32 v169, 0xffff0000, v235
	v_pk_add_f32 v[154:155], v[154:155], v[162:163]
	v_pk_add_f32 v[156:157], v[156:157], v[164:165]
	v_pk_add_f32 v[158:159], v[158:159], v[166:167]
	v_pk_add_f32 v[160:161], v[160:161], v[168:169]
	v_pk_fma_f32 v[170:171], v[154:155], v[154:155], v[170:171]
	v_pk_fma_f32 v[170:171], v[156:157], v[156:157], v[170:171]
	v_pk_fma_f32 v[170:171], v[158:159], v[158:159], v[170:171]
	v_pk_fma_f32 v[170:171], v[160:161], v[160:161], v[170:171]
	v_cvt_pk_bf16_f32 v176, v154, v155
	v_cvt_pk_bf16_f32 v177, v156, v157
	v_cvt_pk_bf16_f32 v178, v158, v159
	v_cvt_pk_bf16_f32 v179, v160, v161
	global_store_dwordx4 v144, v[176:179], s[98:99] offset:256
	v_add_f32_e32 v162, v170, v171
	s_nop 1
	v_add_f32_dpp v163, v162, v162 quad_perm:[1,0,3,2] row_mask:0xf bank_mask:0xf
	s_nop 1
	v_add_f32_dpp v164, v163, v163 quad_perm:[2,3,0,1] row_mask:0xf bank_mask:0xf
	s_mov_b64 exec, vcc
	global_atomic_add_f32 v145, v164, s[10:11] offset:576
	s_mov_b64 exec, s[18:19]
	s_add_u32 s98, s98, 0x8000
	s_addc_u32 s99, s99, 0
	s_waitcnt lgkmcnt(0)
	ds_read_b128 v[146:149], v142
	ds_read_b128 v[150:153], v143
	ds_read_b128 v[154:157], v142 offset:128
	ds_read_b128 v[158:161], v143 offset:128
	s_waitcnt lgkmcnt(0)
	ds_write_b128 v140, v[12:15]
	ds_write_b128 v141, v[8:11]
	ds_write_b128 v140, v[4:7] offset:128
	ds_write_b128 v141, v[0:3] offset:128
	s_waitcnt vmcnt(20)
	v_lshlrev_b32_e32 v162, 16, v236
	v_and_b32_e32 v163, 0xffff0000, v236
	v_lshlrev_b32_e32 v164, 16, v237
	v_and_b32_e32 v165, 0xffff0000, v237
	v_lshlrev_b32_e32 v166, 16, v238
	v_and_b32_e32 v167, 0xffff0000, v238
	v_lshlrev_b32_e32 v168, 16, v239
	v_and_b32_e32 v169, 0xffff0000, v239
	v_pk_add_f32 v[146:147], v[146:147], v[162:163]
	v_pk_add_f32 v[148:149], v[148:149], v[164:165]
	v_pk_add_f32 v[150:151], v[150:151], v[166:167]
	v_pk_add_f32 v[152:153], v[152:153], v[168:169]
	v_pk_mul_f32 v[170:171], v[146:147], v[146:147]
	v_pk_fma_f32 v[170:171], v[148:149], v[148:149], v[170:171]
	v_pk_fma_f32 v[170:171], v[150:151], v[150:151], v[170:171]
	v_pk_fma_f32 v[170:171], v[152:153], v[152:153], v[170:171]
	v_cvt_pk_bf16_f32 v172, v146, v147
	v_cvt_pk_bf16_f32 v173, v148, v149
	v_cvt_pk_bf16_f32 v174, v150, v151
	v_cvt_pk_bf16_f32 v175, v152, v153
	global_store_dwordx4 v144, v[172:175], s[98:99]
	v_lshlrev_b32_e32 v162, 16, v240
	v_and_b32_e32 v163, 0xffff0000, v240
	v_lshlrev_b32_e32 v164, 16, v241
	v_and_b32_e32 v165, 0xffff0000, v241
	v_lshlrev_b32_e32 v166, 16, v242
	v_and_b32_e32 v167, 0xffff0000, v242
	v_lshlrev_b32_e32 v168, 16, v243
	v_and_b32_e32 v169, 0xffff0000, v243
	v_pk_add_f32 v[154:155], v[154:155], v[162:163]
	v_pk_add_f32 v[156:157], v[156:157], v[164:165]
	v_pk_add_f32 v[158:159], v[158:159], v[166:167]
	v_pk_add_f32 v[160:161], v[160:161], v[168:169]
	v_pk_fma_f32 v[170:171], v[154:155], v[154:155], v[170:171]
	v_pk_fma_f32 v[170:171], v[156:157], v[156:157], v[170:171]
	v_pk_fma_f32 v[170:171], v[158:159], v[158:159], v[170:171]
	v_pk_fma_f32 v[170:171], v[160:161], v[160:161], v[170:171]
	v_cvt_pk_bf16_f32 v176, v154, v155
	v_cvt_pk_bf16_f32 v177, v156, v157
	v_cvt_pk_bf16_f32 v178, v158, v159
	v_cvt_pk_bf16_f32 v179, v160, v161
	global_store_dwordx4 v144, v[176:179], s[98:99] offset:256
	v_add_f32_e32 v162, v170, v171
	s_nop 1
	v_add_f32_dpp v163, v162, v162 quad_perm:[1,0,3,2] row_mask:0xf bank_mask:0xf
	s_nop 1
	v_add_f32_dpp v164, v163, v163 quad_perm:[2,3,0,1] row_mask:0xf bank_mask:0xf
	s_mov_b64 exec, vcc
	global_atomic_add_f32 v145, v164, s[10:11] offset:640
	s_mov_b64 exec, s[18:19]
	s_add_u32 s98, s98, 0x8000
	s_addc_u32 s99, s99, 0
	s_waitcnt lgkmcnt(0)
	ds_read_b128 v[146:149], v142
	ds_read_b128 v[150:153], v143
	ds_read_b128 v[154:157], v142 offset:128
	ds_read_b128 v[158:161], v143 offset:128
	s_waitcnt lgkmcnt(0)
	s_waitcnt vmcnt(21)
	v_lshlrev_b32_e32 v162, 16, v244
	v_and_b32_e32 v163, 0xffff0000, v244
	v_lshlrev_b32_e32 v164, 16, v245
	v_and_b32_e32 v165, 0xffff0000, v245
	v_lshlrev_b32_e32 v166, 16, v246
	v_and_b32_e32 v167, 0xffff0000, v246
	v_lshlrev_b32_e32 v168, 16, v247
	v_and_b32_e32 v169, 0xffff0000, v247
	v_pk_add_f32 v[146:147], v[146:147], v[162:163]
	v_pk_add_f32 v[148:149], v[148:149], v[164:165]
	v_pk_add_f32 v[150:151], v[150:151], v[166:167]
	v_pk_add_f32 v[152:153], v[152:153], v[168:169]
	v_pk_mul_f32 v[170:171], v[146:147], v[146:147]
	v_pk_fma_f32 v[170:171], v[148:149], v[148:149], v[170:171]
	v_pk_fma_f32 v[170:171], v[150:151], v[150:151], v[170:171]
	v_pk_fma_f32 v[170:171], v[152:153], v[152:153], v[170:171]
	v_cvt_pk_bf16_f32 v172, v146, v147
	v_cvt_pk_bf16_f32 v173, v148, v149
	v_cvt_pk_bf16_f32 v174, v150, v151
	v_cvt_pk_bf16_f32 v175, v152, v153
	global_store_dwordx4 v144, v[172:175], s[98:99]
	v_lshlrev_b32_e32 v162, 16, v248
	v_and_b32_e32 v163, 0xffff0000, v248
	v_lshlrev_b32_e32 v164, 16, v249
	v_and_b32_e32 v165, 0xffff0000, v249
	v_lshlrev_b32_e32 v166, 16, v250
	v_and_b32_e32 v167, 0xffff0000, v250
	v_lshlrev_b32_e32 v168, 16, v251
	v_and_b32_e32 v169, 0xffff0000, v251
	v_pk_add_f32 v[154:155], v[154:155], v[162:163]
	v_pk_add_f32 v[156:157], v[156:157], v[164:165]
	v_pk_add_f32 v[158:159], v[158:159], v[166:167]
	v_pk_add_f32 v[160:161], v[160:161], v[168:169]
	v_pk_fma_f32 v[170:171], v[154:155], v[154:155], v[170:171]
	v_pk_fma_f32 v[170:171], v[156:157], v[156:157], v[170:171]
	v_pk_fma_f32 v[170:171], v[158:159], v[158:159], v[170:171]
	v_pk_fma_f32 v[170:171], v[160:161], v[160:161], v[170:171]
	v_cvt_pk_bf16_f32 v176, v154, v155
	v_cvt_pk_bf16_f32 v177, v156, v157
	v_cvt_pk_bf16_f32 v178, v158, v159
	v_cvt_pk_bf16_f32 v179, v160, v161
	global_store_dwordx4 v144, v[176:179], s[98:99] offset:256
	v_add_f32_e32 v162, v170, v171
	s_nop 1
	v_add_f32_dpp v163, v162, v162 quad_perm:[1,0,3,2] row_mask:0xf bank_mask:0xf
	s_nop 1
	v_add_f32_dpp v164, v163, v163 quad_perm:[2,3,0,1] row_mask:0xf bank_mask:0xf
	s_mov_b64 exec, vcc
	global_atomic_add_f32 v145, v164, s[10:11] offset:704
	s_mov_b64 exec, s[18:19]
	s_branch .Lqepi_end_13

.Lqn_done_ph13:
	v_and_b32_e32 v146, 63, v180
	v_and_b32_e32 v147, 15, v180
	v_bfe_u32 v148, v180, 4, 2
	v_lshrrev_b32_e32 v149, 6, v180
	v_lshlrev_b32_e32 v149, 12, v149
	v_add_u32_e32 v149, 0x20000, v149
	v_and_b32_e32 v150, 7, v147
	v_xor_b32_e32 v150, v148, v150
	v_lshlrev_b32_e32 v150, 4, v150
	v_lshl_add_u32 v150, v147, 8, v150
	v_add_u32_e32 v140, v149, v150
	v_xor_b32_e32 v141, 64, v140
	v_lshrrev_b32_e32 v151, 2, v146
	v_and_b32_e32 v152, 3, v146
	v_and_b32_e32 v153, 7, v151
	v_lshlrev_b32_e32 v154, 1, v152
	v_xor_b32_e32 v154, v154, v153
	v_lshlrev_b32_e32 v154, 4, v154
	v_lshl_add_u32 v154, v151, 8, v154
	v_add_u32_e32 v142, v149, v154
	v_xor_b32_e32 v143, 16, v142
	s_lshr_b32 s99, s98, 1
	s_lshl_b32 s99, s99, 7
	s_lshl_b32 s18, s48, 8
	s_add_i32 s18, s18, s37
	s_add_i32 s18, s18, s99
	v_add_u32_e32 v155, s18, v151
	v_lshlrev_b32_e32 v145, 2, v155
	v_lshlrev_b32_e32 v155, 11, v155
	s_and_b32 s99, s98, 1
	s_lshl_b32 s99, s99, 7
	s_lshl_b32 s18, s45, 8
	s_add_i32 s18, s18, s38
	s_add_i32 s18, s18, s99
	v_lshl_add_u32 v156, v152, 3, s18
	v_lshl_add_u32 v144, v156, 1, v155
	v_cmp_eq_u32_e32 vcc, 0, v152
	s_mov_b64 s[98:99], s[8:9]
	global_load_dwordx4 v[188:191], v144, s[98:99]
	s_add_u32 s98, s98, 0x8000
	s_addc_u32 s99, s99, 0
	global_load_dwordx4 v[192:195], v144, s[98:99]
	s_add_u32 s98, s98, 0x8000
	s_addc_u32 s99, s99, 0
	global_load_dwordx4 v[196:199], v144, s[98:99]
	s_add_u32 s98, s98, 0x8000
	s_addc_u32 s99, s99, 0
	global_load_dwordx4 v[200:203], v144, s[98:99]
	s_mov_b64 s[18:19], exec
	s_mov_b64 s[98:99], s[8:9]
	ds_write_b128 v140, v[124:127]
	ds_write_b128 v141, v[120:123]
	s_waitcnt lgkmcnt(0)
	ds_read_b128 v[146:149], v142
	ds_read_b128 v[150:153], v143
	s_waitcnt vmcnt(0)
	s_waitcnt lgkmcnt(0)
	v_lshlrev_b32_e32 v162, 16, v188
	v_and_b32_e32 v163, 0xffff0000, v188
	v_lshlrev_b32_e32 v164, 16, v189
	v_and_b32_e32 v165, 0xffff0000, v189
	v_lshlrev_b32_e32 v166, 16, v190
	v_and_b32_e32 v167, 0xffff0000, v190
	v_lshlrev_b32_e32 v168, 16, v191
	v_and_b32_e32 v169, 0xffff0000, v191
	v_pk_add_f32 v[146:147], v[146:147], v[162:163]
	v_pk_add_f32 v[148:149], v[148:149], v[164:165]
	v_pk_add_f32 v[150:151], v[150:151], v[166:167]
	v_pk_add_f32 v[152:153], v[152:153], v[168:169]
	v_pk_mul_f32 v[170:171], v[146:147], v[146:147]
	v_pk_fma_f32 v[170:171], v[148:149], v[148:149], v[170:171]
	v_pk_fma_f32 v[170:171], v[150:151], v[150:151], v[170:171]
	v_pk_fma_f32 v[170:171], v[152:153], v[152:153], v[170:171]
	v_cvt_pk_bf16_f32 v172, v146, v147
	v_cvt_pk_bf16_f32 v173, v148, v149
	v_cvt_pk_bf16_f32 v174, v150, v151
	v_cvt_pk_bf16_f32 v175, v152, v153
	global_store_dwordx4 v144, v[172:175], s[98:99]
	v_add_f32_e32 v162, v170, v171
	s_nop 1
	v_add_f32_dpp v163, v162, v162 quad_perm:[1,0,3,2] row_mask:0xf bank_mask:0xf
	s_nop 1
	v_add_f32_dpp v164, v163, v163 quad_perm:[2,3,0,1] row_mask:0xf bank_mask:0xf
	s_mov_b64 exec, vcc
	global_atomic_add_f32 v145, v164, s[10:11] offset:0
	s_mov_b64 exec, s[18:19]
	s_add_u32 s98, s98, 0x8000
	s_addc_u32 s99, s99, 0
	ds_write_b128 v140, v[108:111]
	ds_write_b128 v141, v[104:107]
	s_waitcnt lgkmcnt(0)
	ds_read_b128 v[146:149], v142
	ds_read_b128 v[150:153], v143
	s_waitcnt vmcnt(0)
	s_waitcnt lgkmcnt(0)
	v_lshlrev_b32_e32 v162, 16, v192
	v_and_b32_e32 v163, 0xffff0000, v192
	v_lshlrev_b32_e32 v164, 16, v193
	v_and_b32_e32 v165, 0xffff0000, v193
	v_lshlrev_b32_e32 v166, 16, v194
	v_and_b32_e32 v167, 0xffff0000, v194
	v_lshlrev_b32_e32 v168, 16, v195
	v_and_b32_e32 v169, 0xffff0000, v195
	v_pk_add_f32 v[146:147], v[146:147], v[162:163]
	v_pk_add_f32 v[148:149], v[148:149], v[164:165]
	v_pk_add_f32 v[150:151], v[150:151], v[166:167]
	v_pk_add_f32 v[152:153], v[152:153], v[168:169]
	v_pk_mul_f32 v[170:171], v[146:147], v[146:147]
	v_pk_fma_f32 v[170:171], v[148:149], v[148:149], v[170:171]
	v_pk_fma_f32 v[170:171], v[150:151], v[150:151], v[170:171]
	v_pk_fma_f32 v[170:171], v[152:153], v[152:153], v[170:171]
	v_cvt_pk_bf16_f32 v172, v146, v147
	v_cvt_pk_bf16_f32 v173, v148, v149
	v_cvt_pk_bf16_f32 v174, v150, v151
	v_cvt_pk_bf16_f32 v175, v152, v153
	global_store_dwordx4 v144, v[172:175], s[98:99]
	v_add_f32_e32 v162, v170, v171
	s_nop 1
	v_add_f32_dpp v163, v162, v162 quad_perm:[1,0,3,2] row_mask:0xf bank_mask:0xf
	s_nop 1
	v_add_f32_dpp v164, v163, v163 quad_perm:[2,3,0,1] row_mask:0xf bank_mask:0xf
	s_mov_b64 exec, vcc
	global_atomic_add_f32 v145, v164, s[10:11] offset:64
	s_mov_b64 exec, s[18:19]
	s_add_u32 s98, s98, 0x8000
	s_addc_u32 s99, s99, 0
	ds_write_b128 v140, v[92:95]
	ds_write_b128 v141, v[88:91]
	s_waitcnt lgkmcnt(0)
	ds_read_b128 v[146:149], v142
	ds_read_b128 v[150:153], v143
	s_waitcnt vmcnt(0)
	s_waitcnt lgkmcnt(0)
	v_lshlrev_b32_e32 v162, 16, v196
	v_and_b32_e32 v163, 0xffff0000, v196
	v_lshlrev_b32_e32 v164, 16, v197
	v_and_b32_e32 v165, 0xffff0000, v197
	v_lshlrev_b32_e32 v166, 16, v198
	v_and_b32_e32 v167, 0xffff0000, v198
	v_lshlrev_b32_e32 v168, 16, v199
	v_and_b32_e32 v169, 0xffff0000, v199
	v_pk_add_f32 v[146:147], v[146:147], v[162:163]
	v_pk_add_f32 v[148:149], v[148:149], v[164:165]
	v_pk_add_f32 v[150:151], v[150:151], v[166:167]
	v_pk_add_f32 v[152:153], v[152:153], v[168:169]
	v_pk_mul_f32 v[170:171], v[146:147], v[146:147]
	v_pk_fma_f32 v[170:171], v[148:149], v[148:149], v[170:171]
	v_pk_fma_f32 v[170:171], v[150:151], v[150:151], v[170:171]
	v_pk_fma_f32 v[170:171], v[152:153], v[152:153], v[170:171]
	v_cvt_pk_bf16_f32 v172, v146, v147
	v_cvt_pk_bf16_f32 v173, v148, v149
	v_cvt_pk_bf16_f32 v174, v150, v151
	v_cvt_pk_bf16_f32 v175, v152, v153
	global_store_dwordx4 v144, v[172:175], s[98:99]
	v_add_f32_e32 v162, v170, v171
	s_nop 1
	v_add_f32_dpp v163, v162, v162 quad_perm:[1,0,3,2] row_mask:0xf bank_mask:0xf
	s_nop 1
	v_add_f32_dpp v164, v163, v163 quad_perm:[2,3,0,1] row_mask:0xf bank_mask:0xf
	s_mov_b64 exec, vcc
	global_atomic_add_f32 v145, v164, s[10:11] offset:128
	s_mov_b64 exec, s[18:19]
	s_add_u32 s98, s98, 0x8000
	s_addc_u32 s99, s99, 0
	ds_write_b128 v140, v[76:79]
	ds_write_b128 v141, v[72:75]
	s_waitcnt lgkmcnt(0)
	ds_read_b128 v[146:149], v142
	ds_read_b128 v[150:153], v143
	s_waitcnt vmcnt(0)
	s_waitcnt lgkmcnt(0)
	v_lshlrev_b32_e32 v162, 16, v200
	v_and_b32_e32 v163, 0xffff0000, v200
	v_lshlrev_b32_e32 v164, 16, v201
	v_and_b32_e32 v165, 0xffff0000, v201
	v_lshlrev_b32_e32 v166, 16, v202
	v_and_b32_e32 v167, 0xffff0000, v202
	v_lshlrev_b32_e32 v168, 16, v203
	v_and_b32_e32 v169, 0xffff0000, v203
	v_pk_add_f32 v[146:147], v[146:147], v[162:163]
	v_pk_add_f32 v[148:149], v[148:149], v[164:165]
	v_pk_add_f32 v[150:151], v[150:151], v[166:167]
	v_pk_add_f32 v[152:153], v[152:153], v[168:169]
	v_pk_mul_f32 v[170:171], v[146:147], v[146:147]
	v_pk_fma_f32 v[170:171], v[148:149], v[148:149], v[170:171]
	v_pk_fma_f32 v[170:171], v[150:151], v[150:151], v[170:171]
	v_pk_fma_f32 v[170:171], v[152:153], v[152:153], v[170:171]
	v_cvt_pk_bf16_f32 v172, v146, v147
	v_cvt_pk_bf16_f32 v173, v148, v149
	v_cvt_pk_bf16_f32 v174, v150, v151
	v_cvt_pk_bf16_f32 v175, v152, v153
	global_store_dwordx4 v144, v[172:175], s[98:99]
	v_add_f32_e32 v162, v170, v171
	s_nop 1
	v_add_f32_dpp v163, v162, v162 quad_perm:[1,0,3,2] row_mask:0xf bank_mask:0xf
	s_nop 1
	v_add_f32_dpp v164, v163, v163 quad_perm:[2,3,0,1] row_mask:0xf bank_mask:0xf
	s_mov_b64 exec, vcc
	global_atomic_add_f32 v145, v164, s[10:11] offset:192
	s_mov_b64 exec, s[18:19]
.Lqepi_end_13:
.LBB0_1936:
	s_or_b64 exec, exec, s[18:19]
	s_and_b64 vcc, exec, s[4:5]
	s_mov_b64 s[4:5], -1
	s_cbranch_vccnz .LBB0_1905
	s_andn2_b64 vcc, exec, s[2:3]
	s_cbranch_vccnz .LBB0_1904
	s_barrier
	s_branch .LBB0_1904
